# v36: v32 + one static s_setprio 1 for waves 4-7 at kernel entry, all per-segment s_setprio flips deleted
# baseline (speedup 1.0000x reference)
; #define LAS __attribute__((address_space(3)))
; DI KA get_ka() { KA p = (KA)__builtin_amdgcn_kernarg_segment_ptr(); asm volatile("" : "+s"(p)); return p; }
; __global__ void __launch_bounds__(512, 2) hymba_fwd(Args a_unused) {
;     extern __shared__ __attribute__((aligned(16))) unsigned char lds_raw[];
;     LAS unsigned char* lds = (LAS unsigned char*)lds_raw;
;     cg::grid_group grid = cg::this_grid();
;     if (gridDim.x == 0x7fffffffu) grid.sync();
;     volatile LAS unsigned* bst = (volatile LAS unsigned*)(lds + 147200);
;     if (threadIdx.x < 2) bst[threadIdx.x] = 0u;
;     __syncthreads();
;     (void)xcd_barrier_post((unsigned*)(get_ka()->ws), bst);
_Z9hymba_fwd4Args:
	v_readfirstlane_b32 s26, v0
	s_nop 3
	s_and_b32 s26, s26, 0x3ff
	s_lshr_b32 s26, s26, 6
	s_cmp_ge_u32 s26, 4
	s_cbranch_scc0 .Lprio_done
	s_setprio 1
.Lprio_done:
	s_load_dwordx2 s[52:53], s[0:1], 0xe0
	v_writelane_b32 v254, s2, 0
	s_add_u32 s2, s0, 0xe0
	s_addc_u32 s3, s1, 0
	s_waitcnt lgkmcnt(0)
	s_cmp_eq_u32 s52, 0x7fffffff
	s_cbranch_scc1 .LBB0_2
	v_and_b32_e32 v212, 0x3ff, v0
	s_load_dword s26, s[0:1], 0xe8
	s_cbranch_execz .LBB0_3
	s_branch .LBB0_14

; #define PG8_STAGE(bufoff, gbase, voff) do { _Pragma("unroll") for (int _i = 0; _i < 2; ++_i) \
;         __builtin_amdgcn_global_load_lds((const unsigned*)((const char*)(gbase) + (voff)[_i]), (PG8_LAS unsigned*)(lds + (bufoff) + ldsw + _i * 8192), 16, 0, 0); } while (0)
; #define PG8_LDA(dst, b, h) do { _Pragma("unroll") for (int m = 0; m < 4; ++m) _Pragma("unroll") for (int k = 0; k < 2; ++k) dst[m][k] = *(const PG8_LAS bf16x8*)(lds + PG8_SA(b, h) + aoff + m * 2048 + k * 1024); } while (0)
; #define PG8_LDB(dst, b, h) do { _Pragma("unroll") for (int n = 0; n < 2; ++n) _Pragma("unroll") for (int k = 0; k < 2; ++k) dst[n][k] = *(const PG8_LAS bf16x8*)(lds + PG8_SB(b, h) + boff + n * 2048 + k * 1024); } while (0)
; #define PG8_MMA(ai, bj, At, Bt) do { __builtin_amdgcn_s_setprio(1); _Pragma("unroll") for (int m = 0; m < 4; ++m) _Pragma("unroll") for (int n = 0; n < 2; ++n) _Pragma("unroll") for (int k = 0; k < 2; ++k) \
;         acc[ai][bj][m][n] = __builtin_amdgcn_mfma_f32_16x16x32_bf16(Bt[n][k], At[m][k], acc[ai][bj][m][n], 0, 0, 0); __builtin_amdgcn_s_setprio(0); } while (0)
; #define PG8_WAIT_V(n) asm volatile("s_waitcnt vmcnt(" #n ")" ::: "memory")
; #define PG8_WAIT_L(n) asm volatile("s_waitcnt lgkmcnt(" #n ")" ::: "memory")
; #define PG8_BAR __builtin_amdgcn_s_barrier()
; #define PG8_SCHED __builtin_amdgcn_sched_barrier(0)
; template <class Epi, class Sched, bool ALIGN_EPI = false, bool SP2 = false>
; __device__ __forceinline__ void gemm_phase(PG8_LAS unsigned char* lds, const Gemm g, const Sched& S, const Epi& E) {
;     ...
;             PG8_LDB(B0, 0, 0); PG8_LDB(B1, 0, 1); PG8_SCHED; PG8_LDA(At, 0, 0); PG8_STAGE(PG8_SA(1, 1), a1 + hstep, voffA);
;             PG8_WAIT_V(8); PG8_WAIT_L(0); PG8_BAR; PG8_MMA(0, 0, At, B0); PG8_MMA(0, 1, At, B1); PG8_BAR; PG8_SCHED;
;             PG8_LDA(At, 0, 1); PG8_STAGE(PG8_SB(0, 0), b2, voffB); PG8_STAGE(PG8_SB(0, 1), b2 + hstep, voffB); PG8_STAGE(PG8_SA(0, 0), a2, voffA);
;             PG8_WAIT_V(8); PG8_WAIT_L(0); PG8_BAR; PG8_MMA(1, 0, At, B0); PG8_MMA(1, 1, At, B1); PG8_BAR; PG8_SCHED;
.LBB0_294:
	s_add_u32 s24, s2, 0xfffc0080
	s_addc_u32 s25, s3, -1
	s_add_i32 s48, 0, 0x10000
	s_cmp_eq_u32 s47, 12
	s_cselect_b32 s27, s17, s25
	s_cselect_b32 s26, s42, s24
	v_add_u32_e32 v142, s48, v156
	s_cselect_b32 s25, s15, s46
	s_cselect_b32 s24, s43, s45
	s_add_i32 s50, 0, 0x14000
	ds_read_b128 v[138:141], v142
	ds_read_b128 v[160:163], v142 offset:1024
	ds_read_b128 v[164:167], v142 offset:2048
	ds_read_b128 v[168:171], v142 offset:3072
	v_add_u32_e32 v142, s50, v156
	ds_read_b128 v[172:175], v142
	ds_read_b128 v[176:179], v142 offset:1024
	ds_read_b128 v[180:183], v142 offset:2048
	ds_read_b128 v[184:187], v142 offset:3072
	v_lshl_add_u64 v[142:143], s[2:3], 0, v[136:137]
	s_add_i32 m0, s33, 0xc000
	ds_read_b128 v[188:191], v158
	ds_read_b128 v[192:195], v158 offset:1024
	ds_read_b128 v[196:199], v158 offset:2048
	ds_read_b128 v[200:203], v158 offset:3072
	ds_read_b128 v[204:207], v158 offset:4096
	ds_read_b128 v[208:211], v158 offset:5120
	ds_read_b128 v[234:237], v158 offset:6144
	ds_read_b128 v[244:247], v158 offset:7168
	global_load_lds_dwordx4 v[142:143], off
	v_lshl_add_u64 v[142:143], s[2:3], 0, v[134:135]
	s_add_i32 m0, s33, 0xe000
	s_nop 0
	global_load_lds_dwordx4 v[142:143], off
	s_waitcnt vmcnt(8)
	s_waitcnt lgkmcnt(0)
	s_barrier
	s_waitcnt lgkmcnt(0)
	v_mfma_f32_16x16x32_bf16 v[124:127], v[138:141], v[188:191], v[124:127]
	v_mfma_f32_16x16x32_bf16 v[116:119], v[164:167], v[188:191], v[116:119]
	v_mfma_f32_16x16x32_bf16 v[108:111], v[138:141], v[196:199], v[108:111]
	v_mfma_f32_16x16x32_bf16 v[100:103], v[164:167], v[196:199], v[100:103]
	v_mfma_f32_16x16x32_bf16 v[92:95], v[138:141], v[204:207], v[92:95]
	v_mfma_f32_16x16x32_bf16 v[84:87], v[164:167], v[204:207], v[84:87]
	v_mfma_f32_16x16x32_bf16 v[76:79], v[138:141], v[234:237], v[76:79]
	v_mfma_f32_16x16x32_bf16 v[68:71], v[164:167], v[234:237], v[68:71]
	v_mfma_f32_16x16x32_bf16 v[124:127], v[160:163], v[192:195], v[124:127]
	v_mfma_f32_16x16x32_bf16 v[116:119], v[168:171], v[192:195], v[116:119]
	v_mfma_f32_16x16x32_bf16 v[108:111], v[160:163], v[200:203], v[108:111]
	v_mfma_f32_16x16x32_bf16 v[100:103], v[168:171], v[200:203], v[100:103]
	v_mfma_f32_16x16x32_bf16 v[92:95], v[160:163], v[208:211], v[92:95]
	v_mfma_f32_16x16x32_bf16 v[84:87], v[168:171], v[208:211], v[84:87]
	v_mfma_f32_16x16x32_bf16 v[76:79], v[160:163], v[244:247], v[76:79]
	v_mfma_f32_16x16x32_bf16 v[68:71], v[168:171], v[244:247], v[68:71]
	v_mfma_f32_16x16x32_bf16 v[120:123], v[172:175], v[188:191], v[120:123]
	v_mfma_f32_16x16x32_bf16 v[112:115], v[180:183], v[188:191], v[112:115]
	v_mfma_f32_16x16x32_bf16 v[104:107], v[172:175], v[196:199], v[104:107]
	v_mfma_f32_16x16x32_bf16 v[96:99], v[180:183], v[196:199], v[96:99]
	v_mfma_f32_16x16x32_bf16 v[88:91], v[172:175], v[204:207], v[88:91]
	v_mfma_f32_16x16x32_bf16 v[80:83], v[180:183], v[204:207], v[80:83]
	v_mfma_f32_16x16x32_bf16 v[72:75], v[172:175], v[234:237], v[72:75]
	v_mfma_f32_16x16x32_bf16 v[64:67], v[180:183], v[234:237], v[64:67]
	v_mfma_f32_16x16x32_bf16 v[120:123], v[176:179], v[192:195], v[120:123]
	v_mfma_f32_16x16x32_bf16 v[112:115], v[184:187], v[192:195], v[112:115]
	v_mfma_f32_16x16x32_bf16 v[104:107], v[176:179], v[200:203], v[104:107]
	v_mfma_f32_16x16x32_bf16 v[96:99], v[184:187], v[200:203], v[96:99]
	v_mfma_f32_16x16x32_bf16 v[88:91], v[176:179], v[208:211], v[88:91]
	v_mfma_f32_16x16x32_bf16 v[80:83], v[184:187], v[208:211], v[80:83]
	v_mfma_f32_16x16x32_bf16 v[72:75], v[176:179], v[244:247], v[72:75]
	v_mfma_f32_16x16x32_bf16 v[64:67], v[184:187], v[244:247], v[64:67]
	s_barrier
	s_add_i32 s48, s48, s31
	v_lshl_add_u64 v[142:143], s[24:25], 0, v[144:145]
	s_mov_b32 m0, s48
	ds_read_b128 v[188:191], v158 offset:16384
	ds_read_b128 v[192:195], v158 offset:17408
	ds_read_b128 v[196:199], v158 offset:18432
	ds_read_b128 v[200:203], v158 offset:19456
	ds_read_b128 v[204:207], v158 offset:20480
	ds_read_b128 v[208:211], v158 offset:21504
	ds_read_b128 v[234:237], v158 offset:22528
	ds_read_b128 v[244:247], v158 offset:23552
	global_load_lds_dwordx4 v[142:143], off
	s_add_i32 m0, s48, 0x2000
	s_add_u32 s48, s24, 0x40000
	v_lshl_add_u64 v[238:239], s[24:25], 0, v[128:129]
	s_addc_u32 s49, s25, 0
	s_add_i32 s50, s50, s31
	global_load_lds_dwordx4 v[238:239], off
	v_lshl_add_u64 v[248:249], s[48:49], 0, v[144:145]
	s_mov_b32 m0, s50
	v_lshl_add_u64 v[250:251], s[26:27], 0, v[130:131]
	global_load_lds_dwordx4 v[248:249], off
	v_lshl_add_u64 v[248:249], s[48:49], 0, v[128:129]
	s_add_i32 m0, s50, 0x2000
	s_nop 0
	global_load_lds_dwordx4 v[248:249], off
	v_lshl_add_u64 v[248:249], s[26:27], 0, v[132:133]
	s_mov_b32 m0, s33
	s_nop 0
	global_load_lds_dwordx4 v[248:249], off
	s_mov_b32 m0, s34
	s_nop 0
	global_load_lds_dwordx4 v[250:251], off
	s_waitcnt vmcnt(8)
	s_waitcnt lgkmcnt(0)
	s_barrier
; #define PG8_STAGE(bufoff, gbase, voff) do { _Pragma("unroll") for (int _i = 0; _i < 2; ++_i) \
;         __builtin_amdgcn_global_load_lds((const unsigned*)((const char*)(gbase) + (voff)[_i]), (PG8_LAS unsigned*)(lds + (bufoff) + ldsw + _i * 8192), 16, 0, 0); } while (0)
; #define PG8_LDA(dst, b, h) do { _Pragma("unroll") for (int m = 0; m < 4; ++m) _Pragma("unroll") for (int k = 0; k < 2; ++k) dst[m][k] = *(const PG8_LAS bf16x8*)(lds + PG8_SA(b, h) + aoff + m * 2048 + k * 1024); } while (0)
; #define PG8_LDB(dst, b, h) do { _Pragma("unroll") for (int n = 0; n < 2; ++n) _Pragma("unroll") for (int k = 0; k < 2; ++k) dst[n][k] = *(const PG8_LAS bf16x8*)(lds + PG8_SB(b, h) + boff + n * 2048 + k * 1024); } while (0)
; #define PG8_MMA(ai, bj, At, Bt) do { __builtin_amdgcn_s_setprio(1); _Pragma("unroll") for (int m = 0; m < 4; ++m) _Pragma("unroll") for (int n = 0; n < 2; ++n) _Pragma("unroll") for (int k = 0; k < 2; ++k) \
;         acc[ai][bj][m][n] = __builtin_amdgcn_mfma_f32_16x16x32_bf16(Bt[n][k], At[m][k], acc[ai][bj][m][n], 0, 0, 0); __builtin_amdgcn_s_setprio(0); } while (0)
; #define PG8_WAIT_V(n) asm volatile("s_waitcnt vmcnt(" #n ")" ::: "memory")
; #define PG8_WAIT_L(n) asm volatile("s_waitcnt lgkmcnt(" #n ")" ::: "memory")
; #define PG8_BAR __builtin_amdgcn_s_barrier()
; #define PG8_SCHED __builtin_amdgcn_sched_barrier(0)
; template <class Epi, class Sched, bool ALIGN_EPI = false, bool SP2 = false>
; __device__ __forceinline__ void gemm_phase(PG8_LAS unsigned char* lds, const Gemm g, const Sched& S, const Epi& E) {
;     ...
;             PG8_WAIT_V(8); PG8_WAIT_L(0); PG8_BAR; PG8_MMA(1, 0, At, B0); PG8_MMA(1, 1, At, B1); PG8_BAR; PG8_SCHED;
;             PG8_LDB(B0, 1, 0); PG8_LDB(B1, 1, 1); PG8_SCHED; PG8_LDA(At, 1, 0); PG8_STAGE(PG8_SA(0, 1), a2 + hstep, voffA);
;             PG8_WAIT_V(8); PG8_WAIT_L(0); PG8_BAR; PG8_MMA(0, 0, At, B0); PG8_MMA(0, 1, At, B1); PG8_BAR; PG8_SCHED;
	s_waitcnt lgkmcnt(0)
	v_mfma_f32_16x16x32_bf16 v[60:63], v[138:141], v[188:191], v[60:63]
	v_mfma_f32_16x16x32_bf16 v[52:55], v[164:167], v[188:191], v[52:55]
	v_mfma_f32_16x16x32_bf16 v[44:47], v[138:141], v[196:199], v[44:47]
	v_mfma_f32_16x16x32_bf16 v[36:39], v[164:167], v[196:199], v[36:39]
	v_mfma_f32_16x16x32_bf16 v[28:31], v[138:141], v[204:207], v[28:31]
	v_mfma_f32_16x16x32_bf16 v[20:23], v[164:167], v[204:207], v[20:23]
	v_mfma_f32_16x16x32_bf16 v[12:15], v[138:141], v[234:237], v[12:15]
	v_mfma_f32_16x16x32_bf16 v[4:7], v[164:167], v[234:237], v[4:7]
	v_mfma_f32_16x16x32_bf16 v[60:63], v[160:163], v[192:195], v[60:63]
	v_mfma_f32_16x16x32_bf16 v[52:55], v[168:171], v[192:195], v[52:55]
	v_mfma_f32_16x16x32_bf16 v[44:47], v[160:163], v[200:203], v[44:47]
	v_mfma_f32_16x16x32_bf16 v[36:39], v[168:171], v[200:203], v[36:39]
	v_mfma_f32_16x16x32_bf16 v[28:31], v[160:163], v[208:211], v[28:31]
	v_mfma_f32_16x16x32_bf16 v[20:23], v[168:171], v[208:211], v[20:23]
	v_mfma_f32_16x16x32_bf16 v[12:15], v[160:163], v[244:247], v[12:15]
	v_mfma_f32_16x16x32_bf16 v[4:7], v[168:171], v[244:247], v[4:7]
	v_mfma_f32_16x16x32_bf16 v[56:59], v[172:175], v[188:191], v[56:59]
	v_mfma_f32_16x16x32_bf16 v[48:51], v[180:183], v[188:191], v[48:51]
	v_mfma_f32_16x16x32_bf16 v[40:43], v[172:175], v[196:199], v[40:43]
	v_mfma_f32_16x16x32_bf16 v[32:35], v[180:183], v[196:199], v[32:35]
	v_mfma_f32_16x16x32_bf16 v[24:27], v[172:175], v[204:207], v[24:27]
	v_mfma_f32_16x16x32_bf16 v[16:19], v[180:183], v[204:207], v[16:19]
	v_mfma_f32_16x16x32_bf16 v[8:11], v[172:175], v[234:237], v[8:11]
	v_mfma_f32_16x16x32_bf16 v[0:3], v[180:183], v[234:237], v[0:3]
	v_mfma_f32_16x16x32_bf16 v[56:59], v[176:179], v[192:195], v[56:59]
	v_mfma_f32_16x16x32_bf16 v[48:51], v[184:187], v[192:195], v[48:51]
	v_mfma_f32_16x16x32_bf16 v[40:43], v[176:179], v[200:203], v[40:43]
	v_mfma_f32_16x16x32_bf16 v[32:35], v[184:187], v[200:203], v[32:35]
	v_mfma_f32_16x16x32_bf16 v[24:27], v[176:179], v[208:211], v[24:27]
	v_mfma_f32_16x16x32_bf16 v[16:19], v[184:187], v[208:211], v[16:19]
	v_mfma_f32_16x16x32_bf16 v[8:11], v[176:179], v[244:247], v[8:11]
	v_mfma_f32_16x16x32_bf16 v[0:3], v[184:187], v[244:247], v[0:3]
	s_barrier
	s_add_i32 s48, 0, 0x18000
	v_add_u32_e32 v154, s48, v156
	s_add_i32 s49, 0, 0x1c000
	ds_read_b128 v[138:141], v154
	ds_read_b128 v[160:163], v154 offset:1024
	ds_read_b128 v[164:167], v154 offset:2048
	ds_read_b128 v[168:171], v154 offset:3072
	v_add_u32_e32 v154, s49, v156
	ds_read_b128 v[172:175], v154
	ds_read_b128 v[176:179], v154 offset:1024
	ds_read_b128 v[180:183], v154 offset:2048
	ds_read_b128 v[184:187], v154 offset:3072
	s_add_u32 s26, s26, 0x40000
	s_addc_u32 s27, s27, 0
	s_mov_b32 m0, s35
	v_lshl_add_u64 v[252:253], s[26:27], 0, v[132:133]
	ds_read_b128 v[188:191], v158 offset:32768
	ds_read_b128 v[192:195], v158 offset:33792
	ds_read_b128 v[196:199], v158 offset:34816
	ds_read_b128 v[200:203], v158 offset:35840
	ds_read_b128 v[204:207], v158 offset:36864
	ds_read_b128 v[208:211], v158 offset:37888
	ds_read_b128 v[234:237], v158 offset:38912
	ds_read_b128 v[244:247], v158 offset:39936
	global_load_lds_dwordx4 v[252:253], off
	v_lshl_add_u64 v[252:253], s[26:27], 0, v[130:131]
	s_mov_b32 m0, s36
	s_nop 0
	global_load_lds_dwordx4 v[252:253], off
	s_waitcnt vmcnt(8)
	s_waitcnt lgkmcnt(0)
	s_barrier
	s_waitcnt lgkmcnt(0)
	v_mfma_f32_16x16x32_bf16 v[124:127], v[138:141], v[188:191], v[124:127]
	v_mfma_f32_16x16x32_bf16 v[116:119], v[164:167], v[188:191], v[116:119]
	v_mfma_f32_16x16x32_bf16 v[108:111], v[138:141], v[196:199], v[108:111]
	v_mfma_f32_16x16x32_bf16 v[100:103], v[164:167], v[196:199], v[100:103]
	v_mfma_f32_16x16x32_bf16 v[92:95], v[138:141], v[204:207], v[92:95]
	v_mfma_f32_16x16x32_bf16 v[84:87], v[164:167], v[204:207], v[84:87]
	v_mfma_f32_16x16x32_bf16 v[76:79], v[138:141], v[234:237], v[76:79]
	v_mfma_f32_16x16x32_bf16 v[68:71], v[164:167], v[234:237], v[68:71]
	v_mfma_f32_16x16x32_bf16 v[124:127], v[160:163], v[192:195], v[124:127]
	v_mfma_f32_16x16x32_bf16 v[116:119], v[168:171], v[192:195], v[116:119]
	v_mfma_f32_16x16x32_bf16 v[108:111], v[160:163], v[200:203], v[108:111]
	v_mfma_f32_16x16x32_bf16 v[100:103], v[168:171], v[200:203], v[100:103]
	v_mfma_f32_16x16x32_bf16 v[92:95], v[160:163], v[208:211], v[92:95]
	v_mfma_f32_16x16x32_bf16 v[84:87], v[168:171], v[208:211], v[84:87]
	v_mfma_f32_16x16x32_bf16 v[76:79], v[160:163], v[244:247], v[76:79]
	v_mfma_f32_16x16x32_bf16 v[68:71], v[168:171], v[244:247], v[68:71]
	v_mfma_f32_16x16x32_bf16 v[120:123], v[172:175], v[188:191], v[120:123]
	v_mfma_f32_16x16x32_bf16 v[112:115], v[180:183], v[188:191], v[112:115]
	v_mfma_f32_16x16x32_bf16 v[104:107], v[172:175], v[196:199], v[104:107]
	v_mfma_f32_16x16x32_bf16 v[96:99], v[180:183], v[196:199], v[96:99]
	v_mfma_f32_16x16x32_bf16 v[88:91], v[172:175], v[204:207], v[88:91]
	v_mfma_f32_16x16x32_bf16 v[80:83], v[180:183], v[204:207], v[80:83]
	v_mfma_f32_16x16x32_bf16 v[72:75], v[172:175], v[234:237], v[72:75]
	v_mfma_f32_16x16x32_bf16 v[64:67], v[180:183], v[234:237], v[64:67]
	v_mfma_f32_16x16x32_bf16 v[120:123], v[176:179], v[192:195], v[120:123]
	v_mfma_f32_16x16x32_bf16 v[112:115], v[184:187], v[192:195], v[112:115]
	v_mfma_f32_16x16x32_bf16 v[104:107], v[176:179], v[200:203], v[104:107]
	v_mfma_f32_16x16x32_bf16 v[96:99], v[184:187], v[200:203], v[96:99]
	v_mfma_f32_16x16x32_bf16 v[88:91], v[176:179], v[208:211], v[88:91]
	v_mfma_f32_16x16x32_bf16 v[80:83], v[184:187], v[208:211], v[80:83]
	v_mfma_f32_16x16x32_bf16 v[72:75], v[176:179], v[244:247], v[72:75]
	v_mfma_f32_16x16x32_bf16 v[64:67], v[184:187], v[244:247], v[64:67]
	s_barrier
; #define PG8_STAGE(bufoff, gbase, voff) do { _Pragma("unroll") for (int _i = 0; _i < 2; ++_i) \
;         __builtin_amdgcn_global_load_lds((const unsigned*)((const char*)(gbase) + (voff)[_i]), (PG8_LAS unsigned*)(lds + (bufoff) + ldsw + _i * 8192), 16, 0, 0); } while (0)
; #define PG8_LDA(dst, b, h) do { _Pragma("unroll") for (int m = 0; m < 4; ++m) _Pragma("unroll") for (int k = 0; k < 2; ++k) dst[m][k] = *(const PG8_LAS bf16x8*)(lds + PG8_SA(b, h) + aoff + m * 2048 + k * 1024); } while (0)
; #define PG8_MMA(ai, bj, At, Bt) do { __builtin_amdgcn_s_setprio(1); _Pragma("unroll") for (int m = 0; m < 4; ++m) _Pragma("unroll") for (int n = 0; n < 2; ++n) _Pragma("unroll") for (int k = 0; k < 2; ++k) \
;         acc[ai][bj][m][n] = __builtin_amdgcn_mfma_f32_16x16x32_bf16(Bt[n][k], At[m][k], acc[ai][bj][m][n], 0, 0, 0); __builtin_amdgcn_s_setprio(0); } while (0)
; #define PG8_WAIT_V(n) asm volatile("s_waitcnt vmcnt(" #n ")" ::: "memory")
; #define PG8_WAIT_L(n) asm volatile("s_waitcnt lgkmcnt(" #n ")" ::: "memory")
; #define PG8_BAR __builtin_amdgcn_s_barrier()
; #define PG8_SCHED __builtin_amdgcn_sched_barrier(0)
; template <class Epi, class Sched, bool ALIGN_EPI = false, bool SP2 = false>
; __device__ __forceinline__ void gemm_phase(PG8_LAS unsigned char* lds, const Gemm g, const Sched& S, const Epi& E) {
;     ...
;             PG8_LDA(At, 1, 1); PG8_STAGE(PG8_SB(1, 0), b3, voffB); PG8_STAGE(PG8_SB(1, 1), b3 + hstep, voffB); PG8_STAGE(PG8_SA(1, 0), a3, voffA);
;             PG8_WAIT_V(8); PG8_WAIT_L(0); PG8_BAR; PG8_MMA(1, 0, At, B0); PG8_MMA(1, 1, At, B1); PG8_BAR; PG8_SCHED;
;     ...
;         if constexpr (ALIGN_EPI) { if (wr == 0) PG8_BAR; }
	s_add_i32 s26, s48, s31
	v_lshl_add_u64 v[142:143], v[142:143], 0, s[52:53]
	s_mov_b32 m0, s26
	ds_read_b128 v[188:191], v158 offset:49152
	ds_read_b128 v[192:195], v158 offset:50176
	ds_read_b128 v[196:199], v158 offset:51200
	ds_read_b128 v[200:203], v158 offset:52224
	ds_read_b128 v[204:207], v158 offset:53248
	ds_read_b128 v[208:211], v158 offset:54272
	ds_read_b128 v[234:237], v158 offset:55296
	ds_read_b128 v[244:247], v158 offset:56320
	global_load_lds_dwordx4 v[142:143], off
	s_add_i32 m0, s26, 0x2000
	s_add_u32 s24, s24, 0x40080
	v_lshl_add_u64 v[142:143], v[238:239], 0, s[52:53]
	s_addc_u32 s25, s25, 0
	s_add_i32 s26, s49, s31
	global_load_lds_dwordx4 v[142:143], off
	v_lshl_add_u64 v[142:143], s[24:25], 0, v[144:145]
	s_mov_b32 m0, s26
	s_nop 0
	global_load_lds_dwordx4 v[142:143], off
	v_lshl_add_u64 v[142:143], s[24:25], 0, v[128:129]
	s_add_i32 m0, s26, 0x2000
	s_nop 0
	global_load_lds_dwordx4 v[142:143], off
	v_lshl_add_u64 v[142:143], v[248:249], 0, s[52:53]
	s_mov_b32 m0, s37
	s_nop 0
	global_load_lds_dwordx4 v[142:143], off
	v_lshl_add_u64 v[142:143], v[250:251], 0, s[52:53]
	s_mov_b32 m0, s38
	s_nop 0
	global_load_lds_dwordx4 v[142:143], off
	s_waitcnt vmcnt(8)
	s_waitcnt lgkmcnt(0)
	s_barrier
	s_waitcnt lgkmcnt(0)
	v_mfma_f32_16x16x32_bf16 v[60:63], v[138:141], v[188:191], v[60:63]
	v_mfma_f32_16x16x32_bf16 v[52:55], v[164:167], v[188:191], v[52:55]
	v_mfma_f32_16x16x32_bf16 v[44:47], v[138:141], v[196:199], v[44:47]
	v_mfma_f32_16x16x32_bf16 v[36:39], v[164:167], v[196:199], v[36:39]
	v_mfma_f32_16x16x32_bf16 v[28:31], v[138:141], v[204:207], v[28:31]
	v_mfma_f32_16x16x32_bf16 v[20:23], v[164:167], v[204:207], v[20:23]
	v_mfma_f32_16x16x32_bf16 v[12:15], v[138:141], v[234:237], v[12:15]
	v_mfma_f32_16x16x32_bf16 v[4:7], v[164:167], v[234:237], v[4:7]
	v_mfma_f32_16x16x32_bf16 v[60:63], v[160:163], v[192:195], v[60:63]
	v_mfma_f32_16x16x32_bf16 v[52:55], v[168:171], v[192:195], v[52:55]
	v_mfma_f32_16x16x32_bf16 v[44:47], v[160:163], v[200:203], v[44:47]
	v_mfma_f32_16x16x32_bf16 v[36:39], v[168:171], v[200:203], v[36:39]
	v_mfma_f32_16x16x32_bf16 v[28:31], v[160:163], v[208:211], v[28:31]
	v_mfma_f32_16x16x32_bf16 v[20:23], v[168:171], v[208:211], v[20:23]
	v_mfma_f32_16x16x32_bf16 v[12:15], v[160:163], v[244:247], v[12:15]
	v_mfma_f32_16x16x32_bf16 v[4:7], v[168:171], v[244:247], v[4:7]
	v_mfma_f32_16x16x32_bf16 v[56:59], v[172:175], v[188:191], v[56:59]
	v_mfma_f32_16x16x32_bf16 v[48:51], v[180:183], v[188:191], v[48:51]
	v_mfma_f32_16x16x32_bf16 v[40:43], v[172:175], v[196:199], v[40:43]
	v_mfma_f32_16x16x32_bf16 v[32:35], v[180:183], v[196:199], v[32:35]
	v_mfma_f32_16x16x32_bf16 v[24:27], v[172:175], v[204:207], v[24:27]
	v_mfma_f32_16x16x32_bf16 v[16:19], v[180:183], v[204:207], v[16:19]
	v_mfma_f32_16x16x32_bf16 v[8:11], v[172:175], v[234:237], v[8:11]
	v_mfma_f32_16x16x32_bf16 v[0:3], v[180:183], v[234:237], v[0:3]
	v_mfma_f32_16x16x32_bf16 v[56:59], v[176:179], v[192:195], v[56:59]
	v_mfma_f32_16x16x32_bf16 v[48:51], v[184:187], v[192:195], v[48:51]
	v_mfma_f32_16x16x32_bf16 v[40:43], v[176:179], v[200:203], v[40:43]
	v_mfma_f32_16x16x32_bf16 v[32:35], v[184:187], v[200:203], v[32:35]
	v_mfma_f32_16x16x32_bf16 v[24:27], v[176:179], v[208:211], v[24:27]
	v_mfma_f32_16x16x32_bf16 v[16:19], v[184:187], v[208:211], v[16:19]
	v_mfma_f32_16x16x32_bf16 v[8:11], v[176:179], v[244:247], v[8:11]
	v_mfma_f32_16x16x32_bf16 v[0:3], v[184:187], v[244:247], v[0:3]
	s_barrier
	s_add_i32 s47, s47, 2
	s_add_u32 s45, s45, 0x100
	s_addc_u32 s46, s46, 0
	s_add_u32 s2, s2, 0x100
	s_addc_u32 s3, s3, 0
	s_cmp_gt_u32 s47, 13
	s_cbranch_scc0 .LBB0_294
	s_and_b64 vcc, exec, s[12:13]
	s_cbranch_vccz .LBB0_297
	s_barrier

; #define PG8_STAGE(bufoff, gbase, voff) do { _Pragma("unroll") for (int _i = 0; _i < 2; ++_i) \
;         __builtin_amdgcn_global_load_lds((const unsigned*)((const char*)(gbase) + (voff)[_i]), (PG8_LAS unsigned*)(lds + (bufoff) + ldsw + _i * 8192), 16, 0, 0); } while (0)
; #define PG8_LDA(dst, b, h) do { _Pragma("unroll") for (int m = 0; m < 4; ++m) _Pragma("unroll") for (int k = 0; k < 2; ++k) dst[m][k] = *(const PG8_LAS bf16x8*)(lds + PG8_SA(b, h) + aoff + m * 2048 + k * 1024); } while (0)
; #define PG8_LDB(dst, b, h) do { _Pragma("unroll") for (int n = 0; n < 2; ++n) _Pragma("unroll") for (int k = 0; k < 2; ++k) dst[n][k] = *(const PG8_LAS bf16x8*)(lds + PG8_SB(b, h) + boff + n * 2048 + k * 1024); } while (0)
; #define PG8_MMA(ai, bj, At, Bt) do { __builtin_amdgcn_s_setprio(1); _Pragma("unroll") for (int m = 0; m < 4; ++m) _Pragma("unroll") for (int n = 0; n < 2; ++n) _Pragma("unroll") for (int k = 0; k < 2; ++k) \
;         acc[ai][bj][m][n] = __builtin_amdgcn_mfma_f32_16x16x32_bf16(Bt[n][k], At[m][k], acc[ai][bj][m][n], 0, 0, 0); __builtin_amdgcn_s_setprio(0); } while (0)
; #define PG8_WAIT_V(n) asm volatile("s_waitcnt vmcnt(" #n ")" ::: "memory")
; #define PG8_WAIT_L(n) asm volatile("s_waitcnt lgkmcnt(" #n ")" ::: "memory")
; #define PG8_BAR __builtin_amdgcn_s_barrier()
; #define PG8_SCHED __builtin_amdgcn_sched_barrier(0)
; template <class Epi, class Sched, bool ALIGN_EPI = false, bool SP2 = false>
; __device__ __forceinline__ void gemm_phase(PG8_LAS unsigned char* lds, const Gemm g, const Sched& S, const Epi& E) {
;     ...
;             const bool last = (t == nt - 2);
;             const char* a1 = cA + (size_t)(t + 1) * kstep;
;             const char* a2 = last ? nA : cA + (size_t)(t + 2) * kstep; const char* b2 = last ? nB : cB + (size_t)(t + 2) * kstep;
;             const char* a3 = a2 + kstep; const char* b3 = b2 + kstep;
;             if (last && has_next) S.a_ready(nxt);
;             if constexpr (SP2) {
;             PG8_LDB(B0, 0, 0); PG8_LDB(B1, 0, 1); PG8_SCHED; PG8_LDA(At, 0, 0); PG8_STAGE(PG8_SA(1, 1), a1 + hstep, voffA);
;             PG8_WAIT_V(8); PG8_WAIT_L(0); PG8_BAR; PG8_MMA(0, 0, At, B0); PG8_MMA(0, 1, At, B1); PG8_BAR; PG8_SCHED;
;             PG8_LDA(At, 0, 1); PG8_STAGE(PG8_SB(0, 0), b2, voffB); PG8_STAGE(PG8_SB(0, 1), b2 + hstep, voffB); PG8_STAGE(PG8_SA(0, 0), a2, voffA);
.LBB0_377:
	s_add_i32 s60, s34, 2
	s_add_u32 s12, s30, 0x100
	s_addc_u32 s13, s31, 0
	s_add_i32 s61, 0, 0x10000
	s_cmp_eq_u32 s25, s34
	s_cselect_b32 s37, s23, s13
	s_cselect_b32 s36, s22, s12
	s_cselect_b32 s35, s21, s59
	s_cselect_b32 s34, s20, s58
	s_add_i32 s62, 0, 0x14000
	v_add_u32_e32 v140, s61, v234
	v_add_u32_e32 v178, s62, v234
	s_waitcnt lgkmcnt(0)
	ds_read_b128 v[128:131], v140
	ds_read_b128 v[132:135], v140 offset:1024
	ds_read_b128 v[136:139], v140 offset:2048
	ds_read_b128 v[140:143], v140 offset:3072
	ds_read_b128 v[166:169], v178
	ds_read_b128 v[170:173], v178 offset:1024
	ds_read_b128 v[174:177], v178 offset:2048
	ds_read_b128 v[178:181], v178 offset:3072
	v_lshl_add_u64 v[210:211], s[30:31], 0, v[164:165]
	s_add_i32 m0, s46, 0xc000
	ds_read_b128 v[182:185], v236
	ds_read_b128 v[186:189], v236 offset:1024
	ds_read_b128 v[190:193], v236 offset:2048
	ds_read_b128 v[194:197], v236 offset:3072
	ds_read_b128 v[198:201], v236 offset:4096
	ds_read_b128 v[202:205], v236 offset:5120
	ds_read_b128 v[206:209], v236 offset:6144
	ds_read_b128 v[244:247], v236 offset:7168
	global_load_lds_dwordx4 v[210:211], off
	v_lshl_add_u64 v[210:211], s[30:31], 0, v[162:163]
	s_add_i32 m0, s46, 0xe000
	s_nop 0
	global_load_lds_dwordx4 v[210:211], off
	s_waitcnt vmcnt(8)
	s_waitcnt lgkmcnt(0)
	s_barrier
	s_waitcnt lgkmcnt(0)
	v_mfma_f32_16x16x32_bf16 v[124:127], v[128:131], v[182:185], v[124:127]
	v_mfma_f32_16x16x32_bf16 v[120:123], v[136:139], v[182:185], v[120:123]
	v_mfma_f32_16x16x32_bf16 v[116:119], v[128:131], v[190:193], v[116:119]
	v_mfma_f32_16x16x32_bf16 v[112:115], v[136:139], v[190:193], v[112:115]
	v_mfma_f32_16x16x32_bf16 v[108:111], v[128:131], v[198:201], v[108:111]
	v_mfma_f32_16x16x32_bf16 v[104:107], v[136:139], v[198:201], v[104:107]
	v_mfma_f32_16x16x32_bf16 v[100:103], v[128:131], v[206:209], v[100:103]
	v_mfma_f32_16x16x32_bf16 v[96:99], v[136:139], v[206:209], v[96:99]
	v_mfma_f32_16x16x32_bf16 v[124:127], v[132:135], v[186:189], v[124:127]
	v_mfma_f32_16x16x32_bf16 v[120:123], v[140:143], v[186:189], v[120:123]
	v_mfma_f32_16x16x32_bf16 v[116:119], v[132:135], v[194:197], v[116:119]
	v_mfma_f32_16x16x32_bf16 v[112:115], v[140:143], v[194:197], v[112:115]
	v_mfma_f32_16x16x32_bf16 v[108:111], v[132:135], v[202:205], v[108:111]
	v_mfma_f32_16x16x32_bf16 v[104:107], v[140:143], v[202:205], v[104:107]
	v_mfma_f32_16x16x32_bf16 v[100:103], v[132:135], v[244:247], v[100:103]
	v_mfma_f32_16x16x32_bf16 v[96:99], v[140:143], v[244:247], v[96:99]
	v_mfma_f32_16x16x32_bf16 v[92:95], v[166:169], v[182:185], v[92:95]
	v_mfma_f32_16x16x32_bf16 v[88:91], v[174:177], v[182:185], v[88:91]
	v_mfma_f32_16x16x32_bf16 v[84:87], v[166:169], v[190:193], v[84:87]
	v_mfma_f32_16x16x32_bf16 v[80:83], v[174:177], v[190:193], v[80:83]
	v_mfma_f32_16x16x32_bf16 v[76:79], v[166:169], v[198:201], v[76:79]
	v_mfma_f32_16x16x32_bf16 v[72:75], v[174:177], v[198:201], v[72:75]
	v_mfma_f32_16x16x32_bf16 v[68:71], v[166:169], v[206:209], v[68:71]
	v_mfma_f32_16x16x32_bf16 v[64:67], v[174:177], v[206:209], v[64:67]
	v_mfma_f32_16x16x32_bf16 v[92:95], v[170:173], v[186:189], v[92:95]
	v_mfma_f32_16x16x32_bf16 v[88:91], v[178:181], v[186:189], v[88:91]
	v_mfma_f32_16x16x32_bf16 v[84:87], v[170:173], v[194:197], v[84:87]
	v_mfma_f32_16x16x32_bf16 v[80:83], v[178:181], v[194:197], v[80:83]
	v_mfma_f32_16x16x32_bf16 v[76:79], v[170:173], v[202:205], v[76:79]
	v_mfma_f32_16x16x32_bf16 v[72:75], v[178:181], v[202:205], v[72:75]
	v_mfma_f32_16x16x32_bf16 v[68:71], v[170:173], v[244:247], v[68:71]
	v_mfma_f32_16x16x32_bf16 v[64:67], v[178:181], v[244:247], v[64:67]
	s_barrier
	s_add_i32 s30, s61, s45
	v_lshl_add_u64 v[210:211], s[34:35], 0, v[144:145]
	s_mov_b32 m0, s30
	ds_read_b128 v[182:185], v236 offset:16384
	ds_read_b128 v[186:189], v236 offset:17408
	ds_read_b128 v[190:193], v236 offset:18432
	ds_read_b128 v[194:197], v236 offset:19456
	ds_read_b128 v[198:201], v236 offset:20480
	ds_read_b128 v[202:205], v236 offset:21504
	ds_read_b128 v[206:209], v236 offset:22528
	ds_read_b128 v[244:247], v236 offset:23552
	global_load_lds_dwordx4 v[210:211], off
	s_add_i32 m0, s30, 0x2000
	s_add_u32 s30, s34, 0xb0000
	v_lshl_add_u64 v[248:249], s[34:35], 0, v[158:159]
	s_addc_u32 s31, s35, 0
	s_add_i32 s61, s62, s45
	global_load_lds_dwordx4 v[248:249], off
	v_lshl_add_u64 v[250:251], s[30:31], 0, v[144:145]
	s_mov_b32 m0, s61
	v_lshl_add_u64 v[252:253], s[36:37], 0, v[156:157]
	global_load_lds_dwordx4 v[250:251], off
	v_lshl_add_u64 v[250:251], s[30:31], 0, v[158:159]
	s_add_i32 m0, s61, 0x2000
	s_nop 0
	global_load_lds_dwordx4 v[250:251], off
	v_lshl_add_u64 v[250:251], s[36:37], 0, v[154:155]
	s_mov_b32 m0, s46
	s_nop 0
	global_load_lds_dwordx4 v[250:251], off
	s_mov_b32 m0, s47
	s_nop 0
	global_load_lds_dwordx4 v[252:253], off
	s_waitcnt vmcnt(8)
	s_waitcnt lgkmcnt(0)
	s_barrier
; #define PG8_STAGE(bufoff, gbase, voff) do { _Pragma("unroll") for (int _i = 0; _i < 2; ++_i) \
;         __builtin_amdgcn_global_load_lds((const unsigned*)((const char*)(gbase) + (voff)[_i]), (PG8_LAS unsigned*)(lds + (bufoff) + ldsw + _i * 8192), 16, 0, 0); } while (0)
; #define PG8_LDA(dst, b, h) do { _Pragma("unroll") for (int m = 0; m < 4; ++m) _Pragma("unroll") for (int k = 0; k < 2; ++k) dst[m][k] = *(const PG8_LAS bf16x8*)(lds + PG8_SA(b, h) + aoff + m * 2048 + k * 1024); } while (0)
; #define PG8_LDB(dst, b, h) do { _Pragma("unroll") for (int n = 0; n < 2; ++n) _Pragma("unroll") for (int k = 0; k < 2; ++k) dst[n][k] = *(const PG8_LAS bf16x8*)(lds + PG8_SB(b, h) + boff + n * 2048 + k * 1024); } while (0)
; #define PG8_MMA(ai, bj, At, Bt) do { __builtin_amdgcn_s_setprio(1); _Pragma("unroll") for (int m = 0; m < 4; ++m) _Pragma("unroll") for (int n = 0; n < 2; ++n) _Pragma("unroll") for (int k = 0; k < 2; ++k) \
;         acc[ai][bj][m][n] = __builtin_amdgcn_mfma_f32_16x16x32_bf16(Bt[n][k], At[m][k], acc[ai][bj][m][n], 0, 0, 0); __builtin_amdgcn_s_setprio(0); } while (0)
; #define PG8_WAIT_V(n) asm volatile("s_waitcnt vmcnt(" #n ")" ::: "memory")
; #define PG8_WAIT_L(n) asm volatile("s_waitcnt lgkmcnt(" #n ")" ::: "memory")
; #define PG8_BAR __builtin_amdgcn_s_barrier()
; #define PG8_SCHED __builtin_amdgcn_sched_barrier(0)
; template <class Epi, class Sched, bool ALIGN_EPI = false, bool SP2 = false>
; __device__ __forceinline__ void gemm_phase(PG8_LAS unsigned char* lds, const Gemm g, const Sched& S, const Epi& E) {
;     ...
;             PG8_WAIT_V(8); PG8_WAIT_L(0); PG8_BAR; PG8_MMA(1, 0, At, B0); PG8_MMA(1, 1, At, B1); PG8_BAR; PG8_SCHED;
;             PG8_LDB(B0, 1, 0); PG8_LDB(B1, 1, 1); PG8_SCHED; PG8_LDA(At, 1, 0); PG8_STAGE(PG8_SA(0, 1), a2 + hstep, voffA);
;             PG8_WAIT_V(8); PG8_WAIT_L(0); PG8_BAR; PG8_MMA(0, 0, At, B0); PG8_MMA(0, 1, At, B1); PG8_BAR; PG8_SCHED;
	s_waitcnt lgkmcnt(0)
	v_mfma_f32_16x16x32_bf16 v[60:63], v[128:131], v[182:185], v[60:63]
	v_mfma_f32_16x16x32_bf16 v[56:59], v[136:139], v[182:185], v[56:59]
	v_mfma_f32_16x16x32_bf16 v[52:55], v[128:131], v[190:193], v[52:55]
	v_mfma_f32_16x16x32_bf16 v[48:51], v[136:139], v[190:193], v[48:51]
	v_mfma_f32_16x16x32_bf16 v[44:47], v[128:131], v[198:201], v[44:47]
	v_mfma_f32_16x16x32_bf16 v[40:43], v[136:139], v[198:201], v[40:43]
	v_mfma_f32_16x16x32_bf16 v[36:39], v[128:131], v[206:209], v[36:39]
	v_mfma_f32_16x16x32_bf16 v[32:35], v[136:139], v[206:209], v[32:35]
	v_mfma_f32_16x16x32_bf16 v[60:63], v[132:135], v[186:189], v[60:63]
	v_mfma_f32_16x16x32_bf16 v[56:59], v[140:143], v[186:189], v[56:59]
	v_mfma_f32_16x16x32_bf16 v[52:55], v[132:135], v[194:197], v[52:55]
	v_mfma_f32_16x16x32_bf16 v[48:51], v[140:143], v[194:197], v[48:51]
	v_mfma_f32_16x16x32_bf16 v[44:47], v[132:135], v[202:205], v[44:47]
	v_mfma_f32_16x16x32_bf16 v[40:43], v[140:143], v[202:205], v[40:43]
	v_mfma_f32_16x16x32_bf16 v[36:39], v[132:135], v[244:247], v[36:39]
	v_mfma_f32_16x16x32_bf16 v[32:35], v[140:143], v[244:247], v[32:35]
	v_mfma_f32_16x16x32_bf16 v[28:31], v[166:169], v[182:185], v[28:31]
	v_mfma_f32_16x16x32_bf16 v[24:27], v[174:177], v[182:185], v[24:27]
	v_mfma_f32_16x16x32_bf16 v[20:23], v[166:169], v[190:193], v[20:23]
	v_mfma_f32_16x16x32_bf16 v[16:19], v[174:177], v[190:193], v[16:19]
	v_mfma_f32_16x16x32_bf16 v[12:15], v[166:169], v[198:201], v[12:15]
	v_mfma_f32_16x16x32_bf16 v[8:11], v[174:177], v[198:201], v[8:11]
	v_mfma_f32_16x16x32_bf16 v[4:7], v[166:169], v[206:209], v[4:7]
	v_mfma_f32_16x16x32_bf16 v[0:3], v[174:177], v[206:209], v[0:3]
	v_mfma_f32_16x16x32_bf16 v[28:31], v[170:173], v[186:189], v[28:31]
	v_mfma_f32_16x16x32_bf16 v[24:27], v[178:181], v[186:189], v[24:27]
	v_mfma_f32_16x16x32_bf16 v[20:23], v[170:173], v[194:197], v[20:23]
	v_mfma_f32_16x16x32_bf16 v[16:19], v[178:181], v[194:197], v[16:19]
	v_mfma_f32_16x16x32_bf16 v[12:15], v[170:173], v[202:205], v[12:15]
	v_mfma_f32_16x16x32_bf16 v[8:11], v[178:181], v[202:205], v[8:11]
	v_mfma_f32_16x16x32_bf16 v[4:7], v[170:173], v[244:247], v[4:7]
	v_mfma_f32_16x16x32_bf16 v[0:3], v[178:181], v[244:247], v[0:3]
	s_barrier
	s_add_i32 s61, 0, 0x18000
	s_add_i32 s62, 0, 0x1c000
	v_add_u32_e32 v140, s61, v234
	v_add_u32_e32 v178, s62, v234
	ds_read_b128 v[128:131], v140
	ds_read_b128 v[132:135], v140 offset:1024
	ds_read_b128 v[136:139], v140 offset:2048
	ds_read_b128 v[140:143], v140 offset:3072
	ds_read_b128 v[166:169], v178
	ds_read_b128 v[170:173], v178 offset:1024
	ds_read_b128 v[174:177], v178 offset:2048
	ds_read_b128 v[178:181], v178 offset:3072
	s_add_u32 s30, s36, 0xb0000
	s_addc_u32 s31, s37, 0
	s_mov_b32 m0, s48
	v_lshl_add_u64 v[214:215], s[30:31], 0, v[154:155]
	ds_read_b128 v[182:185], v236 offset:32768
	ds_read_b128 v[186:189], v236 offset:33792
	ds_read_b128 v[190:193], v236 offset:34816
	ds_read_b128 v[194:197], v236 offset:35840
	ds_read_b128 v[198:201], v236 offset:36864
	ds_read_b128 v[202:205], v236 offset:37888
	ds_read_b128 v[206:209], v236 offset:38912
	ds_read_b128 v[244:247], v236 offset:39936
	global_load_lds_dwordx4 v[214:215], off
	v_lshl_add_u64 v[214:215], s[30:31], 0, v[156:157]
	s_mov_b32 m0, s49
	s_nop 0
	global_load_lds_dwordx4 v[214:215], off
	s_waitcnt vmcnt(8)
	s_waitcnt lgkmcnt(0)
	s_barrier
	s_waitcnt lgkmcnt(0)
	v_mfma_f32_16x16x32_bf16 v[124:127], v[128:131], v[182:185], v[124:127]
	v_mfma_f32_16x16x32_bf16 v[120:123], v[136:139], v[182:185], v[120:123]
	v_mfma_f32_16x16x32_bf16 v[116:119], v[128:131], v[190:193], v[116:119]
	v_mfma_f32_16x16x32_bf16 v[112:115], v[136:139], v[190:193], v[112:115]
	v_mfma_f32_16x16x32_bf16 v[108:111], v[128:131], v[198:201], v[108:111]
	v_mfma_f32_16x16x32_bf16 v[104:107], v[136:139], v[198:201], v[104:107]
	v_mfma_f32_16x16x32_bf16 v[100:103], v[128:131], v[206:209], v[100:103]
	v_mfma_f32_16x16x32_bf16 v[96:99], v[136:139], v[206:209], v[96:99]
	v_mfma_f32_16x16x32_bf16 v[124:127], v[132:135], v[186:189], v[124:127]
	v_mfma_f32_16x16x32_bf16 v[120:123], v[140:143], v[186:189], v[120:123]
	v_mfma_f32_16x16x32_bf16 v[116:119], v[132:135], v[194:197], v[116:119]
	v_mfma_f32_16x16x32_bf16 v[112:115], v[140:143], v[194:197], v[112:115]
	v_mfma_f32_16x16x32_bf16 v[108:111], v[132:135], v[202:205], v[108:111]
	v_mfma_f32_16x16x32_bf16 v[104:107], v[140:143], v[202:205], v[104:107]
	v_mfma_f32_16x16x32_bf16 v[100:103], v[132:135], v[244:247], v[100:103]
	v_mfma_f32_16x16x32_bf16 v[96:99], v[140:143], v[244:247], v[96:99]
	v_mfma_f32_16x16x32_bf16 v[92:95], v[166:169], v[182:185], v[92:95]
	v_mfma_f32_16x16x32_bf16 v[88:91], v[174:177], v[182:185], v[88:91]
	v_mfma_f32_16x16x32_bf16 v[84:87], v[166:169], v[190:193], v[84:87]
	v_mfma_f32_16x16x32_bf16 v[80:83], v[174:177], v[190:193], v[80:83]
	v_mfma_f32_16x16x32_bf16 v[76:79], v[166:169], v[198:201], v[76:79]
	v_mfma_f32_16x16x32_bf16 v[72:75], v[174:177], v[198:201], v[72:75]
	v_mfma_f32_16x16x32_bf16 v[68:71], v[166:169], v[206:209], v[68:71]
	v_mfma_f32_16x16x32_bf16 v[64:67], v[174:177], v[206:209], v[64:67]
	v_mfma_f32_16x16x32_bf16 v[92:95], v[170:173], v[186:189], v[92:95]
	v_mfma_f32_16x16x32_bf16 v[88:91], v[178:181], v[186:189], v[88:91]
	v_mfma_f32_16x16x32_bf16 v[84:87], v[170:173], v[194:197], v[84:87]
	v_mfma_f32_16x16x32_bf16 v[80:83], v[178:181], v[194:197], v[80:83]
	v_mfma_f32_16x16x32_bf16 v[76:79], v[170:173], v[202:205], v[76:79]
	v_mfma_f32_16x16x32_bf16 v[72:75], v[178:181], v[202:205], v[72:75]
	v_mfma_f32_16x16x32_bf16 v[68:71], v[170:173], v[244:247], v[68:71]
	v_mfma_f32_16x16x32_bf16 v[64:67], v[178:181], v[244:247], v[64:67]
	s_barrier
; #define PG8_STAGE(bufoff, gbase, voff) do { _Pragma("unroll") for (int _i = 0; _i < 2; ++_i) \
;         __builtin_amdgcn_global_load_lds((const unsigned*)((const char*)(gbase) + (voff)[_i]), (PG8_LAS unsigned*)(lds + (bufoff) + ldsw + _i * 8192), 16, 0, 0); } while (0)
; #define PG8_LDA(dst, b, h) do { _Pragma("unroll") for (int m = 0; m < 4; ++m) _Pragma("unroll") for (int k = 0; k < 2; ++k) dst[m][k] = *(const PG8_LAS bf16x8*)(lds + PG8_SA(b, h) + aoff + m * 2048 + k * 1024); } while (0)
; #define PG8_MMA(ai, bj, At, Bt) do { __builtin_amdgcn_s_setprio(1); _Pragma("unroll") for (int m = 0; m < 4; ++m) _Pragma("unroll") for (int n = 0; n < 2; ++n) _Pragma("unroll") for (int k = 0; k < 2; ++k) \
;         acc[ai][bj][m][n] = __builtin_amdgcn_mfma_f32_16x16x32_bf16(Bt[n][k], At[m][k], acc[ai][bj][m][n], 0, 0, 0); __builtin_amdgcn_s_setprio(0); } while (0)
; #define PG8_WAIT_V(n) asm volatile("s_waitcnt vmcnt(" #n ")" ::: "memory")
; #define PG8_WAIT_L(n) asm volatile("s_waitcnt lgkmcnt(" #n ")" ::: "memory")
; #define PG8_BAR __builtin_amdgcn_s_barrier()
; #define PG8_SCHED __builtin_amdgcn_sched_barrier(0)
; template <class Epi, class Sched, bool ALIGN_EPI = false, bool SP2 = false>
; __device__ __forceinline__ void gemm_phase(PG8_LAS unsigned char* lds, const Gemm g, const Sched& S, const Epi& E) {
;     ...
;             PG8_LDA(At, 1, 1); PG8_STAGE(PG8_SB(1, 0), b3, voffB); PG8_STAGE(PG8_SB(1, 1), b3 + hstep, voffB); PG8_STAGE(PG8_SA(1, 0), a3, voffA);
;             PG8_WAIT_V(8); PG8_WAIT_L(0); PG8_BAR; PG8_MMA(1, 0, At, B0); PG8_MMA(1, 1, At, B1); PG8_BAR; PG8_SCHED;
	s_add_i32 s30, s61, s45
	v_lshl_add_u64 v[210:211], v[210:211], 0, s[66:67]
	s_mov_b32 m0, s30
	ds_read_b128 v[182:185], v236 offset:49152
	ds_read_b128 v[186:189], v236 offset:50176
	ds_read_b128 v[190:193], v236 offset:51200
	ds_read_b128 v[194:197], v236 offset:52224
	ds_read_b128 v[198:201], v236 offset:53248
	ds_read_b128 v[202:205], v236 offset:54272
	ds_read_b128 v[206:209], v236 offset:55296
	ds_read_b128 v[244:247], v236 offset:56320
	global_load_lds_dwordx4 v[210:211], off
	s_add_i32 m0, s30, 0x2000
	s_add_u32 s30, s34, 0xb0080
	v_lshl_add_u64 v[210:211], v[248:249], 0, s[66:67]
	s_addc_u32 s31, s35, 0
	s_add_i32 s34, s62, s45
	global_load_lds_dwordx4 v[210:211], off
	v_lshl_add_u64 v[210:211], s[30:31], 0, v[144:145]
	s_mov_b32 m0, s34
	s_nop 0
	global_load_lds_dwordx4 v[210:211], off
	v_lshl_add_u64 v[210:211], s[30:31], 0, v[158:159]
	s_add_i32 m0, s34, 0x2000
	s_nop 0
	global_load_lds_dwordx4 v[210:211], off
	v_lshl_add_u64 v[210:211], v[250:251], 0, s[66:67]
	s_mov_b32 m0, s52
	s_nop 0
	global_load_lds_dwordx4 v[210:211], off
	v_lshl_add_u64 v[210:211], v[252:253], 0, s[66:67]
	s_mov_b32 m0, s53
	s_nop 0
	global_load_lds_dwordx4 v[210:211], off
	s_waitcnt vmcnt(8)
	s_waitcnt lgkmcnt(0)
	s_barrier
	s_waitcnt lgkmcnt(0)
	v_mfma_f32_16x16x32_bf16 v[60:63], v[128:131], v[182:185], v[60:63]
	v_mfma_f32_16x16x32_bf16 v[56:59], v[136:139], v[182:185], v[56:59]
	v_mfma_f32_16x16x32_bf16 v[52:55], v[128:131], v[190:193], v[52:55]
	v_mfma_f32_16x16x32_bf16 v[48:51], v[136:139], v[190:193], v[48:51]
	v_mfma_f32_16x16x32_bf16 v[44:47], v[128:131], v[198:201], v[44:47]
	v_mfma_f32_16x16x32_bf16 v[40:43], v[136:139], v[198:201], v[40:43]
	v_mfma_f32_16x16x32_bf16 v[36:39], v[128:131], v[206:209], v[36:39]
	v_mfma_f32_16x16x32_bf16 v[32:35], v[136:139], v[206:209], v[32:35]
	v_mfma_f32_16x16x32_bf16 v[60:63], v[132:135], v[186:189], v[60:63]
	v_mfma_f32_16x16x32_bf16 v[56:59], v[140:143], v[186:189], v[56:59]
	v_mfma_f32_16x16x32_bf16 v[52:55], v[132:135], v[194:197], v[52:55]
	v_mfma_f32_16x16x32_bf16 v[48:51], v[140:143], v[194:197], v[48:51]
	v_mfma_f32_16x16x32_bf16 v[44:47], v[132:135], v[202:205], v[44:47]
	v_mfma_f32_16x16x32_bf16 v[40:43], v[140:143], v[202:205], v[40:43]
	v_mfma_f32_16x16x32_bf16 v[36:39], v[132:135], v[244:247], v[36:39]
	v_mfma_f32_16x16x32_bf16 v[32:35], v[140:143], v[244:247], v[32:35]
	v_mfma_f32_16x16x32_bf16 v[28:31], v[166:169], v[182:185], v[28:31]
	v_mfma_f32_16x16x32_bf16 v[24:27], v[174:177], v[182:185], v[24:27]
	v_mfma_f32_16x16x32_bf16 v[20:23], v[166:169], v[190:193], v[20:23]
	v_mfma_f32_16x16x32_bf16 v[16:19], v[174:177], v[190:193], v[16:19]
	v_mfma_f32_16x16x32_bf16 v[12:15], v[166:169], v[198:201], v[12:15]
	v_mfma_f32_16x16x32_bf16 v[8:11], v[174:177], v[198:201], v[8:11]
	v_mfma_f32_16x16x32_bf16 v[4:7], v[166:169], v[206:209], v[4:7]
	v_mfma_f32_16x16x32_bf16 v[0:3], v[174:177], v[206:209], v[0:3]
	v_mfma_f32_16x16x32_bf16 v[28:31], v[170:173], v[186:189], v[28:31]
	v_mfma_f32_16x16x32_bf16 v[24:27], v[178:181], v[186:189], v[24:27]
	v_mfma_f32_16x16x32_bf16 v[20:23], v[170:173], v[194:197], v[20:23]
	v_mfma_f32_16x16x32_bf16 v[16:19], v[178:181], v[194:197], v[16:19]
	v_mfma_f32_16x16x32_bf16 v[12:15], v[170:173], v[202:205], v[12:15]
	v_mfma_f32_16x16x32_bf16 v[8:11], v[178:181], v[202:205], v[8:11]
	v_mfma_f32_16x16x32_bf16 v[4:7], v[170:173], v[244:247], v[4:7]
	v_mfma_f32_16x16x32_bf16 v[0:3], v[178:181], v[244:247], v[0:3]
	s_barrier
	s_add_u32 s58, s58, 0x100
	s_addc_u32 s59, s59, 0
	s_cmp_ge_i32 s60, s27
	s_mov_b64 s[30:31], s[12:13]
	s_mov_b32 s34, s60
	s_cbranch_scc0 .LBB0_377
	s_and_b64 vcc, exec, s[18:19]
	s_cbranch_vccz .LBB0_380

; #define PG8_STAGE(bufoff, gbase, voff) do { _Pragma("unroll") for (int _i = 0; _i < 2; ++_i) \
;         __builtin_amdgcn_global_load_lds((const unsigned*)((const char*)(gbase) + (voff)[_i]), (PG8_LAS unsigned*)(lds + (bufoff) + ldsw + _i * 8192), 16, 0, 0); } while (0)
; #define PG8_LDA(dst, b, h) do { _Pragma("unroll") for (int m = 0; m < 4; ++m) _Pragma("unroll") for (int k = 0; k < 2; ++k) dst[m][k] = *(const PG8_LAS bf16x8*)(lds + PG8_SA(b, h) + aoff + m * 2048 + k * 1024); } while (0)
; #define PG8_LDB(dst, b, h) do { _Pragma("unroll") for (int n = 0; n < 2; ++n) _Pragma("unroll") for (int k = 0; k < 2; ++k) dst[n][k] = *(const PG8_LAS bf16x8*)(lds + PG8_SB(b, h) + boff + n * 2048 + k * 1024); } while (0)
; #define PG8_MMA(ai, bj, At, Bt) do { __builtin_amdgcn_s_setprio(1); _Pragma("unroll") for (int m = 0; m < 4; ++m) _Pragma("unroll") for (int n = 0; n < 2; ++n) _Pragma("unroll") for (int k = 0; k < 2; ++k) \
;         acc[ai][bj][m][n] = __builtin_amdgcn_mfma_f32_16x16x32_bf16(Bt[n][k], At[m][k], acc[ai][bj][m][n], 0, 0, 0); __builtin_amdgcn_s_setprio(0); } while (0)
; #define PG8_WAIT_V(n) asm volatile("s_waitcnt vmcnt(" #n ")" ::: "memory")
; #define PG8_WAIT_L(n) asm volatile("s_waitcnt lgkmcnt(" #n ")" ::: "memory")
; #define PG8_BAR __builtin_amdgcn_s_barrier()
; #define PG8_SCHED __builtin_amdgcn_sched_barrier(0)
; template <class Epi, class Sched, bool ALIGN_EPI = false, bool SP2 = false>
; __device__ __forceinline__ void gemm_phase(PG8_LAS unsigned char* lds, const Gemm g, const Sched& S, const Epi& E) {
;     ...
;             const bool last = (t == nt - 2);
;             const char* a1 = cA + (size_t)(t + 1) * kstep;
;             const char* a2 = last ? nA : cA + (size_t)(t + 2) * kstep; const char* b2 = last ? nB : cB + (size_t)(t + 2) * kstep;
;             const char* a3 = a2 + kstep; const char* b3 = b2 + kstep;
;             if (last && has_next) S.a_ready(nxt);
;             if constexpr (SP2) {
;             PG8_LDB(B0, 0, 0); PG8_LDB(B1, 0, 1); PG8_SCHED; PG8_LDA(At, 0, 0); PG8_STAGE(PG8_SA(1, 1), a1 + hstep, voffA);
;             PG8_WAIT_V(8); PG8_WAIT_L(0); PG8_BAR; PG8_MMA(0, 0, At, B0); PG8_MMA(0, 1, At, B1); PG8_BAR; PG8_SCHED;
;             PG8_LDA(At, 0, 1); PG8_STAGE(PG8_SB(0, 0), b2, voffB); PG8_STAGE(PG8_SB(0, 1), b2 + hstep, voffB); PG8_STAGE(PG8_SA(0, 0), a2, voffA);
.LBB0_453:
	s_add_u32 s18, s16, 0x100
	s_addc_u32 s19, s17, 0
	s_add_i32 s47, 0, 0x10000
	s_cmp_eq_u32 s46, 40
	s_cselect_b32 s23, s13, s19
	s_cselect_b32 s22, s12, s18
	v_add_u32_e32 v142, s47, v157
	s_cselect_b32 s21, s15, s45
	s_cselect_b32 s20, s14, s43
	s_add_i32 s48, 0, 0x14000
	ds_read_b128 v[138:141], v142
	ds_read_b128 v[160:163], v142 offset:1024
	ds_read_b128 v[164:167], v142 offset:2048
	ds_read_b128 v[168:171], v142 offset:3072
	v_add_u32_e32 v142, s48, v157
	ds_read_b128 v[172:175], v142
	ds_read_b128 v[176:179], v142 offset:1024
	ds_read_b128 v[180:183], v142 offset:2048
	ds_read_b128 v[184:187], v142 offset:3072
	v_lshl_add_u64 v[142:143], s[16:17], 0, v[136:137]
	s_add_i32 m0, s24, 0xc000
	ds_read_b128 v[188:191], v159
	ds_read_b128 v[192:195], v159 offset:1024
	ds_read_b128 v[196:199], v159 offset:2048
	ds_read_b128 v[200:203], v159 offset:3072
	ds_read_b128 v[204:207], v159 offset:4096
	ds_read_b128 v[208:211], v159 offset:5120
	ds_read_b128 v[234:237], v159 offset:6144
	ds_read_b128 v[244:247], v159 offset:7168
	global_load_lds_dwordx4 v[142:143], off
	v_lshl_add_u64 v[142:143], s[16:17], 0, v[134:135]
	s_add_i32 m0, s24, 0xe000
	s_nop 0
	global_load_lds_dwordx4 v[142:143], off
	s_waitcnt vmcnt(8)
	s_waitcnt lgkmcnt(0)
	s_barrier
	s_waitcnt lgkmcnt(0)
	v_mfma_f32_16x16x32_bf16 v[124:127], v[138:141], v[188:191], v[124:127]
	v_mfma_f32_16x16x32_bf16 v[120:123], v[164:167], v[188:191], v[120:123]
	v_mfma_f32_16x16x32_bf16 v[108:111], v[138:141], v[196:199], v[108:111]
	v_mfma_f32_16x16x32_bf16 v[104:107], v[164:167], v[196:199], v[104:107]
	v_mfma_f32_16x16x32_bf16 v[92:95], v[138:141], v[204:207], v[92:95]
	v_mfma_f32_16x16x32_bf16 v[88:91], v[164:167], v[204:207], v[88:91]
	v_mfma_f32_16x16x32_bf16 v[76:79], v[138:141], v[234:237], v[76:79]
	v_mfma_f32_16x16x32_bf16 v[72:75], v[164:167], v[234:237], v[72:75]
	v_mfma_f32_16x16x32_bf16 v[124:127], v[160:163], v[192:195], v[124:127]
	v_mfma_f32_16x16x32_bf16 v[120:123], v[168:171], v[192:195], v[120:123]
	v_mfma_f32_16x16x32_bf16 v[108:111], v[160:163], v[200:203], v[108:111]
	v_mfma_f32_16x16x32_bf16 v[104:107], v[168:171], v[200:203], v[104:107]
	v_mfma_f32_16x16x32_bf16 v[92:95], v[160:163], v[208:211], v[92:95]
	v_mfma_f32_16x16x32_bf16 v[88:91], v[168:171], v[208:211], v[88:91]
	v_mfma_f32_16x16x32_bf16 v[76:79], v[160:163], v[244:247], v[76:79]
	v_mfma_f32_16x16x32_bf16 v[72:75], v[168:171], v[244:247], v[72:75]
	v_mfma_f32_16x16x32_bf16 v[116:119], v[172:175], v[188:191], v[116:119]
	v_mfma_f32_16x16x32_bf16 v[112:115], v[180:183], v[188:191], v[112:115]
	v_mfma_f32_16x16x32_bf16 v[100:103], v[172:175], v[196:199], v[100:103]
	v_mfma_f32_16x16x32_bf16 v[96:99], v[180:183], v[196:199], v[96:99]
	v_mfma_f32_16x16x32_bf16 v[84:87], v[172:175], v[204:207], v[84:87]
	v_mfma_f32_16x16x32_bf16 v[80:83], v[180:183], v[204:207], v[80:83]
	v_mfma_f32_16x16x32_bf16 v[68:71], v[172:175], v[234:237], v[68:71]
	v_mfma_f32_16x16x32_bf16 v[64:67], v[180:183], v[234:237], v[64:67]
	v_mfma_f32_16x16x32_bf16 v[116:119], v[176:179], v[192:195], v[116:119]
	v_mfma_f32_16x16x32_bf16 v[112:115], v[184:187], v[192:195], v[112:115]
	v_mfma_f32_16x16x32_bf16 v[100:103], v[176:179], v[200:203], v[100:103]
	v_mfma_f32_16x16x32_bf16 v[96:99], v[184:187], v[200:203], v[96:99]
	v_mfma_f32_16x16x32_bf16 v[84:87], v[176:179], v[208:211], v[84:87]
	v_mfma_f32_16x16x32_bf16 v[80:83], v[184:187], v[208:211], v[80:83]
	v_mfma_f32_16x16x32_bf16 v[68:71], v[176:179], v[244:247], v[68:71]
	v_mfma_f32_16x16x32_bf16 v[64:67], v[184:187], v[244:247], v[64:67]
	s_barrier
	s_add_i32 s16, s47, s0
	v_lshl_add_u64 v[142:143], s[20:21], 0, v[144:145]
	s_mov_b32 m0, s16
	ds_read_b128 v[188:191], v159 offset:16384
	ds_read_b128 v[192:195], v159 offset:17408
	ds_read_b128 v[196:199], v159 offset:18432
	ds_read_b128 v[200:203], v159 offset:19456
	ds_read_b128 v[204:207], v159 offset:20480
	ds_read_b128 v[208:211], v159 offset:21504
	ds_read_b128 v[234:237], v159 offset:22528
	ds_read_b128 v[244:247], v159 offset:23552
	global_load_lds_dwordx4 v[142:143], off
	s_add_i32 m0, s16, 0x2000
	s_add_u32 s16, s20, 0xb0000
	v_lshl_add_u64 v[154:155], s[20:21], 0, v[132:133]
	s_addc_u32 s17, s21, 0
	s_add_i32 s47, s48, s0
	global_load_lds_dwordx4 v[154:155], off
	v_lshl_add_u64 v[214:215], s[16:17], 0, v[144:145]
	s_mov_b32 m0, s47
	v_lshl_add_u64 v[238:239], s[22:23], 0, v[130:131]
	global_load_lds_dwordx4 v[214:215], off
	v_lshl_add_u64 v[214:215], s[16:17], 0, v[132:133]
	s_add_i32 m0, s47, 0x2000
	s_nop 0
	global_load_lds_dwordx4 v[214:215], off
	v_lshl_add_u64 v[214:215], s[22:23], 0, v[128:129]
	s_mov_b32 m0, s24
	s_nop 0
	global_load_lds_dwordx4 v[214:215], off
	s_mov_b32 m0, s25
	s_nop 0
	global_load_lds_dwordx4 v[238:239], off
	s_waitcnt vmcnt(8)
	s_waitcnt lgkmcnt(0)
	s_barrier
; #define PG8_STAGE(bufoff, gbase, voff) do { _Pragma("unroll") for (int _i = 0; _i < 2; ++_i) \
;         __builtin_amdgcn_global_load_lds((const unsigned*)((const char*)(gbase) + (voff)[_i]), (PG8_LAS unsigned*)(lds + (bufoff) + ldsw + _i * 8192), 16, 0, 0); } while (0)
; #define PG8_LDA(dst, b, h) do { _Pragma("unroll") for (int m = 0; m < 4; ++m) _Pragma("unroll") for (int k = 0; k < 2; ++k) dst[m][k] = *(const PG8_LAS bf16x8*)(lds + PG8_SA(b, h) + aoff + m * 2048 + k * 1024); } while (0)
; #define PG8_LDB(dst, b, h) do { _Pragma("unroll") for (int n = 0; n < 2; ++n) _Pragma("unroll") for (int k = 0; k < 2; ++k) dst[n][k] = *(const PG8_LAS bf16x8*)(lds + PG8_SB(b, h) + boff + n * 2048 + k * 1024); } while (0)
; #define PG8_MMA(ai, bj, At, Bt) do { __builtin_amdgcn_s_setprio(1); _Pragma("unroll") for (int m = 0; m < 4; ++m) _Pragma("unroll") for (int n = 0; n < 2; ++n) _Pragma("unroll") for (int k = 0; k < 2; ++k) \
;         acc[ai][bj][m][n] = __builtin_amdgcn_mfma_f32_16x16x32_bf16(Bt[n][k], At[m][k], acc[ai][bj][m][n], 0, 0, 0); __builtin_amdgcn_s_setprio(0); } while (0)
; #define PG8_WAIT_V(n) asm volatile("s_waitcnt vmcnt(" #n ")" ::: "memory")
; #define PG8_WAIT_L(n) asm volatile("s_waitcnt lgkmcnt(" #n ")" ::: "memory")
; #define PG8_BAR __builtin_amdgcn_s_barrier()
; #define PG8_SCHED __builtin_amdgcn_sched_barrier(0)
; template <class Epi, class Sched, bool ALIGN_EPI = false, bool SP2 = false>
; __device__ __forceinline__ void gemm_phase(PG8_LAS unsigned char* lds, const Gemm g, const Sched& S, const Epi& E) {
;     ...
;             PG8_WAIT_V(8); PG8_WAIT_L(0); PG8_BAR; PG8_MMA(1, 0, At, B0); PG8_MMA(1, 1, At, B1); PG8_BAR; PG8_SCHED;
;             PG8_LDB(B0, 1, 0); PG8_LDB(B1, 1, 1); PG8_SCHED; PG8_LDA(At, 1, 0); PG8_STAGE(PG8_SA(0, 1), a2 + hstep, voffA);
;             PG8_WAIT_V(8); PG8_WAIT_L(0); PG8_BAR; PG8_MMA(0, 0, At, B0); PG8_MMA(0, 1, At, B1); PG8_BAR; PG8_SCHED;
	s_waitcnt lgkmcnt(0)
	v_mfma_f32_16x16x32_bf16 v[60:63], v[138:141], v[188:191], v[60:63]
	v_mfma_f32_16x16x32_bf16 v[56:59], v[164:167], v[188:191], v[56:59]
	v_mfma_f32_16x16x32_bf16 v[44:47], v[138:141], v[196:199], v[44:47]
	v_mfma_f32_16x16x32_bf16 v[40:43], v[164:167], v[196:199], v[40:43]
	v_mfma_f32_16x16x32_bf16 v[28:31], v[138:141], v[204:207], v[28:31]
	v_mfma_f32_16x16x32_bf16 v[24:27], v[164:167], v[204:207], v[24:27]
	v_mfma_f32_16x16x32_bf16 v[12:15], v[138:141], v[234:237], v[12:15]
	v_mfma_f32_16x16x32_bf16 v[8:11], v[164:167], v[234:237], v[8:11]
	v_mfma_f32_16x16x32_bf16 v[60:63], v[160:163], v[192:195], v[60:63]
	v_mfma_f32_16x16x32_bf16 v[56:59], v[168:171], v[192:195], v[56:59]
	v_mfma_f32_16x16x32_bf16 v[44:47], v[160:163], v[200:203], v[44:47]
	v_mfma_f32_16x16x32_bf16 v[40:43], v[168:171], v[200:203], v[40:43]
	v_mfma_f32_16x16x32_bf16 v[28:31], v[160:163], v[208:211], v[28:31]
	v_mfma_f32_16x16x32_bf16 v[24:27], v[168:171], v[208:211], v[24:27]
	v_mfma_f32_16x16x32_bf16 v[12:15], v[160:163], v[244:247], v[12:15]
	v_mfma_f32_16x16x32_bf16 v[8:11], v[168:171], v[244:247], v[8:11]
	v_mfma_f32_16x16x32_bf16 v[52:55], v[172:175], v[188:191], v[52:55]
	v_mfma_f32_16x16x32_bf16 v[48:51], v[180:183], v[188:191], v[48:51]
	v_mfma_f32_16x16x32_bf16 v[36:39], v[172:175], v[196:199], v[36:39]
	v_mfma_f32_16x16x32_bf16 v[32:35], v[180:183], v[196:199], v[32:35]
	v_mfma_f32_16x16x32_bf16 v[20:23], v[172:175], v[204:207], v[20:23]
	v_mfma_f32_16x16x32_bf16 v[16:19], v[180:183], v[204:207], v[16:19]
	v_mfma_f32_16x16x32_bf16 v[4:7], v[172:175], v[234:237], v[4:7]
	v_mfma_f32_16x16x32_bf16 v[0:3], v[180:183], v[234:237], v[0:3]
	v_mfma_f32_16x16x32_bf16 v[52:55], v[176:179], v[192:195], v[52:55]
	v_mfma_f32_16x16x32_bf16 v[48:51], v[184:187], v[192:195], v[48:51]
	v_mfma_f32_16x16x32_bf16 v[36:39], v[176:179], v[200:203], v[36:39]
	v_mfma_f32_16x16x32_bf16 v[32:35], v[184:187], v[200:203], v[32:35]
	v_mfma_f32_16x16x32_bf16 v[20:23], v[176:179], v[208:211], v[20:23]
	v_mfma_f32_16x16x32_bf16 v[16:19], v[184:187], v[208:211], v[16:19]
	v_mfma_f32_16x16x32_bf16 v[4:7], v[176:179], v[244:247], v[4:7]
	v_mfma_f32_16x16x32_bf16 v[0:3], v[184:187], v[244:247], v[0:3]
	s_barrier
	s_add_i32 s47, 0, 0x18000
	s_add_i32 s48, 0, 0x1c000
	v_add_u32_e32 v168, s47, v157
	v_add_u32_e32 v184, s48, v157
	ds_read_b128 v[138:141], v168
	ds_read_b128 v[160:163], v168 offset:1024
	ds_read_b128 v[164:167], v168 offset:2048
	ds_read_b128 v[168:171], v168 offset:3072
	ds_read_b128 v[172:175], v184
	ds_read_b128 v[176:179], v184 offset:1024
	ds_read_b128 v[180:183], v184 offset:2048
	ds_read_b128 v[184:187], v184 offset:3072
	s_add_u32 s16, s22, 0xb0000
	s_addc_u32 s17, s23, 0
	s_mov_b32 m0, s26
	v_lshl_add_u64 v[248:249], s[16:17], 0, v[128:129]
	ds_read_b128 v[188:191], v159 offset:32768
	ds_read_b128 v[192:195], v159 offset:33792
	ds_read_b128 v[196:199], v159 offset:34816
	ds_read_b128 v[200:203], v159 offset:35840
	ds_read_b128 v[204:207], v159 offset:36864
	ds_read_b128 v[208:211], v159 offset:37888
	ds_read_b128 v[234:237], v159 offset:38912
	ds_read_b128 v[244:247], v159 offset:39936
	global_load_lds_dwordx4 v[248:249], off
	v_lshl_add_u64 v[248:249], s[16:17], 0, v[130:131]
	s_mov_b32 m0, s27
	s_nop 0
	global_load_lds_dwordx4 v[248:249], off
	s_waitcnt vmcnt(8)
	s_waitcnt lgkmcnt(0)
	s_barrier
	s_waitcnt lgkmcnt(0)
	v_mfma_f32_16x16x32_bf16 v[124:127], v[138:141], v[188:191], v[124:127]
	v_mfma_f32_16x16x32_bf16 v[120:123], v[164:167], v[188:191], v[120:123]
	v_mfma_f32_16x16x32_bf16 v[108:111], v[138:141], v[196:199], v[108:111]
	v_mfma_f32_16x16x32_bf16 v[104:107], v[164:167], v[196:199], v[104:107]
	v_mfma_f32_16x16x32_bf16 v[92:95], v[138:141], v[204:207], v[92:95]
	v_mfma_f32_16x16x32_bf16 v[88:91], v[164:167], v[204:207], v[88:91]
	v_mfma_f32_16x16x32_bf16 v[76:79], v[138:141], v[234:237], v[76:79]
	v_mfma_f32_16x16x32_bf16 v[72:75], v[164:167], v[234:237], v[72:75]
	v_mfma_f32_16x16x32_bf16 v[124:127], v[160:163], v[192:195], v[124:127]
	v_mfma_f32_16x16x32_bf16 v[120:123], v[168:171], v[192:195], v[120:123]
	v_mfma_f32_16x16x32_bf16 v[108:111], v[160:163], v[200:203], v[108:111]
	v_mfma_f32_16x16x32_bf16 v[104:107], v[168:171], v[200:203], v[104:107]
	v_mfma_f32_16x16x32_bf16 v[92:95], v[160:163], v[208:211], v[92:95]
	v_mfma_f32_16x16x32_bf16 v[88:91], v[168:171], v[208:211], v[88:91]
	v_mfma_f32_16x16x32_bf16 v[76:79], v[160:163], v[244:247], v[76:79]
	v_mfma_f32_16x16x32_bf16 v[72:75], v[168:171], v[244:247], v[72:75]
	v_mfma_f32_16x16x32_bf16 v[116:119], v[172:175], v[188:191], v[116:119]
	v_mfma_f32_16x16x32_bf16 v[112:115], v[180:183], v[188:191], v[112:115]
	v_mfma_f32_16x16x32_bf16 v[100:103], v[172:175], v[196:199], v[100:103]
	v_mfma_f32_16x16x32_bf16 v[96:99], v[180:183], v[196:199], v[96:99]
	v_mfma_f32_16x16x32_bf16 v[84:87], v[172:175], v[204:207], v[84:87]
	v_mfma_f32_16x16x32_bf16 v[80:83], v[180:183], v[204:207], v[80:83]
	v_mfma_f32_16x16x32_bf16 v[68:71], v[172:175], v[234:237], v[68:71]
	v_mfma_f32_16x16x32_bf16 v[64:67], v[180:183], v[234:237], v[64:67]
	v_mfma_f32_16x16x32_bf16 v[116:119], v[176:179], v[192:195], v[116:119]
	v_mfma_f32_16x16x32_bf16 v[112:115], v[184:187], v[192:195], v[112:115]
	v_mfma_f32_16x16x32_bf16 v[100:103], v[176:179], v[200:203], v[100:103]
	v_mfma_f32_16x16x32_bf16 v[96:99], v[184:187], v[200:203], v[96:99]
	v_mfma_f32_16x16x32_bf16 v[84:87], v[176:179], v[208:211], v[84:87]
	v_mfma_f32_16x16x32_bf16 v[80:83], v[184:187], v[208:211], v[80:83]
	v_mfma_f32_16x16x32_bf16 v[68:71], v[176:179], v[244:247], v[68:71]
	v_mfma_f32_16x16x32_bf16 v[64:67], v[184:187], v[244:247], v[64:67]
	s_barrier
; #define PG8_STAGE(bufoff, gbase, voff) do { _Pragma("unroll") for (int _i = 0; _i < 2; ++_i) \
;         __builtin_amdgcn_global_load_lds((const unsigned*)((const char*)(gbase) + (voff)[_i]), (PG8_LAS unsigned*)(lds + (bufoff) + ldsw + _i * 8192), 16, 0, 0); } while (0)
; #define PG8_LDA(dst, b, h) do { _Pragma("unroll") for (int m = 0; m < 4; ++m) _Pragma("unroll") for (int k = 0; k < 2; ++k) dst[m][k] = *(const PG8_LAS bf16x8*)(lds + PG8_SA(b, h) + aoff + m * 2048 + k * 1024); } while (0)
; #define PG8_MMA(ai, bj, At, Bt) do { __builtin_amdgcn_s_setprio(1); _Pragma("unroll") for (int m = 0; m < 4; ++m) _Pragma("unroll") for (int n = 0; n < 2; ++n) _Pragma("unroll") for (int k = 0; k < 2; ++k) \
;         acc[ai][bj][m][n] = __builtin_amdgcn_mfma_f32_16x16x32_bf16(Bt[n][k], At[m][k], acc[ai][bj][m][n], 0, 0, 0); __builtin_amdgcn_s_setprio(0); } while (0)
; #define PG8_WAIT_V(n) asm volatile("s_waitcnt vmcnt(" #n ")" ::: "memory")
; #define PG8_WAIT_L(n) asm volatile("s_waitcnt lgkmcnt(" #n ")" ::: "memory")
; #define PG8_BAR __builtin_amdgcn_s_barrier()
; #define PG8_SCHED __builtin_amdgcn_sched_barrier(0)
; template <class Epi, class Sched, bool ALIGN_EPI = false, bool SP2 = false>
; __device__ __forceinline__ void gemm_phase(PG8_LAS unsigned char* lds, const Gemm g, const Sched& S, const Epi& E) {
;     ...
;             PG8_LDA(At, 1, 1); PG8_STAGE(PG8_SB(1, 0), b3, voffB); PG8_STAGE(PG8_SB(1, 1), b3 + hstep, voffB); PG8_STAGE(PG8_SA(1, 0), a3, voffA);
;             PG8_WAIT_V(8); PG8_WAIT_L(0); PG8_BAR; PG8_MMA(1, 0, At, B0); PG8_MMA(1, 1, At, B1); PG8_BAR; PG8_SCHED;
;     ...
;         if constexpr (ALIGN_EPI) { if (wr == 0) PG8_BAR; }
	s_add_i32 s16, s47, s0
	v_lshl_add_u64 v[142:143], v[142:143], 0, s[50:51]
	s_mov_b32 m0, s16
	ds_read_b128 v[188:191], v159 offset:49152
	ds_read_b128 v[192:195], v159 offset:50176
	ds_read_b128 v[196:199], v159 offset:51200
	ds_read_b128 v[200:203], v159 offset:52224
	ds_read_b128 v[204:207], v159 offset:53248
	ds_read_b128 v[208:211], v159 offset:54272
	ds_read_b128 v[234:237], v159 offset:55296
	ds_read_b128 v[244:247], v159 offset:56320
	global_load_lds_dwordx4 v[142:143], off
	s_add_i32 m0, s16, 0x2000
	s_add_u32 s16, s20, 0xb0080
	v_lshl_add_u64 v[142:143], v[154:155], 0, s[50:51]
	s_addc_u32 s17, s21, 0
	s_add_i32 s20, s48, s0
	global_load_lds_dwordx4 v[142:143], off
	v_lshl_add_u64 v[142:143], s[16:17], 0, v[144:145]
	s_mov_b32 m0, s20
	s_nop 0
	global_load_lds_dwordx4 v[142:143], off
	v_lshl_add_u64 v[142:143], s[16:17], 0, v[132:133]
	s_add_i32 m0, s20, 0x2000
	s_nop 0
	global_load_lds_dwordx4 v[142:143], off
	v_lshl_add_u64 v[142:143], v[214:215], 0, s[50:51]
	s_mov_b32 m0, s30
	s_nop 0
	global_load_lds_dwordx4 v[142:143], off
	v_lshl_add_u64 v[142:143], v[238:239], 0, s[50:51]
	s_mov_b32 m0, s31
	s_nop 0
	global_load_lds_dwordx4 v[142:143], off
	s_waitcnt vmcnt(8)
	s_waitcnt lgkmcnt(0)
	s_barrier
	s_waitcnt lgkmcnt(0)
	v_mfma_f32_16x16x32_bf16 v[60:63], v[138:141], v[188:191], v[60:63]
	v_mfma_f32_16x16x32_bf16 v[56:59], v[164:167], v[188:191], v[56:59]
	v_mfma_f32_16x16x32_bf16 v[44:47], v[138:141], v[196:199], v[44:47]
	v_mfma_f32_16x16x32_bf16 v[40:43], v[164:167], v[196:199], v[40:43]
	v_mfma_f32_16x16x32_bf16 v[28:31], v[138:141], v[204:207], v[28:31]
	v_mfma_f32_16x16x32_bf16 v[24:27], v[164:167], v[204:207], v[24:27]
	v_mfma_f32_16x16x32_bf16 v[12:15], v[138:141], v[234:237], v[12:15]
	v_mfma_f32_16x16x32_bf16 v[8:11], v[164:167], v[234:237], v[8:11]
	v_mfma_f32_16x16x32_bf16 v[60:63], v[160:163], v[192:195], v[60:63]
	v_mfma_f32_16x16x32_bf16 v[56:59], v[168:171], v[192:195], v[56:59]
	v_mfma_f32_16x16x32_bf16 v[44:47], v[160:163], v[200:203], v[44:47]
	v_mfma_f32_16x16x32_bf16 v[40:43], v[168:171], v[200:203], v[40:43]
	v_mfma_f32_16x16x32_bf16 v[28:31], v[160:163], v[208:211], v[28:31]
	v_mfma_f32_16x16x32_bf16 v[24:27], v[168:171], v[208:211], v[24:27]
	v_mfma_f32_16x16x32_bf16 v[12:15], v[160:163], v[244:247], v[12:15]
	v_mfma_f32_16x16x32_bf16 v[8:11], v[168:171], v[244:247], v[8:11]
	v_mfma_f32_16x16x32_bf16 v[52:55], v[172:175], v[188:191], v[52:55]
	v_mfma_f32_16x16x32_bf16 v[48:51], v[180:183], v[188:191], v[48:51]
	v_mfma_f32_16x16x32_bf16 v[36:39], v[172:175], v[196:199], v[36:39]
	v_mfma_f32_16x16x32_bf16 v[32:35], v[180:183], v[196:199], v[32:35]
	v_mfma_f32_16x16x32_bf16 v[20:23], v[172:175], v[204:207], v[20:23]
	v_mfma_f32_16x16x32_bf16 v[16:19], v[180:183], v[204:207], v[16:19]
	v_mfma_f32_16x16x32_bf16 v[4:7], v[172:175], v[234:237], v[4:7]
	v_mfma_f32_16x16x32_bf16 v[0:3], v[180:183], v[234:237], v[0:3]
	v_mfma_f32_16x16x32_bf16 v[52:55], v[176:179], v[192:195], v[52:55]
	v_mfma_f32_16x16x32_bf16 v[48:51], v[184:187], v[192:195], v[48:51]
	v_mfma_f32_16x16x32_bf16 v[36:39], v[176:179], v[200:203], v[36:39]
	v_mfma_f32_16x16x32_bf16 v[32:35], v[184:187], v[200:203], v[32:35]
	v_mfma_f32_16x16x32_bf16 v[20:23], v[176:179], v[208:211], v[20:23]
	v_mfma_f32_16x16x32_bf16 v[16:19], v[184:187], v[208:211], v[16:19]
	v_mfma_f32_16x16x32_bf16 v[4:7], v[176:179], v[244:247], v[4:7]
	v_mfma_f32_16x16x32_bf16 v[0:3], v[184:187], v[244:247], v[0:3]
	s_barrier
	s_add_i32 s46, s46, 2
	s_add_u32 s43, s43, 0x100
	s_addc_u32 s45, s45, 0
	s_cmp_gt_u32 s46, 41
	s_mov_b64 s[16:17], s[18:19]
	s_cbranch_scc0 .LBB0_453
	s_and_b64 vcc, exec, s[4:5]
	s_cbranch_vccz .LBB0_456
	s_barrier

; #define PG8_STAGE(bufoff, gbase, voff) do { _Pragma("unroll") for (int _i = 0; _i < 2; ++_i) \
;         __builtin_amdgcn_global_load_lds((const unsigned*)((const char*)(gbase) + (voff)[_i]), (PG8_LAS unsigned*)(lds + (bufoff) + ldsw + _i * 8192), 16, 0, 0); } while (0)
; #define PG8_LDA(dst, b, h) do { _Pragma("unroll") for (int m = 0; m < 4; ++m) _Pragma("unroll") for (int k = 0; k < 2; ++k) dst[m][k] = *(const PG8_LAS bf16x8*)(lds + PG8_SA(b, h) + aoff + m * 2048 + k * 1024); } while (0)
; #define PG8_LDB(dst, b, h) do { _Pragma("unroll") for (int n = 0; n < 2; ++n) _Pragma("unroll") for (int k = 0; k < 2; ++k) dst[n][k] = *(const PG8_LAS bf16x8*)(lds + PG8_SB(b, h) + boff + n * 2048 + k * 1024); } while (0)
; #define PG8_MMA(ai, bj, At, Bt) do { __builtin_amdgcn_s_setprio(1); _Pragma("unroll") for (int m = 0; m < 4; ++m) _Pragma("unroll") for (int n = 0; n < 2; ++n) _Pragma("unroll") for (int k = 0; k < 2; ++k) \
;         acc[ai][bj][m][n] = __builtin_amdgcn_mfma_f32_16x16x32_bf16(Bt[n][k], At[m][k], acc[ai][bj][m][n], 0, 0, 0); __builtin_amdgcn_s_setprio(0); } while (0)
; #define PG8_WAIT_V(n) asm volatile("s_waitcnt vmcnt(" #n ")" ::: "memory")
; #define PG8_WAIT_L(n) asm volatile("s_waitcnt lgkmcnt(" #n ")" ::: "memory")
; #define PG8_BAR __builtin_amdgcn_s_barrier()
; #define PG8_SCHED __builtin_amdgcn_sched_barrier(0)
; template <class Epi, class Sched, bool ALIGN_EPI = false, bool SP2 = false>
; __device__ __forceinline__ void gemm_phase(PG8_LAS unsigned char* lds, const Gemm g, const Sched& S, const Epi& E) {
;     ...
;             const bool last = (t == nt - 2);
;             const char* a1 = cA + (size_t)(t + 1) * kstep;
;             const char* a2 = last ? nA : cA + (size_t)(t + 2) * kstep; const char* b2 = last ? nB : cB + (size_t)(t + 2) * kstep;
;             const char* a3 = a2 + kstep; const char* b3 = b2 + kstep;
;             if (last && has_next) S.a_ready(nxt);
;             if constexpr (SP2) {
;             PG8_LDB(B0, 0, 0); PG8_LDB(B1, 0, 1); PG8_SCHED; PG8_LDA(At, 0, 0); PG8_STAGE(PG8_SA(1, 1), a1 + hstep, voffA);
;             PG8_WAIT_V(8); PG8_WAIT_L(0); PG8_BAR; PG8_MMA(0, 0, At, B0); PG8_MMA(0, 1, At, B1); PG8_BAR; PG8_SCHED;
;             PG8_LDA(At, 0, 1); PG8_STAGE(PG8_SB(0, 0), b2, voffB); PG8_STAGE(PG8_SB(0, 1), b2 + hstep, voffB); PG8_STAGE(PG8_SA(0, 0), a2, voffA);
.LBB0_539:
	s_add_u32 s22, s20, 0xfffc0080
	s_addc_u32 s23, s21, -1
	s_add_i32 s46, 0, 0x10000
	s_cmp_eq_u32 s45, 12
	s_cselect_b32 s25, s13, s23
	s_cselect_b32 s24, s40, s22
	s_cselect_b32 s23, s11, s43
	s_cselect_b32 s22, s41, s42
	s_add_i32 s48, 0, 0x14000
	v_add_u32_e32 v164, s46, v143
	v_add_u32_e32 v180, s48, v143
	ds_read_b128 v[138:141], v164
	ds_read_b128 v[156:159], v164 offset:1024
	ds_read_b128 v[160:163], v164 offset:2048
	ds_read_b128 v[164:167], v164 offset:3072
	ds_read_b128 v[168:171], v180
	ds_read_b128 v[172:175], v180 offset:1024
	ds_read_b128 v[176:179], v180 offset:2048
	ds_read_b128 v[180:183], v180 offset:3072
	v_lshl_add_u64 v[214:215], s[20:21], 0, v[136:137]
	s_add_i32 m0, s30, 0xc000
	ds_read_b128 v[184:187], v155
	ds_read_b128 v[188:191], v155 offset:1024
	ds_read_b128 v[192:195], v155 offset:2048
	ds_read_b128 v[196:199], v155 offset:3072
	ds_read_b128 v[200:203], v155 offset:4096
	ds_read_b128 v[204:207], v155 offset:5120
	ds_read_b128 v[208:211], v155 offset:6144
	ds_read_b128 v[234:237], v155 offset:7168
	global_load_lds_dwordx4 v[214:215], off
	v_lshl_add_u64 v[214:215], s[20:21], 0, v[134:135]
	s_add_i32 m0, s30, 0xe000
	s_nop 0
	global_load_lds_dwordx4 v[214:215], off
	s_waitcnt vmcnt(8)
	s_waitcnt lgkmcnt(0)
	s_barrier
	s_waitcnt lgkmcnt(0)
	v_mfma_f32_16x16x32_bf16 v[124:127], v[138:141], v[184:187], v[124:127]
	v_mfma_f32_16x16x32_bf16 v[120:123], v[160:163], v[184:187], v[120:123]
	v_mfma_f32_16x16x32_bf16 v[108:111], v[138:141], v[192:195], v[108:111]
	v_mfma_f32_16x16x32_bf16 v[104:107], v[160:163], v[192:195], v[104:107]
	v_mfma_f32_16x16x32_bf16 v[92:95], v[138:141], v[200:203], v[92:95]
	v_mfma_f32_16x16x32_bf16 v[88:91], v[160:163], v[200:203], v[88:91]
	v_mfma_f32_16x16x32_bf16 v[76:79], v[138:141], v[208:211], v[76:79]
	v_mfma_f32_16x16x32_bf16 v[72:75], v[160:163], v[208:211], v[72:75]
	v_mfma_f32_16x16x32_bf16 v[124:127], v[156:159], v[188:191], v[124:127]
	v_mfma_f32_16x16x32_bf16 v[120:123], v[164:167], v[188:191], v[120:123]
	v_mfma_f32_16x16x32_bf16 v[108:111], v[156:159], v[196:199], v[108:111]
	v_mfma_f32_16x16x32_bf16 v[104:107], v[164:167], v[196:199], v[104:107]
	v_mfma_f32_16x16x32_bf16 v[92:95], v[156:159], v[204:207], v[92:95]
	v_mfma_f32_16x16x32_bf16 v[88:91], v[164:167], v[204:207], v[88:91]
	v_mfma_f32_16x16x32_bf16 v[76:79], v[156:159], v[234:237], v[76:79]
	v_mfma_f32_16x16x32_bf16 v[72:75], v[164:167], v[234:237], v[72:75]
	v_mfma_f32_16x16x32_bf16 v[116:119], v[168:171], v[184:187], v[116:119]
	v_mfma_f32_16x16x32_bf16 v[112:115], v[176:179], v[184:187], v[112:115]
	v_mfma_f32_16x16x32_bf16 v[100:103], v[168:171], v[192:195], v[100:103]
	v_mfma_f32_16x16x32_bf16 v[96:99], v[176:179], v[192:195], v[96:99]
	v_mfma_f32_16x16x32_bf16 v[84:87], v[168:171], v[200:203], v[84:87]
	v_mfma_f32_16x16x32_bf16 v[80:83], v[176:179], v[200:203], v[80:83]
	v_mfma_f32_16x16x32_bf16 v[68:71], v[168:171], v[208:211], v[68:71]
	v_mfma_f32_16x16x32_bf16 v[64:67], v[176:179], v[208:211], v[64:67]
	v_mfma_f32_16x16x32_bf16 v[116:119], v[172:175], v[188:191], v[116:119]
	v_mfma_f32_16x16x32_bf16 v[112:115], v[180:183], v[188:191], v[112:115]
	v_mfma_f32_16x16x32_bf16 v[100:103], v[172:175], v[196:199], v[100:103]
	v_mfma_f32_16x16x32_bf16 v[96:99], v[180:183], v[196:199], v[96:99]
	v_mfma_f32_16x16x32_bf16 v[84:87], v[172:175], v[204:207], v[84:87]
	v_mfma_f32_16x16x32_bf16 v[80:83], v[180:183], v[204:207], v[80:83]
	v_mfma_f32_16x16x32_bf16 v[68:71], v[172:175], v[234:237], v[68:71]
	v_mfma_f32_16x16x32_bf16 v[64:67], v[180:183], v[234:237], v[64:67]
	s_barrier
	s_add_i32 s46, s46, s29
	v_lshl_add_u64 v[214:215], s[22:23], 0, v[144:145]
	s_mov_b32 m0, s46
	ds_read_b128 v[184:187], v155 offset:16384
	ds_read_b128 v[188:191], v155 offset:17408
	ds_read_b128 v[192:195], v155 offset:18432
	ds_read_b128 v[196:199], v155 offset:19456
	ds_read_b128 v[200:203], v155 offset:20480
	ds_read_b128 v[204:207], v155 offset:21504
	ds_read_b128 v[208:211], v155 offset:22528
	ds_read_b128 v[234:237], v155 offset:23552
	global_load_lds_dwordx4 v[214:215], off
	s_add_i32 m0, s46, 0x2000
	s_add_u32 s46, s22, 0x40000
	v_lshl_add_u64 v[238:239], s[22:23], 0, v[128:129]
	s_addc_u32 s47, s23, 0
	s_add_i32 s48, s48, s29
	global_load_lds_dwordx4 v[238:239], off
	v_lshl_add_u64 v[244:245], s[46:47], 0, v[144:145]
	s_mov_b32 m0, s48
	v_lshl_add_u64 v[246:247], s[24:25], 0, v[130:131]
	global_load_lds_dwordx4 v[244:245], off
	v_lshl_add_u64 v[244:245], s[46:47], 0, v[128:129]
	s_add_i32 m0, s48, 0x2000
	s_nop 0
	global_load_lds_dwordx4 v[244:245], off
	v_lshl_add_u64 v[244:245], s[24:25], 0, v[132:133]
	s_mov_b32 m0, s30
	s_nop 0
	global_load_lds_dwordx4 v[244:245], off
	s_mov_b32 m0, s31
	s_nop 0
	global_load_lds_dwordx4 v[246:247], off
	s_waitcnt vmcnt(8)
	s_waitcnt lgkmcnt(0)
	s_barrier
; #define PG8_STAGE(bufoff, gbase, voff) do { _Pragma("unroll") for (int _i = 0; _i < 2; ++_i) \
;         __builtin_amdgcn_global_load_lds((const unsigned*)((const char*)(gbase) + (voff)[_i]), (PG8_LAS unsigned*)(lds + (bufoff) + ldsw + _i * 8192), 16, 0, 0); } while (0)
; #define PG8_LDA(dst, b, h) do { _Pragma("unroll") for (int m = 0; m < 4; ++m) _Pragma("unroll") for (int k = 0; k < 2; ++k) dst[m][k] = *(const PG8_LAS bf16x8*)(lds + PG8_SA(b, h) + aoff + m * 2048 + k * 1024); } while (0)
; #define PG8_LDB(dst, b, h) do { _Pragma("unroll") for (int n = 0; n < 2; ++n) _Pragma("unroll") for (int k = 0; k < 2; ++k) dst[n][k] = *(const PG8_LAS bf16x8*)(lds + PG8_SB(b, h) + boff + n * 2048 + k * 1024); } while (0)
; #define PG8_MMA(ai, bj, At, Bt) do { __builtin_amdgcn_s_setprio(1); _Pragma("unroll") for (int m = 0; m < 4; ++m) _Pragma("unroll") for (int n = 0; n < 2; ++n) _Pragma("unroll") for (int k = 0; k < 2; ++k) \
;         acc[ai][bj][m][n] = __builtin_amdgcn_mfma_f32_16x16x32_bf16(Bt[n][k], At[m][k], acc[ai][bj][m][n], 0, 0, 0); __builtin_amdgcn_s_setprio(0); } while (0)
; #define PG8_WAIT_V(n) asm volatile("s_waitcnt vmcnt(" #n ")" ::: "memory")
; #define PG8_WAIT_L(n) asm volatile("s_waitcnt lgkmcnt(" #n ")" ::: "memory")
; #define PG8_BAR __builtin_amdgcn_s_barrier()
; #define PG8_SCHED __builtin_amdgcn_sched_barrier(0)
; template <class Epi, class Sched, bool ALIGN_EPI = false, bool SP2 = false>
; __device__ __forceinline__ void gemm_phase(PG8_LAS unsigned char* lds, const Gemm g, const Sched& S, const Epi& E) {
;     ...
;             PG8_WAIT_V(8); PG8_WAIT_L(0); PG8_BAR; PG8_MMA(1, 0, At, B0); PG8_MMA(1, 1, At, B1); PG8_BAR; PG8_SCHED;
;             PG8_LDB(B0, 1, 0); PG8_LDB(B1, 1, 1); PG8_SCHED; PG8_LDA(At, 1, 0); PG8_STAGE(PG8_SA(0, 1), a2 + hstep, voffA);
;             PG8_WAIT_V(8); PG8_WAIT_L(0); PG8_BAR; PG8_MMA(0, 0, At, B0); PG8_MMA(0, 1, At, B1); PG8_BAR; PG8_SCHED;
	s_waitcnt lgkmcnt(0)
	v_mfma_f32_16x16x32_bf16 v[60:63], v[138:141], v[184:187], v[60:63]
	v_mfma_f32_16x16x32_bf16 v[56:59], v[160:163], v[184:187], v[56:59]
	v_mfma_f32_16x16x32_bf16 v[44:47], v[138:141], v[192:195], v[44:47]
	v_mfma_f32_16x16x32_bf16 v[40:43], v[160:163], v[192:195], v[40:43]
	v_mfma_f32_16x16x32_bf16 v[28:31], v[138:141], v[200:203], v[28:31]
	v_mfma_f32_16x16x32_bf16 v[24:27], v[160:163], v[200:203], v[24:27]
	v_mfma_f32_16x16x32_bf16 v[12:15], v[138:141], v[208:211], v[12:15]
	v_mfma_f32_16x16x32_bf16 v[8:11], v[160:163], v[208:211], v[8:11]
	v_mfma_f32_16x16x32_bf16 v[60:63], v[156:159], v[188:191], v[60:63]
	v_mfma_f32_16x16x32_bf16 v[56:59], v[164:167], v[188:191], v[56:59]
	v_mfma_f32_16x16x32_bf16 v[44:47], v[156:159], v[196:199], v[44:47]
	v_mfma_f32_16x16x32_bf16 v[40:43], v[164:167], v[196:199], v[40:43]
	v_mfma_f32_16x16x32_bf16 v[28:31], v[156:159], v[204:207], v[28:31]
	v_mfma_f32_16x16x32_bf16 v[24:27], v[164:167], v[204:207], v[24:27]
	v_mfma_f32_16x16x32_bf16 v[12:15], v[156:159], v[234:237], v[12:15]
	v_mfma_f32_16x16x32_bf16 v[8:11], v[164:167], v[234:237], v[8:11]
	v_mfma_f32_16x16x32_bf16 v[52:55], v[168:171], v[184:187], v[52:55]
	v_mfma_f32_16x16x32_bf16 v[48:51], v[176:179], v[184:187], v[48:51]
	v_mfma_f32_16x16x32_bf16 v[36:39], v[168:171], v[192:195], v[36:39]
	v_mfma_f32_16x16x32_bf16 v[32:35], v[176:179], v[192:195], v[32:35]
	v_mfma_f32_16x16x32_bf16 v[20:23], v[168:171], v[200:203], v[20:23]
	v_mfma_f32_16x16x32_bf16 v[16:19], v[176:179], v[200:203], v[16:19]
	v_mfma_f32_16x16x32_bf16 v[4:7], v[168:171], v[208:211], v[4:7]
	v_mfma_f32_16x16x32_bf16 v[0:3], v[176:179], v[208:211], v[0:3]
	v_mfma_f32_16x16x32_bf16 v[52:55], v[172:175], v[188:191], v[52:55]
	v_mfma_f32_16x16x32_bf16 v[48:51], v[180:183], v[188:191], v[48:51]
	v_mfma_f32_16x16x32_bf16 v[36:39], v[172:175], v[196:199], v[36:39]
	v_mfma_f32_16x16x32_bf16 v[32:35], v[180:183], v[196:199], v[32:35]
	v_mfma_f32_16x16x32_bf16 v[20:23], v[172:175], v[204:207], v[20:23]
	v_mfma_f32_16x16x32_bf16 v[16:19], v[180:183], v[204:207], v[16:19]
	v_mfma_f32_16x16x32_bf16 v[4:7], v[172:175], v[234:237], v[4:7]
	v_mfma_f32_16x16x32_bf16 v[0:3], v[180:183], v[234:237], v[0:3]
	s_barrier
	s_add_i32 s46, 0, 0x18000
	s_add_i32 s47, 0, 0x1c000
	v_add_u32_e32 v164, s46, v143
	v_add_u32_e32 v180, s47, v143
	ds_read_b128 v[138:141], v164
	ds_read_b128 v[156:159], v164 offset:1024
	ds_read_b128 v[160:163], v164 offset:2048
	ds_read_b128 v[164:167], v164 offset:3072
	ds_read_b128 v[168:171], v180
	ds_read_b128 v[172:175], v180 offset:1024
	ds_read_b128 v[176:179], v180 offset:2048
	ds_read_b128 v[180:183], v180 offset:3072
	s_add_u32 s24, s24, 0x40000
	s_addc_u32 s25, s25, 0
	s_mov_b32 m0, s34
	v_lshl_add_u64 v[248:249], s[24:25], 0, v[132:133]
	ds_read_b128 v[184:187], v155 offset:32768
	ds_read_b128 v[188:191], v155 offset:33792
	ds_read_b128 v[192:195], v155 offset:34816
	ds_read_b128 v[196:199], v155 offset:35840
	ds_read_b128 v[200:203], v155 offset:36864
	ds_read_b128 v[204:207], v155 offset:37888
	ds_read_b128 v[208:211], v155 offset:38912
	ds_read_b128 v[234:237], v155 offset:39936
	global_load_lds_dwordx4 v[248:249], off
	v_lshl_add_u64 v[248:249], s[24:25], 0, v[130:131]
	s_mov_b32 m0, s35
	s_nop 0
	global_load_lds_dwordx4 v[248:249], off
	s_waitcnt vmcnt(8)
	s_waitcnt lgkmcnt(0)
	s_barrier
	s_waitcnt lgkmcnt(0)
	v_mfma_f32_16x16x32_bf16 v[124:127], v[138:141], v[184:187], v[124:127]
	v_mfma_f32_16x16x32_bf16 v[120:123], v[160:163], v[184:187], v[120:123]
	v_mfma_f32_16x16x32_bf16 v[108:111], v[138:141], v[192:195], v[108:111]
	v_mfma_f32_16x16x32_bf16 v[104:107], v[160:163], v[192:195], v[104:107]
	v_mfma_f32_16x16x32_bf16 v[92:95], v[138:141], v[200:203], v[92:95]
	v_mfma_f32_16x16x32_bf16 v[88:91], v[160:163], v[200:203], v[88:91]
	v_mfma_f32_16x16x32_bf16 v[76:79], v[138:141], v[208:211], v[76:79]
	v_mfma_f32_16x16x32_bf16 v[72:75], v[160:163], v[208:211], v[72:75]
	v_mfma_f32_16x16x32_bf16 v[124:127], v[156:159], v[188:191], v[124:127]
	v_mfma_f32_16x16x32_bf16 v[120:123], v[164:167], v[188:191], v[120:123]
	v_mfma_f32_16x16x32_bf16 v[108:111], v[156:159], v[196:199], v[108:111]
	v_mfma_f32_16x16x32_bf16 v[104:107], v[164:167], v[196:199], v[104:107]
	v_mfma_f32_16x16x32_bf16 v[92:95], v[156:159], v[204:207], v[92:95]
	v_mfma_f32_16x16x32_bf16 v[88:91], v[164:167], v[204:207], v[88:91]
	v_mfma_f32_16x16x32_bf16 v[76:79], v[156:159], v[234:237], v[76:79]
	v_mfma_f32_16x16x32_bf16 v[72:75], v[164:167], v[234:237], v[72:75]
	v_mfma_f32_16x16x32_bf16 v[116:119], v[168:171], v[184:187], v[116:119]
	v_mfma_f32_16x16x32_bf16 v[112:115], v[176:179], v[184:187], v[112:115]
	v_mfma_f32_16x16x32_bf16 v[100:103], v[168:171], v[192:195], v[100:103]
	v_mfma_f32_16x16x32_bf16 v[96:99], v[176:179], v[192:195], v[96:99]
	v_mfma_f32_16x16x32_bf16 v[84:87], v[168:171], v[200:203], v[84:87]
	v_mfma_f32_16x16x32_bf16 v[80:83], v[176:179], v[200:203], v[80:83]
	v_mfma_f32_16x16x32_bf16 v[68:71], v[168:171], v[208:211], v[68:71]
	v_mfma_f32_16x16x32_bf16 v[64:67], v[176:179], v[208:211], v[64:67]
	v_mfma_f32_16x16x32_bf16 v[116:119], v[172:175], v[188:191], v[116:119]
	v_mfma_f32_16x16x32_bf16 v[112:115], v[180:183], v[188:191], v[112:115]
	v_mfma_f32_16x16x32_bf16 v[100:103], v[172:175], v[196:199], v[100:103]
	v_mfma_f32_16x16x32_bf16 v[96:99], v[180:183], v[196:199], v[96:99]
	v_mfma_f32_16x16x32_bf16 v[84:87], v[172:175], v[204:207], v[84:87]
	v_mfma_f32_16x16x32_bf16 v[80:83], v[180:183], v[204:207], v[80:83]
	v_mfma_f32_16x16x32_bf16 v[68:71], v[172:175], v[234:237], v[68:71]
	v_mfma_f32_16x16x32_bf16 v[64:67], v[180:183], v[234:237], v[64:67]
	s_barrier
; #define PG8_STAGE(bufoff, gbase, voff) do { _Pragma("unroll") for (int _i = 0; _i < 2; ++_i) \
;         __builtin_amdgcn_global_load_lds((const unsigned*)((const char*)(gbase) + (voff)[_i]), (PG8_LAS unsigned*)(lds + (bufoff) + ldsw + _i * 8192), 16, 0, 0); } while (0)
; #define PG8_LDA(dst, b, h) do { _Pragma("unroll") for (int m = 0; m < 4; ++m) _Pragma("unroll") for (int k = 0; k < 2; ++k) dst[m][k] = *(const PG8_LAS bf16x8*)(lds + PG8_SA(b, h) + aoff + m * 2048 + k * 1024); } while (0)
; #define PG8_MMA(ai, bj, At, Bt) do { __builtin_amdgcn_s_setprio(1); _Pragma("unroll") for (int m = 0; m < 4; ++m) _Pragma("unroll") for (int n = 0; n < 2; ++n) _Pragma("unroll") for (int k = 0; k < 2; ++k) \
;         acc[ai][bj][m][n] = __builtin_amdgcn_mfma_f32_16x16x32_bf16(Bt[n][k], At[m][k], acc[ai][bj][m][n], 0, 0, 0); __builtin_amdgcn_s_setprio(0); } while (0)
; #define PG8_WAIT_V(n) asm volatile("s_waitcnt vmcnt(" #n ")" ::: "memory")
; #define PG8_WAIT_L(n) asm volatile("s_waitcnt lgkmcnt(" #n ")" ::: "memory")
; #define PG8_BAR __builtin_amdgcn_s_barrier()
; #define PG8_SCHED __builtin_amdgcn_sched_barrier(0)
; template <class Epi, class Sched, bool ALIGN_EPI = false, bool SP2 = false>
; __device__ __forceinline__ void gemm_phase(PG8_LAS unsigned char* lds, const Gemm g, const Sched& S, const Epi& E) {
;     ...
;             PG8_LDA(At, 1, 1); PG8_STAGE(PG8_SB(1, 0), b3, voffB); PG8_STAGE(PG8_SB(1, 1), b3 + hstep, voffB); PG8_STAGE(PG8_SA(1, 0), a3, voffA);
;             PG8_WAIT_V(8); PG8_WAIT_L(0); PG8_BAR; PG8_MMA(1, 0, At, B0); PG8_MMA(1, 1, At, B1); PG8_BAR; PG8_SCHED;
;     ...
;         if constexpr (ALIGN_EPI) { if (wr == 0) PG8_BAR; }
	s_add_i32 s24, s46, s29
	v_lshl_add_u64 v[214:215], v[214:215], 0, s[50:51]
	s_mov_b32 m0, s24
	ds_read_b128 v[184:187], v155 offset:49152
	ds_read_b128 v[188:191], v155 offset:50176
	ds_read_b128 v[192:195], v155 offset:51200
	ds_read_b128 v[196:199], v155 offset:52224
	ds_read_b128 v[200:203], v155 offset:53248
	ds_read_b128 v[204:207], v155 offset:54272
	ds_read_b128 v[208:211], v155 offset:55296
	ds_read_b128 v[234:237], v155 offset:56320
	global_load_lds_dwordx4 v[214:215], off
	s_add_i32 m0, s24, 0x2000
	s_add_u32 s22, s22, 0x40080
	v_lshl_add_u64 v[214:215], v[238:239], 0, s[50:51]
	s_addc_u32 s23, s23, 0
	s_add_i32 s24, s47, s29
	global_load_lds_dwordx4 v[214:215], off
	v_lshl_add_u64 v[214:215], s[22:23], 0, v[144:145]
	s_mov_b32 m0, s24
	s_nop 0
	global_load_lds_dwordx4 v[214:215], off
	v_lshl_add_u64 v[214:215], s[22:23], 0, v[128:129]
	s_add_i32 m0, s24, 0x2000
	s_nop 0
	global_load_lds_dwordx4 v[214:215], off
	v_lshl_add_u64 v[214:215], v[244:245], 0, s[50:51]
	s_mov_b32 m0, s33
	s_nop 0
	global_load_lds_dwordx4 v[214:215], off
	v_lshl_add_u64 v[214:215], v[246:247], 0, s[50:51]
	s_mov_b32 m0, s36
	s_nop 0
	global_load_lds_dwordx4 v[214:215], off
	s_waitcnt vmcnt(8)
	s_waitcnt lgkmcnt(0)
	s_barrier
	s_waitcnt lgkmcnt(0)
	v_mfma_f32_16x16x32_bf16 v[60:63], v[138:141], v[184:187], v[60:63]
	v_mfma_f32_16x16x32_bf16 v[56:59], v[160:163], v[184:187], v[56:59]
	v_mfma_f32_16x16x32_bf16 v[44:47], v[138:141], v[192:195], v[44:47]
	v_mfma_f32_16x16x32_bf16 v[40:43], v[160:163], v[192:195], v[40:43]
	v_mfma_f32_16x16x32_bf16 v[28:31], v[138:141], v[200:203], v[28:31]
	v_mfma_f32_16x16x32_bf16 v[24:27], v[160:163], v[200:203], v[24:27]
	v_mfma_f32_16x16x32_bf16 v[12:15], v[138:141], v[208:211], v[12:15]
	v_mfma_f32_16x16x32_bf16 v[8:11], v[160:163], v[208:211], v[8:11]
	v_mfma_f32_16x16x32_bf16 v[60:63], v[156:159], v[188:191], v[60:63]
	v_mfma_f32_16x16x32_bf16 v[56:59], v[164:167], v[188:191], v[56:59]
	v_mfma_f32_16x16x32_bf16 v[44:47], v[156:159], v[196:199], v[44:47]
	v_mfma_f32_16x16x32_bf16 v[40:43], v[164:167], v[196:199], v[40:43]
	v_mfma_f32_16x16x32_bf16 v[28:31], v[156:159], v[204:207], v[28:31]
	v_mfma_f32_16x16x32_bf16 v[24:27], v[164:167], v[204:207], v[24:27]
	v_mfma_f32_16x16x32_bf16 v[12:15], v[156:159], v[234:237], v[12:15]
	v_mfma_f32_16x16x32_bf16 v[8:11], v[164:167], v[234:237], v[8:11]
	v_mfma_f32_16x16x32_bf16 v[52:55], v[168:171], v[184:187], v[52:55]
	v_mfma_f32_16x16x32_bf16 v[48:51], v[176:179], v[184:187], v[48:51]
	v_mfma_f32_16x16x32_bf16 v[36:39], v[168:171], v[192:195], v[36:39]
	v_mfma_f32_16x16x32_bf16 v[32:35], v[176:179], v[192:195], v[32:35]
	v_mfma_f32_16x16x32_bf16 v[20:23], v[168:171], v[200:203], v[20:23]
	v_mfma_f32_16x16x32_bf16 v[16:19], v[176:179], v[200:203], v[16:19]
	v_mfma_f32_16x16x32_bf16 v[4:7], v[168:171], v[208:211], v[4:7]
	v_mfma_f32_16x16x32_bf16 v[0:3], v[176:179], v[208:211], v[0:3]
	v_mfma_f32_16x16x32_bf16 v[52:55], v[172:175], v[188:191], v[52:55]
	v_mfma_f32_16x16x32_bf16 v[48:51], v[180:183], v[188:191], v[48:51]
	v_mfma_f32_16x16x32_bf16 v[36:39], v[172:175], v[196:199], v[36:39]
	v_mfma_f32_16x16x32_bf16 v[32:35], v[180:183], v[196:199], v[32:35]
	v_mfma_f32_16x16x32_bf16 v[20:23], v[172:175], v[204:207], v[20:23]
	v_mfma_f32_16x16x32_bf16 v[16:19], v[180:183], v[204:207], v[16:19]
	v_mfma_f32_16x16x32_bf16 v[4:7], v[172:175], v[234:237], v[4:7]
	v_mfma_f32_16x16x32_bf16 v[0:3], v[180:183], v[234:237], v[0:3]
	s_barrier
	s_add_i32 s45, s45, 2
	s_add_u32 s42, s42, 0x100
	s_addc_u32 s43, s43, 0
	s_add_u32 s20, s20, 0x100
	s_addc_u32 s21, s21, 0
	s_cmp_gt_u32 s45, 13
	s_cbranch_scc0 .LBB0_539
	s_and_b64 vcc, exec, s[6:7]
	s_cbranch_vccz .LBB0_542
	s_barrier

; #define PG8_STAGE(bufoff, gbase, voff) do { _Pragma("unroll") for (int _i = 0; _i < 2; ++_i) \
;         __builtin_amdgcn_global_load_lds((const unsigned*)((const char*)(gbase) + (voff)[_i]), (PG8_LAS unsigned*)(lds + (bufoff) + ldsw + _i * 8192), 16, 0, 0); } while (0)
; #define PG8_LDA(dst, b, h) do { _Pragma("unroll") for (int m = 0; m < 4; ++m) _Pragma("unroll") for (int k = 0; k < 2; ++k) dst[m][k] = *(const PG8_LAS bf16x8*)(lds + PG8_SA(b, h) + aoff + m * 2048 + k * 1024); } while (0)
; #define PG8_LDB(dst, b, h) do { _Pragma("unroll") for (int n = 0; n < 2; ++n) _Pragma("unroll") for (int k = 0; k < 2; ++k) dst[n][k] = *(const PG8_LAS bf16x8*)(lds + PG8_SB(b, h) + boff + n * 2048 + k * 1024); } while (0)
; #define PG8_MMA(ai, bj, At, Bt) do { __builtin_amdgcn_s_setprio(1); _Pragma("unroll") for (int m = 0; m < 4; ++m) _Pragma("unroll") for (int n = 0; n < 2; ++n) _Pragma("unroll") for (int k = 0; k < 2; ++k) \
;         acc[ai][bj][m][n] = __builtin_amdgcn_mfma_f32_16x16x32_bf16(Bt[n][k], At[m][k], acc[ai][bj][m][n], 0, 0, 0); __builtin_amdgcn_s_setprio(0); } while (0)
; #define PG8_WAIT_V(n) asm volatile("s_waitcnt vmcnt(" #n ")" ::: "memory")
; #define PG8_WAIT_L(n) asm volatile("s_waitcnt lgkmcnt(" #n ")" ::: "memory")
; #define PG8_BAR __builtin_amdgcn_s_barrier()
; #define PG8_SCHED __builtin_amdgcn_sched_barrier(0)
; template <class Epi, class Sched, bool ALIGN_EPI = false, bool SP2 = false>
; __device__ __forceinline__ void gemm_phase(PG8_LAS unsigned char* lds, const Gemm g, const Sched& S, const Epi& E) {
;     ...
;             const bool last = (t == nt - 2);
;             const char* a1 = cA + (size_t)(t + 1) * kstep;
;             const char* a2 = last ? nA : cA + (size_t)(t + 2) * kstep; const char* b2 = last ? nB : cB + (size_t)(t + 2) * kstep;
;             const char* a3 = a2 + kstep; const char* b3 = b2 + kstep;
;             if (last && has_next) S.a_ready(nxt);
;             if constexpr (SP2) {
;             PG8_LDB(B0, 0, 0); PG8_LDB(B1, 0, 1); PG8_SCHED; PG8_LDA(At, 0, 0); PG8_STAGE(PG8_SA(1, 1), a1 + hstep, voffA);
;             PG8_WAIT_V(8); PG8_WAIT_L(0); PG8_BAR; PG8_MMA(0, 0, At, B0); PG8_MMA(0, 1, At, B1); PG8_BAR; PG8_SCHED;
;             PG8_LDA(At, 0, 1); PG8_STAGE(PG8_SB(0, 0), b2, voffB); PG8_STAGE(PG8_SB(0, 1), b2 + hstep, voffB); PG8_STAGE(PG8_SA(0, 0), a2, voffA);
.LBB0_1133:
	s_add_i32 s42, s38, 2
	s_add_u32 s39, s16, 0xfffc0080
	s_addc_u32 s40, s17, -1
	s_add_i32 s43, 0, 0x10000
	s_cmp_eq_u32 s19, s38
	s_cselect_b32 s41, s29, s40
	s_cselect_b32 s40, s28, s39
	s_cselect_b32 s39, s27, s31
	s_cselect_b32 s38, s26, s21
	s_add_i32 s61, 0, 0x14000
	v_add_u32_e32 v140, s43, v234
	v_add_u32_e32 v178, s61, v234
	s_waitcnt lgkmcnt(0)
	ds_read_b128 v[128:131], v140
	ds_read_b128 v[132:135], v140 offset:1024
	ds_read_b128 v[136:139], v140 offset:2048
	ds_read_b128 v[140:143], v140 offset:3072
	ds_read_b128 v[166:169], v178
	ds_read_b128 v[170:173], v178 offset:1024
	ds_read_b128 v[174:177], v178 offset:2048
	ds_read_b128 v[178:181], v178 offset:3072
	v_lshl_add_u64 v[210:211], s[16:17], 0, v[164:165]
	s_add_i32 m0, s49, 0xc000
	ds_read_b128 v[182:185], v236
	ds_read_b128 v[186:189], v236 offset:1024
	ds_read_b128 v[190:193], v236 offset:2048
	ds_read_b128 v[194:197], v236 offset:3072
	ds_read_b128 v[198:201], v236 offset:4096
	ds_read_b128 v[202:205], v236 offset:5120
	ds_read_b128 v[206:209], v236 offset:6144
	ds_read_b128 v[244:247], v236 offset:7168
	global_load_lds_dwordx4 v[210:211], off
	v_lshl_add_u64 v[210:211], s[16:17], 0, v[162:163]
	s_add_i32 m0, s49, 0xe000
	s_nop 0
	global_load_lds_dwordx4 v[210:211], off
	s_waitcnt vmcnt(8)
	s_waitcnt lgkmcnt(0)
	s_barrier
	s_waitcnt lgkmcnt(0)
	v_mfma_f32_16x16x32_bf16 v[124:127], v[128:131], v[182:185], v[124:127]
	v_mfma_f32_16x16x32_bf16 v[120:123], v[136:139], v[182:185], v[120:123]
	v_mfma_f32_16x16x32_bf16 v[116:119], v[128:131], v[190:193], v[116:119]
	v_mfma_f32_16x16x32_bf16 v[112:115], v[136:139], v[190:193], v[112:115]
	v_mfma_f32_16x16x32_bf16 v[108:111], v[128:131], v[198:201], v[108:111]
	v_mfma_f32_16x16x32_bf16 v[104:107], v[136:139], v[198:201], v[104:107]
	v_mfma_f32_16x16x32_bf16 v[100:103], v[128:131], v[206:209], v[100:103]
	v_mfma_f32_16x16x32_bf16 v[96:99], v[136:139], v[206:209], v[96:99]
	v_mfma_f32_16x16x32_bf16 v[124:127], v[132:135], v[186:189], v[124:127]
	v_mfma_f32_16x16x32_bf16 v[120:123], v[140:143], v[186:189], v[120:123]
	v_mfma_f32_16x16x32_bf16 v[116:119], v[132:135], v[194:197], v[116:119]
	v_mfma_f32_16x16x32_bf16 v[112:115], v[140:143], v[194:197], v[112:115]
	v_mfma_f32_16x16x32_bf16 v[108:111], v[132:135], v[202:205], v[108:111]
	v_mfma_f32_16x16x32_bf16 v[104:107], v[140:143], v[202:205], v[104:107]
	v_mfma_f32_16x16x32_bf16 v[100:103], v[132:135], v[244:247], v[100:103]
	v_mfma_f32_16x16x32_bf16 v[96:99], v[140:143], v[244:247], v[96:99]
	v_mfma_f32_16x16x32_bf16 v[92:95], v[166:169], v[182:185], v[92:95]
	v_mfma_f32_16x16x32_bf16 v[88:91], v[174:177], v[182:185], v[88:91]
	v_mfma_f32_16x16x32_bf16 v[84:87], v[166:169], v[190:193], v[84:87]
	v_mfma_f32_16x16x32_bf16 v[80:83], v[174:177], v[190:193], v[80:83]
	v_mfma_f32_16x16x32_bf16 v[76:79], v[166:169], v[198:201], v[76:79]
	v_mfma_f32_16x16x32_bf16 v[72:75], v[174:177], v[198:201], v[72:75]
	v_mfma_f32_16x16x32_bf16 v[68:71], v[166:169], v[206:209], v[68:71]
	v_mfma_f32_16x16x32_bf16 v[64:67], v[174:177], v[206:209], v[64:67]
	v_mfma_f32_16x16x32_bf16 v[92:95], v[170:173], v[186:189], v[92:95]
	v_mfma_f32_16x16x32_bf16 v[88:91], v[178:181], v[186:189], v[88:91]
	v_mfma_f32_16x16x32_bf16 v[84:87], v[170:173], v[194:197], v[84:87]
	v_mfma_f32_16x16x32_bf16 v[80:83], v[178:181], v[194:197], v[80:83]
	v_mfma_f32_16x16x32_bf16 v[76:79], v[170:173], v[202:205], v[76:79]
	v_mfma_f32_16x16x32_bf16 v[72:75], v[178:181], v[202:205], v[72:75]
	v_mfma_f32_16x16x32_bf16 v[68:71], v[170:173], v[244:247], v[68:71]
	v_mfma_f32_16x16x32_bf16 v[64:67], v[178:181], v[244:247], v[64:67]
	s_barrier
	s_add_i32 s43, s43, s48
	v_lshl_add_u64 v[210:211], s[38:39], 0, v[144:145]
	s_mov_b32 m0, s43
	ds_read_b128 v[182:185], v236 offset:16384
	ds_read_b128 v[186:189], v236 offset:17408
	ds_read_b128 v[190:193], v236 offset:18432
	ds_read_b128 v[194:197], v236 offset:19456
	ds_read_b128 v[198:201], v236 offset:20480
	ds_read_b128 v[202:205], v236 offset:21504
	ds_read_b128 v[206:209], v236 offset:22528
	ds_read_b128 v[244:247], v236 offset:23552
	global_load_lds_dwordx4 v[210:211], off
	s_add_i32 m0, s43, 0x2000
	s_add_u32 s62, s38, 0x40000
	v_lshl_add_u64 v[214:215], s[38:39], 0, v[158:159]
	s_addc_u32 s63, s39, 0
	s_add_i32 s43, s61, s48
	global_load_lds_dwordx4 v[214:215], off
	v_lshl_add_u64 v[248:249], s[62:63], 0, v[144:145]
	s_mov_b32 m0, s43
	v_lshl_add_u64 v[250:251], s[40:41], 0, v[156:157]
	global_load_lds_dwordx4 v[248:249], off
	v_lshl_add_u64 v[248:249], s[62:63], 0, v[158:159]
	s_add_i32 m0, s43, 0x2000
	s_nop 0
	global_load_lds_dwordx4 v[248:249], off
	v_lshl_add_u64 v[248:249], s[40:41], 0, v[154:155]
	s_mov_b32 m0, s49
	s_nop 0
	global_load_lds_dwordx4 v[248:249], off
	s_mov_b32 m0, s50
	s_nop 0
	global_load_lds_dwordx4 v[250:251], off
	s_waitcnt vmcnt(8)
	s_waitcnt lgkmcnt(0)
	s_barrier
; #define PG8_STAGE(bufoff, gbase, voff) do { _Pragma("unroll") for (int _i = 0; _i < 2; ++_i) \
;         __builtin_amdgcn_global_load_lds((const unsigned*)((const char*)(gbase) + (voff)[_i]), (PG8_LAS unsigned*)(lds + (bufoff) + ldsw + _i * 8192), 16, 0, 0); } while (0)
; #define PG8_LDA(dst, b, h) do { _Pragma("unroll") for (int m = 0; m < 4; ++m) _Pragma("unroll") for (int k = 0; k < 2; ++k) dst[m][k] = *(const PG8_LAS bf16x8*)(lds + PG8_SA(b, h) + aoff + m * 2048 + k * 1024); } while (0)
; #define PG8_LDB(dst, b, h) do { _Pragma("unroll") for (int n = 0; n < 2; ++n) _Pragma("unroll") for (int k = 0; k < 2; ++k) dst[n][k] = *(const PG8_LAS bf16x8*)(lds + PG8_SB(b, h) + boff + n * 2048 + k * 1024); } while (0)
; #define PG8_MMA(ai, bj, At, Bt) do { __builtin_amdgcn_s_setprio(1); _Pragma("unroll") for (int m = 0; m < 4; ++m) _Pragma("unroll") for (int n = 0; n < 2; ++n) _Pragma("unroll") for (int k = 0; k < 2; ++k) \
;         acc[ai][bj][m][n] = __builtin_amdgcn_mfma_f32_16x16x32_bf16(Bt[n][k], At[m][k], acc[ai][bj][m][n], 0, 0, 0); __builtin_amdgcn_s_setprio(0); } while (0)
; #define PG8_WAIT_V(n) asm volatile("s_waitcnt vmcnt(" #n ")" ::: "memory")
; #define PG8_WAIT_L(n) asm volatile("s_waitcnt lgkmcnt(" #n ")" ::: "memory")
; #define PG8_BAR __builtin_amdgcn_s_barrier()
; #define PG8_SCHED __builtin_amdgcn_sched_barrier(0)
; template <class Epi, class Sched, bool ALIGN_EPI = false, bool SP2 = false>
; __device__ __forceinline__ void gemm_phase(PG8_LAS unsigned char* lds, const Gemm g, const Sched& S, const Epi& E) {
;     ...
;             PG8_WAIT_V(8); PG8_WAIT_L(0); PG8_BAR; PG8_MMA(1, 0, At, B0); PG8_MMA(1, 1, At, B1); PG8_BAR; PG8_SCHED;
;             PG8_LDB(B0, 1, 0); PG8_LDB(B1, 1, 1); PG8_SCHED; PG8_LDA(At, 1, 0); PG8_STAGE(PG8_SA(0, 1), a2 + hstep, voffA);
;             PG8_WAIT_V(8); PG8_WAIT_L(0); PG8_BAR; PG8_MMA(0, 0, At, B0); PG8_MMA(0, 1, At, B1); PG8_BAR; PG8_SCHED;
	s_waitcnt lgkmcnt(0)
	v_mfma_f32_16x16x32_bf16 v[60:63], v[128:131], v[182:185], v[60:63]
	v_mfma_f32_16x16x32_bf16 v[56:59], v[136:139], v[182:185], v[56:59]
	v_mfma_f32_16x16x32_bf16 v[52:55], v[128:131], v[190:193], v[52:55]
	v_mfma_f32_16x16x32_bf16 v[48:51], v[136:139], v[190:193], v[48:51]
	v_mfma_f32_16x16x32_bf16 v[44:47], v[128:131], v[198:201], v[44:47]
	v_mfma_f32_16x16x32_bf16 v[40:43], v[136:139], v[198:201], v[40:43]
	v_mfma_f32_16x16x32_bf16 v[36:39], v[128:131], v[206:209], v[36:39]
	v_mfma_f32_16x16x32_bf16 v[32:35], v[136:139], v[206:209], v[32:35]
	v_mfma_f32_16x16x32_bf16 v[60:63], v[132:135], v[186:189], v[60:63]
	v_mfma_f32_16x16x32_bf16 v[56:59], v[140:143], v[186:189], v[56:59]
	v_mfma_f32_16x16x32_bf16 v[52:55], v[132:135], v[194:197], v[52:55]
	v_mfma_f32_16x16x32_bf16 v[48:51], v[140:143], v[194:197], v[48:51]
	v_mfma_f32_16x16x32_bf16 v[44:47], v[132:135], v[202:205], v[44:47]
	v_mfma_f32_16x16x32_bf16 v[40:43], v[140:143], v[202:205], v[40:43]
	v_mfma_f32_16x16x32_bf16 v[36:39], v[132:135], v[244:247], v[36:39]
	v_mfma_f32_16x16x32_bf16 v[32:35], v[140:143], v[244:247], v[32:35]
	v_mfma_f32_16x16x32_bf16 v[28:31], v[166:169], v[182:185], v[28:31]
	v_mfma_f32_16x16x32_bf16 v[24:27], v[174:177], v[182:185], v[24:27]
	v_mfma_f32_16x16x32_bf16 v[20:23], v[166:169], v[190:193], v[20:23]
	v_mfma_f32_16x16x32_bf16 v[16:19], v[174:177], v[190:193], v[16:19]
	v_mfma_f32_16x16x32_bf16 v[12:15], v[166:169], v[198:201], v[12:15]
	v_mfma_f32_16x16x32_bf16 v[8:11], v[174:177], v[198:201], v[8:11]
	v_mfma_f32_16x16x32_bf16 v[4:7], v[166:169], v[206:209], v[4:7]
	v_mfma_f32_16x16x32_bf16 v[0:3], v[174:177], v[206:209], v[0:3]
	v_mfma_f32_16x16x32_bf16 v[28:31], v[170:173], v[186:189], v[28:31]
	v_mfma_f32_16x16x32_bf16 v[24:27], v[178:181], v[186:189], v[24:27]
	v_mfma_f32_16x16x32_bf16 v[20:23], v[170:173], v[194:197], v[20:23]
	v_mfma_f32_16x16x32_bf16 v[16:19], v[178:181], v[194:197], v[16:19]
	v_mfma_f32_16x16x32_bf16 v[12:15], v[170:173], v[202:205], v[12:15]
	v_mfma_f32_16x16x32_bf16 v[8:11], v[178:181], v[202:205], v[8:11]
	v_mfma_f32_16x16x32_bf16 v[4:7], v[170:173], v[244:247], v[4:7]
	v_mfma_f32_16x16x32_bf16 v[0:3], v[178:181], v[244:247], v[0:3]
	s_barrier
	s_add_i32 s43, 0, 0x18000
	s_add_i32 s61, 0, 0x1c000
	v_add_u32_e32 v140, s43, v234
	v_add_u32_e32 v178, s61, v234
	ds_read_b128 v[128:131], v140
	ds_read_b128 v[132:135], v140 offset:1024
	ds_read_b128 v[136:139], v140 offset:2048
	ds_read_b128 v[140:143], v140 offset:3072
	ds_read_b128 v[166:169], v178
	ds_read_b128 v[170:173], v178 offset:1024
	ds_read_b128 v[174:177], v178 offset:2048
	ds_read_b128 v[178:181], v178 offset:3072
	s_add_u32 s40, s40, 0x40000
	s_addc_u32 s41, s41, 0
	s_mov_b32 m0, s51
	v_lshl_add_u64 v[252:253], s[40:41], 0, v[154:155]
	ds_read_b128 v[182:185], v236 offset:32768
	ds_read_b128 v[186:189], v236 offset:33792
	ds_read_b128 v[190:193], v236 offset:34816
	ds_read_b128 v[194:197], v236 offset:35840
	ds_read_b128 v[198:201], v236 offset:36864
	ds_read_b128 v[202:205], v236 offset:37888
	ds_read_b128 v[206:209], v236 offset:38912
	ds_read_b128 v[244:247], v236 offset:39936
	global_load_lds_dwordx4 v[252:253], off
	v_lshl_add_u64 v[252:253], s[40:41], 0, v[156:157]
	s_mov_b32 m0, s52
	s_nop 0
	global_load_lds_dwordx4 v[252:253], off
	s_waitcnt vmcnt(8)
	s_waitcnt lgkmcnt(0)
	s_barrier
	s_waitcnt lgkmcnt(0)
	v_mfma_f32_16x16x32_bf16 v[124:127], v[128:131], v[182:185], v[124:127]
	v_mfma_f32_16x16x32_bf16 v[120:123], v[136:139], v[182:185], v[120:123]
	v_mfma_f32_16x16x32_bf16 v[116:119], v[128:131], v[190:193], v[116:119]
	v_mfma_f32_16x16x32_bf16 v[112:115], v[136:139], v[190:193], v[112:115]
	v_mfma_f32_16x16x32_bf16 v[108:111], v[128:131], v[198:201], v[108:111]
	v_mfma_f32_16x16x32_bf16 v[104:107], v[136:139], v[198:201], v[104:107]
	v_mfma_f32_16x16x32_bf16 v[100:103], v[128:131], v[206:209], v[100:103]
	v_mfma_f32_16x16x32_bf16 v[96:99], v[136:139], v[206:209], v[96:99]
	v_mfma_f32_16x16x32_bf16 v[124:127], v[132:135], v[186:189], v[124:127]
	v_mfma_f32_16x16x32_bf16 v[120:123], v[140:143], v[186:189], v[120:123]
	v_mfma_f32_16x16x32_bf16 v[116:119], v[132:135], v[194:197], v[116:119]
	v_mfma_f32_16x16x32_bf16 v[112:115], v[140:143], v[194:197], v[112:115]
	v_mfma_f32_16x16x32_bf16 v[108:111], v[132:135], v[202:205], v[108:111]
	v_mfma_f32_16x16x32_bf16 v[104:107], v[140:143], v[202:205], v[104:107]
	v_mfma_f32_16x16x32_bf16 v[100:103], v[132:135], v[244:247], v[100:103]
	v_mfma_f32_16x16x32_bf16 v[96:99], v[140:143], v[244:247], v[96:99]
	v_mfma_f32_16x16x32_bf16 v[92:95], v[166:169], v[182:185], v[92:95]
	v_mfma_f32_16x16x32_bf16 v[88:91], v[174:177], v[182:185], v[88:91]
	v_mfma_f32_16x16x32_bf16 v[84:87], v[166:169], v[190:193], v[84:87]
	v_mfma_f32_16x16x32_bf16 v[80:83], v[174:177], v[190:193], v[80:83]
	v_mfma_f32_16x16x32_bf16 v[76:79], v[166:169], v[198:201], v[76:79]
	v_mfma_f32_16x16x32_bf16 v[72:75], v[174:177], v[198:201], v[72:75]
	v_mfma_f32_16x16x32_bf16 v[68:71], v[166:169], v[206:209], v[68:71]
	v_mfma_f32_16x16x32_bf16 v[64:67], v[174:177], v[206:209], v[64:67]
	v_mfma_f32_16x16x32_bf16 v[92:95], v[170:173], v[186:189], v[92:95]
	v_mfma_f32_16x16x32_bf16 v[88:91], v[178:181], v[186:189], v[88:91]
	v_mfma_f32_16x16x32_bf16 v[84:87], v[170:173], v[194:197], v[84:87]
	v_mfma_f32_16x16x32_bf16 v[80:83], v[178:181], v[194:197], v[80:83]
	v_mfma_f32_16x16x32_bf16 v[76:79], v[170:173], v[202:205], v[76:79]
	v_mfma_f32_16x16x32_bf16 v[72:75], v[178:181], v[202:205], v[72:75]
	v_mfma_f32_16x16x32_bf16 v[68:71], v[170:173], v[244:247], v[68:71]
	v_mfma_f32_16x16x32_bf16 v[64:67], v[178:181], v[244:247], v[64:67]
	s_barrier
; #define PG8_STAGE(bufoff, gbase, voff) do { _Pragma("unroll") for (int _i = 0; _i < 2; ++_i) \
;         __builtin_amdgcn_global_load_lds((const unsigned*)((const char*)(gbase) + (voff)[_i]), (PG8_LAS unsigned*)(lds + (bufoff) + ldsw + _i * 8192), 16, 0, 0); } while (0)
; #define PG8_LDA(dst, b, h) do { _Pragma("unroll") for (int m = 0; m < 4; ++m) _Pragma("unroll") for (int k = 0; k < 2; ++k) dst[m][k] = *(const PG8_LAS bf16x8*)(lds + PG8_SA(b, h) + aoff + m * 2048 + k * 1024); } while (0)
; #define PG8_MMA(ai, bj, At, Bt) do { __builtin_amdgcn_s_setprio(1); _Pragma("unroll") for (int m = 0; m < 4; ++m) _Pragma("unroll") for (int n = 0; n < 2; ++n) _Pragma("unroll") for (int k = 0; k < 2; ++k) \
;         acc[ai][bj][m][n] = __builtin_amdgcn_mfma_f32_16x16x32_bf16(Bt[n][k], At[m][k], acc[ai][bj][m][n], 0, 0, 0); __builtin_amdgcn_s_setprio(0); } while (0)
; #define PG8_WAIT_V(n) asm volatile("s_waitcnt vmcnt(" #n ")" ::: "memory")
; #define PG8_WAIT_L(n) asm volatile("s_waitcnt lgkmcnt(" #n ")" ::: "memory")
; #define PG8_BAR __builtin_amdgcn_s_barrier()
; #define PG8_SCHED __builtin_amdgcn_sched_barrier(0)
; template <class Epi, class Sched, bool ALIGN_EPI = false, bool SP2 = false>
; __device__ __forceinline__ void gemm_phase(PG8_LAS unsigned char* lds, const Gemm g, const Sched& S, const Epi& E) {
;     ...
;             PG8_LDA(At, 1, 1); PG8_STAGE(PG8_SB(1, 0), b3, voffB); PG8_STAGE(PG8_SB(1, 1), b3 + hstep, voffB); PG8_STAGE(PG8_SA(1, 0), a3, voffA);
;             PG8_WAIT_V(8); PG8_WAIT_L(0); PG8_BAR; PG8_MMA(1, 0, At, B0); PG8_MMA(1, 1, At, B1); PG8_BAR; PG8_SCHED;
	s_add_i32 s40, s43, s48
	v_lshl_add_u64 v[210:211], v[210:211], 0, s[66:67]
	s_mov_b32 m0, s40
	ds_read_b128 v[182:185], v236 offset:49152
	ds_read_b128 v[186:189], v236 offset:50176
	ds_read_b128 v[190:193], v236 offset:51200
	ds_read_b128 v[194:197], v236 offset:52224
	ds_read_b128 v[198:201], v236 offset:53248
	ds_read_b128 v[202:205], v236 offset:54272
	ds_read_b128 v[206:209], v236 offset:55296
	ds_read_b128 v[244:247], v236 offset:56320
	global_load_lds_dwordx4 v[210:211], off
	s_add_i32 m0, s40, 0x2000
	s_add_u32 s38, s38, 0x40080
	v_lshl_add_u64 v[210:211], v[214:215], 0, s[66:67]
	s_addc_u32 s39, s39, 0
	s_add_i32 s40, s61, s48
	global_load_lds_dwordx4 v[210:211], off
	v_lshl_add_u64 v[210:211], s[38:39], 0, v[144:145]
	s_mov_b32 m0, s40
	s_nop 0
	global_load_lds_dwordx4 v[210:211], off
	v_lshl_add_u64 v[210:211], s[38:39], 0, v[158:159]
	s_add_i32 m0, s40, 0x2000
	s_nop 0
	global_load_lds_dwordx4 v[210:211], off
	v_lshl_add_u64 v[210:211], v[248:249], 0, s[66:67]
	s_mov_b32 m0, s55
	s_nop 0
	global_load_lds_dwordx4 v[210:211], off
	v_lshl_add_u64 v[210:211], v[250:251], 0, s[66:67]
	s_mov_b32 m0, s56
	s_nop 0
	global_load_lds_dwordx4 v[210:211], off
	s_waitcnt vmcnt(8)
	s_waitcnt lgkmcnt(0)
	s_barrier
	s_waitcnt lgkmcnt(0)
	v_mfma_f32_16x16x32_bf16 v[60:63], v[128:131], v[182:185], v[60:63]
	v_mfma_f32_16x16x32_bf16 v[56:59], v[136:139], v[182:185], v[56:59]
	v_mfma_f32_16x16x32_bf16 v[52:55], v[128:131], v[190:193], v[52:55]
	v_mfma_f32_16x16x32_bf16 v[48:51], v[136:139], v[190:193], v[48:51]
	v_mfma_f32_16x16x32_bf16 v[44:47], v[128:131], v[198:201], v[44:47]
	v_mfma_f32_16x16x32_bf16 v[40:43], v[136:139], v[198:201], v[40:43]
	v_mfma_f32_16x16x32_bf16 v[36:39], v[128:131], v[206:209], v[36:39]
	v_mfma_f32_16x16x32_bf16 v[32:35], v[136:139], v[206:209], v[32:35]
	v_mfma_f32_16x16x32_bf16 v[60:63], v[132:135], v[186:189], v[60:63]
	v_mfma_f32_16x16x32_bf16 v[56:59], v[140:143], v[186:189], v[56:59]
	v_mfma_f32_16x16x32_bf16 v[52:55], v[132:135], v[194:197], v[52:55]
	v_mfma_f32_16x16x32_bf16 v[48:51], v[140:143], v[194:197], v[48:51]
	v_mfma_f32_16x16x32_bf16 v[44:47], v[132:135], v[202:205], v[44:47]
	v_mfma_f32_16x16x32_bf16 v[40:43], v[140:143], v[202:205], v[40:43]
	v_mfma_f32_16x16x32_bf16 v[36:39], v[132:135], v[244:247], v[36:39]
	v_mfma_f32_16x16x32_bf16 v[32:35], v[140:143], v[244:247], v[32:35]
	v_mfma_f32_16x16x32_bf16 v[28:31], v[166:169], v[182:185], v[28:31]
	v_mfma_f32_16x16x32_bf16 v[24:27], v[174:177], v[182:185], v[24:27]
	v_mfma_f32_16x16x32_bf16 v[20:23], v[166:169], v[190:193], v[20:23]
	v_mfma_f32_16x16x32_bf16 v[16:19], v[174:177], v[190:193], v[16:19]
	v_mfma_f32_16x16x32_bf16 v[12:15], v[166:169], v[198:201], v[12:15]
	v_mfma_f32_16x16x32_bf16 v[8:11], v[174:177], v[198:201], v[8:11]
	v_mfma_f32_16x16x32_bf16 v[4:7], v[166:169], v[206:209], v[4:7]
	v_mfma_f32_16x16x32_bf16 v[0:3], v[174:177], v[206:209], v[0:3]
	v_mfma_f32_16x16x32_bf16 v[28:31], v[170:173], v[186:189], v[28:31]
	v_mfma_f32_16x16x32_bf16 v[24:27], v[178:181], v[186:189], v[24:27]
	v_mfma_f32_16x16x32_bf16 v[20:23], v[170:173], v[194:197], v[20:23]
	v_mfma_f32_16x16x32_bf16 v[16:19], v[178:181], v[194:197], v[16:19]
	v_mfma_f32_16x16x32_bf16 v[12:15], v[170:173], v[202:205], v[12:15]
	v_mfma_f32_16x16x32_bf16 v[8:11], v[178:181], v[202:205], v[8:11]
	v_mfma_f32_16x16x32_bf16 v[4:7], v[170:173], v[244:247], v[4:7]
	v_mfma_f32_16x16x32_bf16 v[0:3], v[178:181], v[244:247], v[0:3]
	s_barrier
	s_add_u32 s21, s21, 0x100
	s_addc_u32 s31, s31, 0
	s_add_u32 s16, s16, 0x100
	s_addc_u32 s17, s17, 0
	s_cmp_ge_i32 s42, s35
	s_mov_b32 s38, s42
	s_cbranch_scc0 .LBB0_1133
	s_and_b64 vcc, exec, s[24:25]
	s_cbranch_vccz .LBB0_1136

; #define PG8_STAGE(bufoff, gbase, voff) do { _Pragma("unroll") for (int _i = 0; _i < 2; ++_i) \
;         __builtin_amdgcn_global_load_lds((const unsigned*)((const char*)(gbase) + (voff)[_i]), (PG8_LAS unsigned*)(lds + (bufoff) + ldsw + _i * 8192), 16, 0, 0); } while (0)
; #define PG8_LDA(dst, b, h) do { _Pragma("unroll") for (int m = 0; m < 4; ++m) _Pragma("unroll") for (int k = 0; k < 2; ++k) dst[m][k] = *(const PG8_LAS bf16x8*)(lds + PG8_SA(b, h) + aoff + m * 2048 + k * 1024); } while (0)
; #define PG8_LDB(dst, b, h) do { _Pragma("unroll") for (int n = 0; n < 2; ++n) _Pragma("unroll") for (int k = 0; k < 2; ++k) dst[n][k] = *(const PG8_LAS bf16x8*)(lds + PG8_SB(b, h) + boff + n * 2048 + k * 1024); } while (0)
; #define PG8_MMA(ai, bj, At, Bt) do { __builtin_amdgcn_s_setprio(1); _Pragma("unroll") for (int m = 0; m < 4; ++m) _Pragma("unroll") for (int n = 0; n < 2; ++n) _Pragma("unroll") for (int k = 0; k < 2; ++k) \
;         acc[ai][bj][m][n] = __builtin_amdgcn_mfma_f32_16x16x32_bf16(Bt[n][k], At[m][k], acc[ai][bj][m][n], 0, 0, 0); __builtin_amdgcn_s_setprio(0); } while (0)
; #define PG8_WAIT_V(n) asm volatile("s_waitcnt vmcnt(" #n ")" ::: "memory")
; #define PG8_WAIT_L(n) asm volatile("s_waitcnt lgkmcnt(" #n ")" ::: "memory")
; #define PG8_BAR __builtin_amdgcn_s_barrier()
; #define PG8_SCHED __builtin_amdgcn_sched_barrier(0)
; template <class Epi, class Sched, bool ALIGN_EPI = false, bool SP2 = false>
; __device__ __forceinline__ void gemm_phase(PG8_LAS unsigned char* lds, const Gemm g, const Sched& S, const Epi& E) {
;     ...
;             const bool last = (t == nt - 2);
;             const char* a1 = cA + (size_t)(t + 1) * kstep;
;             const char* a2 = last ? nA : cA + (size_t)(t + 2) * kstep; const char* b2 = last ? nB : cB + (size_t)(t + 2) * kstep;
;             const char* a3 = a2 + kstep; const char* b3 = b2 + kstep;
;             if (last && has_next) S.a_ready(nxt);
;             if constexpr (SP2) {
;             PG8_LDB(B0, 0, 0); PG8_LDB(B1, 0, 1); PG8_SCHED; PG8_LDA(At, 0, 0); PG8_STAGE(PG8_SA(1, 1), a1 + hstep, voffA);
;             PG8_WAIT_V(8); PG8_WAIT_L(0); PG8_BAR; PG8_MMA(0, 0, At, B0); PG8_MMA(0, 1, At, B1); PG8_BAR; PG8_SCHED;
;             PG8_LDA(At, 0, 1); PG8_STAGE(PG8_SB(0, 0), b2, voffB); PG8_STAGE(PG8_SB(0, 1), b2 + hstep, voffB); PG8_STAGE(PG8_SA(0, 0), a2, voffA);
.LBB0_1205:
	s_add_u32 s28, s26, 0xfffc0080
	s_addc_u32 s29, s27, -1
	s_add_i32 s50, 0, 0x10000
	s_cmp_eq_u32 s49, 12
	s_cselect_b32 s31, s17, s29
	s_cselect_b32 s30, s23, s28
	v_add_u32_e32 v142, s50, v157
	s_cselect_b32 s29, s15, s48
	s_cselect_b32 s28, s42, s43
	s_add_i32 s52, 0, 0x14000
	ds_read_b128 v[138:141], v142
	ds_read_b128 v[160:163], v142 offset:1024
	ds_read_b128 v[164:167], v142 offset:2048
	ds_read_b128 v[168:171], v142 offset:3072
	v_add_u32_e32 v142, s52, v157
	ds_read_b128 v[172:175], v142
	ds_read_b128 v[176:179], v142 offset:1024
	ds_read_b128 v[180:183], v142 offset:2048
	ds_read_b128 v[184:187], v142 offset:3072
	v_lshl_add_u64 v[142:143], s[26:27], 0, v[136:137]
	s_add_i32 m0, s25, 0xc000
	ds_read_b128 v[188:191], v159
	ds_read_b128 v[192:195], v159 offset:1024
	ds_read_b128 v[196:199], v159 offset:2048
	ds_read_b128 v[200:203], v159 offset:3072
	ds_read_b128 v[204:207], v159 offset:4096
	ds_read_b128 v[208:211], v159 offset:5120
	ds_read_b128 v[234:237], v159 offset:6144
	ds_read_b128 v[244:247], v159 offset:7168
	global_load_lds_dwordx4 v[142:143], off
	v_lshl_add_u64 v[142:143], s[26:27], 0, v[134:135]
	s_add_i32 m0, s25, 0xe000
	s_nop 0
	global_load_lds_dwordx4 v[142:143], off
	s_waitcnt vmcnt(8)
	s_waitcnt lgkmcnt(0)
	s_barrier
	s_waitcnt lgkmcnt(0)
	v_mfma_f32_16x16x32_bf16 v[124:127], v[138:141], v[188:191], v[124:127]
	v_mfma_f32_16x16x32_bf16 v[120:123], v[164:167], v[188:191], v[120:123]
	v_mfma_f32_16x16x32_bf16 v[108:111], v[138:141], v[196:199], v[108:111]
	v_mfma_f32_16x16x32_bf16 v[104:107], v[164:167], v[196:199], v[104:107]
	v_mfma_f32_16x16x32_bf16 v[92:95], v[138:141], v[204:207], v[92:95]
	v_mfma_f32_16x16x32_bf16 v[88:91], v[164:167], v[204:207], v[88:91]
	v_mfma_f32_16x16x32_bf16 v[76:79], v[138:141], v[234:237], v[76:79]
	v_mfma_f32_16x16x32_bf16 v[72:75], v[164:167], v[234:237], v[72:75]
	v_mfma_f32_16x16x32_bf16 v[124:127], v[160:163], v[192:195], v[124:127]
	v_mfma_f32_16x16x32_bf16 v[120:123], v[168:171], v[192:195], v[120:123]
	v_mfma_f32_16x16x32_bf16 v[108:111], v[160:163], v[200:203], v[108:111]
	v_mfma_f32_16x16x32_bf16 v[104:107], v[168:171], v[200:203], v[104:107]
	v_mfma_f32_16x16x32_bf16 v[92:95], v[160:163], v[208:211], v[92:95]
	v_mfma_f32_16x16x32_bf16 v[88:91], v[168:171], v[208:211], v[88:91]
	v_mfma_f32_16x16x32_bf16 v[76:79], v[160:163], v[244:247], v[76:79]
	v_mfma_f32_16x16x32_bf16 v[72:75], v[168:171], v[244:247], v[72:75]
	v_mfma_f32_16x16x32_bf16 v[116:119], v[172:175], v[188:191], v[116:119]
	v_mfma_f32_16x16x32_bf16 v[112:115], v[180:183], v[188:191], v[112:115]
	v_mfma_f32_16x16x32_bf16 v[100:103], v[172:175], v[196:199], v[100:103]
	v_mfma_f32_16x16x32_bf16 v[96:99], v[180:183], v[196:199], v[96:99]
	v_mfma_f32_16x16x32_bf16 v[84:87], v[172:175], v[204:207], v[84:87]
	v_mfma_f32_16x16x32_bf16 v[80:83], v[180:183], v[204:207], v[80:83]
	v_mfma_f32_16x16x32_bf16 v[68:71], v[172:175], v[234:237], v[68:71]
	v_mfma_f32_16x16x32_bf16 v[64:67], v[180:183], v[234:237], v[64:67]
	v_mfma_f32_16x16x32_bf16 v[116:119], v[176:179], v[192:195], v[116:119]
	v_mfma_f32_16x16x32_bf16 v[112:115], v[184:187], v[192:195], v[112:115]
	v_mfma_f32_16x16x32_bf16 v[100:103], v[176:179], v[200:203], v[100:103]
	v_mfma_f32_16x16x32_bf16 v[96:99], v[184:187], v[200:203], v[96:99]
	v_mfma_f32_16x16x32_bf16 v[84:87], v[176:179], v[208:211], v[84:87]
	v_mfma_f32_16x16x32_bf16 v[80:83], v[184:187], v[208:211], v[80:83]
	v_mfma_f32_16x16x32_bf16 v[68:71], v[176:179], v[244:247], v[68:71]
	v_mfma_f32_16x16x32_bf16 v[64:67], v[184:187], v[244:247], v[64:67]
	s_barrier
	s_add_i32 s50, s50, s0
	v_lshl_add_u64 v[142:143], s[28:29], 0, v[144:145]
	s_mov_b32 m0, s50
	ds_read_b128 v[188:191], v159 offset:16384
	ds_read_b128 v[192:195], v159 offset:17408
	ds_read_b128 v[196:199], v159 offset:18432
	ds_read_b128 v[200:203], v159 offset:19456
	ds_read_b128 v[204:207], v159 offset:20480
	ds_read_b128 v[208:211], v159 offset:21504
	ds_read_b128 v[234:237], v159 offset:22528
	ds_read_b128 v[244:247], v159 offset:23552
	global_load_lds_dwordx4 v[142:143], off
	s_add_i32 m0, s50, 0x2000
	s_add_u32 s50, s28, 0x40000
	v_lshl_add_u64 v[154:155], s[28:29], 0, v[132:133]
	s_addc_u32 s51, s29, 0
	s_add_i32 s52, s52, s0
	global_load_lds_dwordx4 v[154:155], off
	v_lshl_add_u64 v[214:215], s[50:51], 0, v[144:145]
	s_mov_b32 m0, s52
	v_lshl_add_u64 v[238:239], s[30:31], 0, v[130:131]
	global_load_lds_dwordx4 v[214:215], off
	v_lshl_add_u64 v[214:215], s[50:51], 0, v[132:133]
	s_add_i32 m0, s52, 0x2000
	s_nop 0
	global_load_lds_dwordx4 v[214:215], off
	v_lshl_add_u64 v[214:215], s[30:31], 0, v[128:129]
	s_mov_b32 m0, s25
	s_nop 0
	global_load_lds_dwordx4 v[214:215], off
	s_mov_b32 m0, s34
	s_nop 0
	global_load_lds_dwordx4 v[238:239], off
	s_waitcnt vmcnt(8)
	s_waitcnt lgkmcnt(0)
	s_barrier
; #define PG8_STAGE(bufoff, gbase, voff) do { _Pragma("unroll") for (int _i = 0; _i < 2; ++_i) \
;         __builtin_amdgcn_global_load_lds((const unsigned*)((const char*)(gbase) + (voff)[_i]), (PG8_LAS unsigned*)(lds + (bufoff) + ldsw + _i * 8192), 16, 0, 0); } while (0)
; #define PG8_LDA(dst, b, h) do { _Pragma("unroll") for (int m = 0; m < 4; ++m) _Pragma("unroll") for (int k = 0; k < 2; ++k) dst[m][k] = *(const PG8_LAS bf16x8*)(lds + PG8_SA(b, h) + aoff + m * 2048 + k * 1024); } while (0)
; #define PG8_LDB(dst, b, h) do { _Pragma("unroll") for (int n = 0; n < 2; ++n) _Pragma("unroll") for (int k = 0; k < 2; ++k) dst[n][k] = *(const PG8_LAS bf16x8*)(lds + PG8_SB(b, h) + boff + n * 2048 + k * 1024); } while (0)
; #define PG8_MMA(ai, bj, At, Bt) do { __builtin_amdgcn_s_setprio(1); _Pragma("unroll") for (int m = 0; m < 4; ++m) _Pragma("unroll") for (int n = 0; n < 2; ++n) _Pragma("unroll") for (int k = 0; k < 2; ++k) \
;         acc[ai][bj][m][n] = __builtin_amdgcn_mfma_f32_16x16x32_bf16(Bt[n][k], At[m][k], acc[ai][bj][m][n], 0, 0, 0); __builtin_amdgcn_s_setprio(0); } while (0)
; #define PG8_WAIT_V(n) asm volatile("s_waitcnt vmcnt(" #n ")" ::: "memory")
; #define PG8_WAIT_L(n) asm volatile("s_waitcnt lgkmcnt(" #n ")" ::: "memory")
; #define PG8_BAR __builtin_amdgcn_s_barrier()
; #define PG8_SCHED __builtin_amdgcn_sched_barrier(0)
; template <class Epi, class Sched, bool ALIGN_EPI = false, bool SP2 = false>
; __device__ __forceinline__ void gemm_phase(PG8_LAS unsigned char* lds, const Gemm g, const Sched& S, const Epi& E) {
;     ...
;             PG8_WAIT_V(8); PG8_WAIT_L(0); PG8_BAR; PG8_MMA(1, 0, At, B0); PG8_MMA(1, 1, At, B1); PG8_BAR; PG8_SCHED;
;             PG8_LDB(B0, 1, 0); PG8_LDB(B1, 1, 1); PG8_SCHED; PG8_LDA(At, 1, 0); PG8_STAGE(PG8_SA(0, 1), a2 + hstep, voffA);
;             PG8_WAIT_V(8); PG8_WAIT_L(0); PG8_BAR; PG8_MMA(0, 0, At, B0); PG8_MMA(0, 1, At, B1); PG8_BAR; PG8_SCHED;
	s_waitcnt lgkmcnt(0)
	v_mfma_f32_16x16x32_bf16 v[60:63], v[138:141], v[188:191], v[60:63]
	v_mfma_f32_16x16x32_bf16 v[56:59], v[164:167], v[188:191], v[56:59]
	v_mfma_f32_16x16x32_bf16 v[44:47], v[138:141], v[196:199], v[44:47]
	v_mfma_f32_16x16x32_bf16 v[40:43], v[164:167], v[196:199], v[40:43]
	v_mfma_f32_16x16x32_bf16 v[28:31], v[138:141], v[204:207], v[28:31]
	v_mfma_f32_16x16x32_bf16 v[24:27], v[164:167], v[204:207], v[24:27]
	v_mfma_f32_16x16x32_bf16 v[12:15], v[138:141], v[234:237], v[12:15]
	v_mfma_f32_16x16x32_bf16 v[8:11], v[164:167], v[234:237], v[8:11]
	v_mfma_f32_16x16x32_bf16 v[60:63], v[160:163], v[192:195], v[60:63]
	v_mfma_f32_16x16x32_bf16 v[56:59], v[168:171], v[192:195], v[56:59]
	v_mfma_f32_16x16x32_bf16 v[44:47], v[160:163], v[200:203], v[44:47]
	v_mfma_f32_16x16x32_bf16 v[40:43], v[168:171], v[200:203], v[40:43]
	v_mfma_f32_16x16x32_bf16 v[28:31], v[160:163], v[208:211], v[28:31]
	v_mfma_f32_16x16x32_bf16 v[24:27], v[168:171], v[208:211], v[24:27]
	v_mfma_f32_16x16x32_bf16 v[12:15], v[160:163], v[244:247], v[12:15]
	v_mfma_f32_16x16x32_bf16 v[8:11], v[168:171], v[244:247], v[8:11]
	v_mfma_f32_16x16x32_bf16 v[52:55], v[172:175], v[188:191], v[52:55]
	v_mfma_f32_16x16x32_bf16 v[48:51], v[180:183], v[188:191], v[48:51]
	v_mfma_f32_16x16x32_bf16 v[36:39], v[172:175], v[196:199], v[36:39]
	v_mfma_f32_16x16x32_bf16 v[32:35], v[180:183], v[196:199], v[32:35]
	v_mfma_f32_16x16x32_bf16 v[20:23], v[172:175], v[204:207], v[20:23]
	v_mfma_f32_16x16x32_bf16 v[16:19], v[180:183], v[204:207], v[16:19]
	v_mfma_f32_16x16x32_bf16 v[4:7], v[172:175], v[234:237], v[4:7]
	v_mfma_f32_16x16x32_bf16 v[0:3], v[180:183], v[234:237], v[0:3]
	v_mfma_f32_16x16x32_bf16 v[52:55], v[176:179], v[192:195], v[52:55]
	v_mfma_f32_16x16x32_bf16 v[48:51], v[184:187], v[192:195], v[48:51]
	v_mfma_f32_16x16x32_bf16 v[36:39], v[176:179], v[200:203], v[36:39]
	v_mfma_f32_16x16x32_bf16 v[32:35], v[184:187], v[200:203], v[32:35]
	v_mfma_f32_16x16x32_bf16 v[20:23], v[176:179], v[208:211], v[20:23]
	v_mfma_f32_16x16x32_bf16 v[16:19], v[184:187], v[208:211], v[16:19]
	v_mfma_f32_16x16x32_bf16 v[4:7], v[176:179], v[244:247], v[4:7]
	v_mfma_f32_16x16x32_bf16 v[0:3], v[184:187], v[244:247], v[0:3]
	s_barrier
	s_add_i32 s50, 0, 0x18000
	s_add_i32 s51, 0, 0x1c000
	v_add_u32_e32 v168, s50, v157
	v_add_u32_e32 v184, s51, v157
	ds_read_b128 v[138:141], v168
	ds_read_b128 v[160:163], v168 offset:1024
	ds_read_b128 v[164:167], v168 offset:2048
	ds_read_b128 v[168:171], v168 offset:3072
	ds_read_b128 v[172:175], v184
	ds_read_b128 v[176:179], v184 offset:1024
	ds_read_b128 v[180:183], v184 offset:2048
	ds_read_b128 v[184:187], v184 offset:3072
	s_add_u32 s30, s30, 0x40000
	s_addc_u32 s31, s31, 0
	s_mov_b32 m0, s35
	v_lshl_add_u64 v[248:249], s[30:31], 0, v[128:129]
	ds_read_b128 v[188:191], v159 offset:32768
	ds_read_b128 v[192:195], v159 offset:33792
	ds_read_b128 v[196:199], v159 offset:34816
	ds_read_b128 v[200:203], v159 offset:35840
	ds_read_b128 v[204:207], v159 offset:36864
	ds_read_b128 v[208:211], v159 offset:37888
	ds_read_b128 v[234:237], v159 offset:38912
	ds_read_b128 v[244:247], v159 offset:39936
	global_load_lds_dwordx4 v[248:249], off
	v_lshl_add_u64 v[248:249], s[30:31], 0, v[130:131]
	s_mov_b32 m0, s38
	s_nop 0
	global_load_lds_dwordx4 v[248:249], off
	s_waitcnt vmcnt(8)
	s_waitcnt lgkmcnt(0)
	s_barrier
	s_waitcnt lgkmcnt(0)
	v_mfma_f32_16x16x32_bf16 v[124:127], v[138:141], v[188:191], v[124:127]
	v_mfma_f32_16x16x32_bf16 v[120:123], v[164:167], v[188:191], v[120:123]
	v_mfma_f32_16x16x32_bf16 v[108:111], v[138:141], v[196:199], v[108:111]
	v_mfma_f32_16x16x32_bf16 v[104:107], v[164:167], v[196:199], v[104:107]
	v_mfma_f32_16x16x32_bf16 v[92:95], v[138:141], v[204:207], v[92:95]
	v_mfma_f32_16x16x32_bf16 v[88:91], v[164:167], v[204:207], v[88:91]
	v_mfma_f32_16x16x32_bf16 v[76:79], v[138:141], v[234:237], v[76:79]
	v_mfma_f32_16x16x32_bf16 v[72:75], v[164:167], v[234:237], v[72:75]
	v_mfma_f32_16x16x32_bf16 v[124:127], v[160:163], v[192:195], v[124:127]
	v_mfma_f32_16x16x32_bf16 v[120:123], v[168:171], v[192:195], v[120:123]
	v_mfma_f32_16x16x32_bf16 v[108:111], v[160:163], v[200:203], v[108:111]
	v_mfma_f32_16x16x32_bf16 v[104:107], v[168:171], v[200:203], v[104:107]
	v_mfma_f32_16x16x32_bf16 v[92:95], v[160:163], v[208:211], v[92:95]
	v_mfma_f32_16x16x32_bf16 v[88:91], v[168:171], v[208:211], v[88:91]
	v_mfma_f32_16x16x32_bf16 v[76:79], v[160:163], v[244:247], v[76:79]
	v_mfma_f32_16x16x32_bf16 v[72:75], v[168:171], v[244:247], v[72:75]
	v_mfma_f32_16x16x32_bf16 v[116:119], v[172:175], v[188:191], v[116:119]
	v_mfma_f32_16x16x32_bf16 v[112:115], v[180:183], v[188:191], v[112:115]
	v_mfma_f32_16x16x32_bf16 v[100:103], v[172:175], v[196:199], v[100:103]
	v_mfma_f32_16x16x32_bf16 v[96:99], v[180:183], v[196:199], v[96:99]
	v_mfma_f32_16x16x32_bf16 v[84:87], v[172:175], v[204:207], v[84:87]
	v_mfma_f32_16x16x32_bf16 v[80:83], v[180:183], v[204:207], v[80:83]
	v_mfma_f32_16x16x32_bf16 v[68:71], v[172:175], v[234:237], v[68:71]
	v_mfma_f32_16x16x32_bf16 v[64:67], v[180:183], v[234:237], v[64:67]
	v_mfma_f32_16x16x32_bf16 v[116:119], v[176:179], v[192:195], v[116:119]
	v_mfma_f32_16x16x32_bf16 v[112:115], v[184:187], v[192:195], v[112:115]
	v_mfma_f32_16x16x32_bf16 v[100:103], v[176:179], v[200:203], v[100:103]
	v_mfma_f32_16x16x32_bf16 v[96:99], v[184:187], v[200:203], v[96:99]
	v_mfma_f32_16x16x32_bf16 v[84:87], v[176:179], v[208:211], v[84:87]
	v_mfma_f32_16x16x32_bf16 v[80:83], v[184:187], v[208:211], v[80:83]
	v_mfma_f32_16x16x32_bf16 v[68:71], v[176:179], v[244:247], v[68:71]
	v_mfma_f32_16x16x32_bf16 v[64:67], v[184:187], v[244:247], v[64:67]
	s_barrier
; #define PG8_STAGE(bufoff, gbase, voff) do { _Pragma("unroll") for (int _i = 0; _i < 2; ++_i) \
;         __builtin_amdgcn_global_load_lds((const unsigned*)((const char*)(gbase) + (voff)[_i]), (PG8_LAS unsigned*)(lds + (bufoff) + ldsw + _i * 8192), 16, 0, 0); } while (0)
; #define PG8_LDA(dst, b, h) do { _Pragma("unroll") for (int m = 0; m < 4; ++m) _Pragma("unroll") for (int k = 0; k < 2; ++k) dst[m][k] = *(const PG8_LAS bf16x8*)(lds + PG8_SA(b, h) + aoff + m * 2048 + k * 1024); } while (0)
; #define PG8_MMA(ai, bj, At, Bt) do { __builtin_amdgcn_s_setprio(1); _Pragma("unroll") for (int m = 0; m < 4; ++m) _Pragma("unroll") for (int n = 0; n < 2; ++n) _Pragma("unroll") for (int k = 0; k < 2; ++k) \
;         acc[ai][bj][m][n] = __builtin_amdgcn_mfma_f32_16x16x32_bf16(Bt[n][k], At[m][k], acc[ai][bj][m][n], 0, 0, 0); __builtin_amdgcn_s_setprio(0); } while (0)
; #define PG8_WAIT_V(n) asm volatile("s_waitcnt vmcnt(" #n ")" ::: "memory")
; #define PG8_WAIT_L(n) asm volatile("s_waitcnt lgkmcnt(" #n ")" ::: "memory")
; #define PG8_BAR __builtin_amdgcn_s_barrier()
; #define PG8_SCHED __builtin_amdgcn_sched_barrier(0)
; template <class Epi, class Sched, bool ALIGN_EPI = false, bool SP2 = false>
; __device__ __forceinline__ void gemm_phase(PG8_LAS unsigned char* lds, const Gemm g, const Sched& S, const Epi& E) {
;     ...
;             PG8_LDA(At, 1, 1); PG8_STAGE(PG8_SB(1, 0), b3, voffB); PG8_STAGE(PG8_SB(1, 1), b3 + hstep, voffB); PG8_STAGE(PG8_SA(1, 0), a3, voffA);
;             PG8_WAIT_V(8); PG8_WAIT_L(0); PG8_BAR; PG8_MMA(1, 0, At, B0); PG8_MMA(1, 1, At, B1); PG8_BAR; PG8_SCHED;
;     ...
;         if constexpr (ALIGN_EPI) { if (wr == 0) PG8_BAR; }
	s_add_i32 s30, s50, s0
	v_lshl_add_u64 v[142:143], v[142:143], 0, s[54:55]
	s_mov_b32 m0, s30
	ds_read_b128 v[188:191], v159 offset:49152
	ds_read_b128 v[192:195], v159 offset:50176
	ds_read_b128 v[196:199], v159 offset:51200
	ds_read_b128 v[200:203], v159 offset:52224
	ds_read_b128 v[204:207], v159 offset:53248
	ds_read_b128 v[208:211], v159 offset:54272
	ds_read_b128 v[234:237], v159 offset:55296
	ds_read_b128 v[244:247], v159 offset:56320
	global_load_lds_dwordx4 v[142:143], off
	s_add_i32 m0, s30, 0x2000
	s_add_u32 s28, s28, 0x40080
	v_lshl_add_u64 v[142:143], v[154:155], 0, s[54:55]
	s_addc_u32 s29, s29, 0
	s_add_i32 s30, s51, s0
	global_load_lds_dwordx4 v[142:143], off
	v_lshl_add_u64 v[142:143], s[28:29], 0, v[144:145]
	s_mov_b32 m0, s30
	s_nop 0
	global_load_lds_dwordx4 v[142:143], off
	v_lshl_add_u64 v[142:143], s[28:29], 0, v[132:133]
	s_add_i32 m0, s30, 0x2000
	s_nop 0
	global_load_lds_dwordx4 v[142:143], off
	v_lshl_add_u64 v[142:143], v[214:215], 0, s[54:55]
	s_mov_b32 m0, s39
	s_nop 0
	global_load_lds_dwordx4 v[142:143], off
	v_lshl_add_u64 v[142:143], v[238:239], 0, s[54:55]
	s_mov_b32 m0, s40
	s_nop 0
	global_load_lds_dwordx4 v[142:143], off
	s_waitcnt vmcnt(8)
	s_waitcnt lgkmcnt(0)
	s_barrier
	s_waitcnt lgkmcnt(0)
	v_mfma_f32_16x16x32_bf16 v[60:63], v[138:141], v[188:191], v[60:63]
	v_mfma_f32_16x16x32_bf16 v[56:59], v[164:167], v[188:191], v[56:59]
	v_mfma_f32_16x16x32_bf16 v[44:47], v[138:141], v[196:199], v[44:47]
	v_mfma_f32_16x16x32_bf16 v[40:43], v[164:167], v[196:199], v[40:43]
	v_mfma_f32_16x16x32_bf16 v[28:31], v[138:141], v[204:207], v[28:31]
	v_mfma_f32_16x16x32_bf16 v[24:27], v[164:167], v[204:207], v[24:27]
	v_mfma_f32_16x16x32_bf16 v[12:15], v[138:141], v[234:237], v[12:15]
	v_mfma_f32_16x16x32_bf16 v[8:11], v[164:167], v[234:237], v[8:11]
	v_mfma_f32_16x16x32_bf16 v[60:63], v[160:163], v[192:195], v[60:63]
	v_mfma_f32_16x16x32_bf16 v[56:59], v[168:171], v[192:195], v[56:59]
	v_mfma_f32_16x16x32_bf16 v[44:47], v[160:163], v[200:203], v[44:47]
	v_mfma_f32_16x16x32_bf16 v[40:43], v[168:171], v[200:203], v[40:43]
	v_mfma_f32_16x16x32_bf16 v[28:31], v[160:163], v[208:211], v[28:31]
	v_mfma_f32_16x16x32_bf16 v[24:27], v[168:171], v[208:211], v[24:27]
	v_mfma_f32_16x16x32_bf16 v[12:15], v[160:163], v[244:247], v[12:15]
	v_mfma_f32_16x16x32_bf16 v[8:11], v[168:171], v[244:247], v[8:11]
	v_mfma_f32_16x16x32_bf16 v[52:55], v[172:175], v[188:191], v[52:55]
	v_mfma_f32_16x16x32_bf16 v[48:51], v[180:183], v[188:191], v[48:51]
	v_mfma_f32_16x16x32_bf16 v[36:39], v[172:175], v[196:199], v[36:39]
	v_mfma_f32_16x16x32_bf16 v[32:35], v[180:183], v[196:199], v[32:35]
	v_mfma_f32_16x16x32_bf16 v[20:23], v[172:175], v[204:207], v[20:23]
	v_mfma_f32_16x16x32_bf16 v[16:19], v[180:183], v[204:207], v[16:19]
	v_mfma_f32_16x16x32_bf16 v[4:7], v[172:175], v[234:237], v[4:7]
	v_mfma_f32_16x16x32_bf16 v[0:3], v[180:183], v[234:237], v[0:3]
	v_mfma_f32_16x16x32_bf16 v[52:55], v[176:179], v[192:195], v[52:55]
	v_mfma_f32_16x16x32_bf16 v[48:51], v[184:187], v[192:195], v[48:51]
	v_mfma_f32_16x16x32_bf16 v[36:39], v[176:179], v[200:203], v[36:39]
	v_mfma_f32_16x16x32_bf16 v[32:35], v[184:187], v[200:203], v[32:35]
	v_mfma_f32_16x16x32_bf16 v[20:23], v[176:179], v[208:211], v[20:23]
	v_mfma_f32_16x16x32_bf16 v[16:19], v[184:187], v[208:211], v[16:19]
	v_mfma_f32_16x16x32_bf16 v[4:7], v[176:179], v[244:247], v[4:7]
	v_mfma_f32_16x16x32_bf16 v[0:3], v[184:187], v[244:247], v[0:3]
	s_barrier
	s_add_i32 s49, s49, 2
	s_add_u32 s43, s43, 0x100
	s_addc_u32 s48, s48, 0
	s_add_u32 s26, s26, 0x100
	s_addc_u32 s27, s27, 0
	s_cmp_gt_u32 s49, 13
	s_cbranch_scc0 .LBB0_1205
	s_and_b64 vcc, exec, s[6:7]
	s_cbranch_vccz .LBB0_1208
	s_barrier

; #define PG8_STAGE(bufoff, gbase, voff) do { _Pragma("unroll") for (int _i = 0; _i < 2; ++_i) \
;         __builtin_amdgcn_global_load_lds((const unsigned*)((const char*)(gbase) + (voff)[_i]), (PG8_LAS unsigned*)(lds + (bufoff) + ldsw + _i * 8192), 16, 0, 0); } while (0)
; #define PG8_LDA(dst, b, h) do { _Pragma("unroll") for (int m = 0; m < 4; ++m) _Pragma("unroll") for (int k = 0; k < 2; ++k) dst[m][k] = *(const PG8_LAS bf16x8*)(lds + PG8_SA(b, h) + aoff + m * 2048 + k * 1024); } while (0)
; #define PG8_LDB(dst, b, h) do { _Pragma("unroll") for (int n = 0; n < 2; ++n) _Pragma("unroll") for (int k = 0; k < 2; ++k) dst[n][k] = *(const PG8_LAS bf16x8*)(lds + PG8_SB(b, h) + boff + n * 2048 + k * 1024); } while (0)
; #define PG8_MMA(ai, bj, At, Bt) do { __builtin_amdgcn_s_setprio(1); _Pragma("unroll") for (int m = 0; m < 4; ++m) _Pragma("unroll") for (int n = 0; n < 2; ++n) _Pragma("unroll") for (int k = 0; k < 2; ++k) \
;         acc[ai][bj][m][n] = __builtin_amdgcn_mfma_f32_16x16x32_bf16(Bt[n][k], At[m][k], acc[ai][bj][m][n], 0, 0, 0); __builtin_amdgcn_s_setprio(0); } while (0)
; #define PG8_WAIT_V(n) asm volatile("s_waitcnt vmcnt(" #n ")" ::: "memory")
; #define PG8_WAIT_L(n) asm volatile("s_waitcnt lgkmcnt(" #n ")" ::: "memory")
; #define PG8_BAR __builtin_amdgcn_s_barrier()
; #define PG8_SCHED __builtin_amdgcn_sched_barrier(0)
; template <class Epi, class Sched, bool ALIGN_EPI = false, bool SP2 = false>
; __device__ __forceinline__ void gemm_phase(PG8_LAS unsigned char* lds, const Gemm g, const Sched& S, const Epi& E) {
;     ...
;             const bool last = (t == nt - 2);
;             const char* a1 = cA + (size_t)(t + 1) * kstep;
;             const char* a2 = last ? nA : cA + (size_t)(t + 2) * kstep; const char* b2 = last ? nB : cB + (size_t)(t + 2) * kstep;
;             const char* a3 = a2 + kstep; const char* b3 = b2 + kstep;
;             if (last && has_next) S.a_ready(nxt);
;             if constexpr (SP2) {
;             PG8_LDB(B0, 0, 0); PG8_LDB(B1, 0, 1); PG8_SCHED; PG8_LDA(At, 0, 0); PG8_STAGE(PG8_SA(1, 1), a1 + hstep, voffA);
;             PG8_WAIT_V(8); PG8_WAIT_L(0); PG8_BAR; PG8_MMA(0, 0, At, B0); PG8_MMA(0, 1, At, B1); PG8_BAR; PG8_SCHED;
;             PG8_LDA(At, 0, 1); PG8_STAGE(PG8_SB(0, 0), b2, voffB); PG8_STAGE(PG8_SB(0, 1), b2 + hstep, voffB); PG8_STAGE(PG8_SA(0, 0), a2, voffA);
.LBB0_1295:
	s_add_u32 s24, s22, 0xfffc0080
	s_addc_u32 s25, s23, -1
	s_add_i32 s47, 0, 0x10000
	s_cmp_eq_u32 s46, 12
	s_cselect_b32 s27, s17, s25
	s_cselect_b32 s26, s42, s24
	v_add_u32_e32 v142, s47, v156
	s_cselect_b32 s25, s15, s45
	s_cselect_b32 s24, s43, s44
	s_add_i32 s50, 0, 0x14000
	ds_read_b128 v[138:141], v142
	ds_read_b128 v[160:163], v142 offset:1024
	ds_read_b128 v[164:167], v142 offset:2048
	ds_read_b128 v[168:171], v142 offset:3072
	v_add_u32_e32 v142, s50, v156
	ds_read_b128 v[172:175], v142
	ds_read_b128 v[176:179], v142 offset:1024
	ds_read_b128 v[180:183], v142 offset:2048
	ds_read_b128 v[184:187], v142 offset:3072
	v_lshl_add_u64 v[142:143], s[22:23], 0, v[136:137]
	s_add_i32 m0, s34, 0xc000
	ds_read_b128 v[188:191], v158
	ds_read_b128 v[192:195], v158 offset:1024
	ds_read_b128 v[196:199], v158 offset:2048
	ds_read_b128 v[200:203], v158 offset:3072
	ds_read_b128 v[204:207], v158 offset:4096
	ds_read_b128 v[208:211], v158 offset:5120
	ds_read_b128 v[234:237], v158 offset:6144
	ds_read_b128 v[244:247], v158 offset:7168
	global_load_lds_dwordx4 v[142:143], off
	v_lshl_add_u64 v[142:143], s[22:23], 0, v[134:135]
	s_add_i32 m0, s34, 0xe000
	s_nop 0
	global_load_lds_dwordx4 v[142:143], off
	s_waitcnt vmcnt(8)
	s_waitcnt lgkmcnt(0)
	s_barrier
	s_waitcnt lgkmcnt(0)
	v_mfma_f32_16x16x32_bf16 v[124:127], v[138:141], v[188:191], v[124:127]
	v_mfma_f32_16x16x32_bf16 v[116:119], v[164:167], v[188:191], v[116:119]
	v_mfma_f32_16x16x32_bf16 v[108:111], v[138:141], v[196:199], v[108:111]
	v_mfma_f32_16x16x32_bf16 v[100:103], v[164:167], v[196:199], v[100:103]
	v_mfma_f32_16x16x32_bf16 v[92:95], v[138:141], v[204:207], v[92:95]
	v_mfma_f32_16x16x32_bf16 v[84:87], v[164:167], v[204:207], v[84:87]
	v_mfma_f32_16x16x32_bf16 v[76:79], v[138:141], v[234:237], v[76:79]
	v_mfma_f32_16x16x32_bf16 v[68:71], v[164:167], v[234:237], v[68:71]
	v_mfma_f32_16x16x32_bf16 v[124:127], v[160:163], v[192:195], v[124:127]
	v_mfma_f32_16x16x32_bf16 v[116:119], v[168:171], v[192:195], v[116:119]
	v_mfma_f32_16x16x32_bf16 v[108:111], v[160:163], v[200:203], v[108:111]
	v_mfma_f32_16x16x32_bf16 v[100:103], v[168:171], v[200:203], v[100:103]
	v_mfma_f32_16x16x32_bf16 v[92:95], v[160:163], v[208:211], v[92:95]
	v_mfma_f32_16x16x32_bf16 v[84:87], v[168:171], v[208:211], v[84:87]
	v_mfma_f32_16x16x32_bf16 v[76:79], v[160:163], v[244:247], v[76:79]
	v_mfma_f32_16x16x32_bf16 v[68:71], v[168:171], v[244:247], v[68:71]
	v_mfma_f32_16x16x32_bf16 v[120:123], v[172:175], v[188:191], v[120:123]
	v_mfma_f32_16x16x32_bf16 v[112:115], v[180:183], v[188:191], v[112:115]
	v_mfma_f32_16x16x32_bf16 v[104:107], v[172:175], v[196:199], v[104:107]
	v_mfma_f32_16x16x32_bf16 v[96:99], v[180:183], v[196:199], v[96:99]
	v_mfma_f32_16x16x32_bf16 v[88:91], v[172:175], v[204:207], v[88:91]
	v_mfma_f32_16x16x32_bf16 v[80:83], v[180:183], v[204:207], v[80:83]
	v_mfma_f32_16x16x32_bf16 v[72:75], v[172:175], v[234:237], v[72:75]
	v_mfma_f32_16x16x32_bf16 v[64:67], v[180:183], v[234:237], v[64:67]
	v_mfma_f32_16x16x32_bf16 v[120:123], v[176:179], v[192:195], v[120:123]
	v_mfma_f32_16x16x32_bf16 v[112:115], v[184:187], v[192:195], v[112:115]
	v_mfma_f32_16x16x32_bf16 v[104:107], v[176:179], v[200:203], v[104:107]
	v_mfma_f32_16x16x32_bf16 v[96:99], v[184:187], v[200:203], v[96:99]
	v_mfma_f32_16x16x32_bf16 v[88:91], v[176:179], v[208:211], v[88:91]
	v_mfma_f32_16x16x32_bf16 v[80:83], v[184:187], v[208:211], v[80:83]
	v_mfma_f32_16x16x32_bf16 v[72:75], v[176:179], v[244:247], v[72:75]
	v_mfma_f32_16x16x32_bf16 v[64:67], v[184:187], v[244:247], v[64:67]
	s_barrier
	s_add_i32 s47, s47, s31
	v_lshl_add_u64 v[142:143], s[24:25], 0, v[144:145]
	s_mov_b32 m0, s47
	ds_read_b128 v[188:191], v158 offset:16384
	ds_read_b128 v[192:195], v158 offset:17408
	ds_read_b128 v[196:199], v158 offset:18432
	ds_read_b128 v[200:203], v158 offset:19456
	ds_read_b128 v[204:207], v158 offset:20480
	ds_read_b128 v[208:211], v158 offset:21504
	ds_read_b128 v[234:237], v158 offset:22528
	ds_read_b128 v[244:247], v158 offset:23552
	global_load_lds_dwordx4 v[142:143], off
	s_add_i32 m0, s47, 0x2000
	s_add_u32 s48, s24, 0x40000
	v_lshl_add_u64 v[214:215], s[24:25], 0, v[128:129]
	s_addc_u32 s49, s25, 0
	s_add_i32 s47, s50, s31
	global_load_lds_dwordx4 v[214:215], off
	v_lshl_add_u64 v[238:239], s[48:49], 0, v[144:145]
	s_mov_b32 m0, s47
	v_lshl_add_u64 v[248:249], s[26:27], 0, v[130:131]
	global_load_lds_dwordx4 v[238:239], off
	v_lshl_add_u64 v[238:239], s[48:49], 0, v[128:129]
	s_add_i32 m0, s47, 0x2000
	s_nop 0
	global_load_lds_dwordx4 v[238:239], off
	v_lshl_add_u64 v[238:239], s[26:27], 0, v[132:133]
	s_mov_b32 m0, s34
	s_nop 0
	global_load_lds_dwordx4 v[238:239], off
	s_mov_b32 m0, s35
	s_nop 0
	global_load_lds_dwordx4 v[248:249], off
	s_waitcnt vmcnt(8)
	s_waitcnt lgkmcnt(0)
	s_barrier
; #define PG8_STAGE(bufoff, gbase, voff) do { _Pragma("unroll") for (int _i = 0; _i < 2; ++_i) \
;         __builtin_amdgcn_global_load_lds((const unsigned*)((const char*)(gbase) + (voff)[_i]), (PG8_LAS unsigned*)(lds + (bufoff) + ldsw + _i * 8192), 16, 0, 0); } while (0)
; #define PG8_LDA(dst, b, h) do { _Pragma("unroll") for (int m = 0; m < 4; ++m) _Pragma("unroll") for (int k = 0; k < 2; ++k) dst[m][k] = *(const PG8_LAS bf16x8*)(lds + PG8_SA(b, h) + aoff + m * 2048 + k * 1024); } while (0)
; #define PG8_LDB(dst, b, h) do { _Pragma("unroll") for (int n = 0; n < 2; ++n) _Pragma("unroll") for (int k = 0; k < 2; ++k) dst[n][k] = *(const PG8_LAS bf16x8*)(lds + PG8_SB(b, h) + boff + n * 2048 + k * 1024); } while (0)
; #define PG8_MMA(ai, bj, At, Bt) do { __builtin_amdgcn_s_setprio(1); _Pragma("unroll") for (int m = 0; m < 4; ++m) _Pragma("unroll") for (int n = 0; n < 2; ++n) _Pragma("unroll") for (int k = 0; k < 2; ++k) \
;         acc[ai][bj][m][n] = __builtin_amdgcn_mfma_f32_16x16x32_bf16(Bt[n][k], At[m][k], acc[ai][bj][m][n], 0, 0, 0); __builtin_amdgcn_s_setprio(0); } while (0)
; #define PG8_WAIT_V(n) asm volatile("s_waitcnt vmcnt(" #n ")" ::: "memory")
; #define PG8_WAIT_L(n) asm volatile("s_waitcnt lgkmcnt(" #n ")" ::: "memory")
; #define PG8_BAR __builtin_amdgcn_s_barrier()
; #define PG8_SCHED __builtin_amdgcn_sched_barrier(0)
; template <class Epi, class Sched, bool ALIGN_EPI = false, bool SP2 = false>
; __device__ __forceinline__ void gemm_phase(PG8_LAS unsigned char* lds, const Gemm g, const Sched& S, const Epi& E) {
;     ...
;             PG8_WAIT_V(8); PG8_WAIT_L(0); PG8_BAR; PG8_MMA(1, 0, At, B0); PG8_MMA(1, 1, At, B1); PG8_BAR; PG8_SCHED;
;             PG8_LDB(B0, 1, 0); PG8_LDB(B1, 1, 1); PG8_SCHED; PG8_LDA(At, 1, 0); PG8_STAGE(PG8_SA(0, 1), a2 + hstep, voffA);
;             PG8_WAIT_V(8); PG8_WAIT_L(0); PG8_BAR; PG8_MMA(0, 0, At, B0); PG8_MMA(0, 1, At, B1); PG8_BAR; PG8_SCHED;
	s_waitcnt lgkmcnt(0)
	v_mfma_f32_16x16x32_bf16 v[60:63], v[138:141], v[188:191], v[60:63]
	v_mfma_f32_16x16x32_bf16 v[52:55], v[164:167], v[188:191], v[52:55]
	v_mfma_f32_16x16x32_bf16 v[44:47], v[138:141], v[196:199], v[44:47]
	v_mfma_f32_16x16x32_bf16 v[36:39], v[164:167], v[196:199], v[36:39]
	v_mfma_f32_16x16x32_bf16 v[28:31], v[138:141], v[204:207], v[28:31]
	v_mfma_f32_16x16x32_bf16 v[20:23], v[164:167], v[204:207], v[20:23]
	v_mfma_f32_16x16x32_bf16 v[12:15], v[138:141], v[234:237], v[12:15]
	v_mfma_f32_16x16x32_bf16 v[4:7], v[164:167], v[234:237], v[4:7]
	v_mfma_f32_16x16x32_bf16 v[60:63], v[160:163], v[192:195], v[60:63]
	v_mfma_f32_16x16x32_bf16 v[52:55], v[168:171], v[192:195], v[52:55]
	v_mfma_f32_16x16x32_bf16 v[44:47], v[160:163], v[200:203], v[44:47]
	v_mfma_f32_16x16x32_bf16 v[36:39], v[168:171], v[200:203], v[36:39]
	v_mfma_f32_16x16x32_bf16 v[28:31], v[160:163], v[208:211], v[28:31]
	v_mfma_f32_16x16x32_bf16 v[20:23], v[168:171], v[208:211], v[20:23]
	v_mfma_f32_16x16x32_bf16 v[12:15], v[160:163], v[244:247], v[12:15]
	v_mfma_f32_16x16x32_bf16 v[4:7], v[168:171], v[244:247], v[4:7]
	v_mfma_f32_16x16x32_bf16 v[56:59], v[172:175], v[188:191], v[56:59]
	v_mfma_f32_16x16x32_bf16 v[48:51], v[180:183], v[188:191], v[48:51]
	v_mfma_f32_16x16x32_bf16 v[40:43], v[172:175], v[196:199], v[40:43]
	v_mfma_f32_16x16x32_bf16 v[32:35], v[180:183], v[196:199], v[32:35]
	v_mfma_f32_16x16x32_bf16 v[24:27], v[172:175], v[204:207], v[24:27]
	v_mfma_f32_16x16x32_bf16 v[16:19], v[180:183], v[204:207], v[16:19]
	v_mfma_f32_16x16x32_bf16 v[8:11], v[172:175], v[234:237], v[8:11]
	v_mfma_f32_16x16x32_bf16 v[0:3], v[180:183], v[234:237], v[0:3]
	v_mfma_f32_16x16x32_bf16 v[56:59], v[176:179], v[192:195], v[56:59]
	v_mfma_f32_16x16x32_bf16 v[48:51], v[184:187], v[192:195], v[48:51]
	v_mfma_f32_16x16x32_bf16 v[40:43], v[176:179], v[200:203], v[40:43]
	v_mfma_f32_16x16x32_bf16 v[32:35], v[184:187], v[200:203], v[32:35]
	v_mfma_f32_16x16x32_bf16 v[24:27], v[176:179], v[208:211], v[24:27]
	v_mfma_f32_16x16x32_bf16 v[16:19], v[184:187], v[208:211], v[16:19]
	v_mfma_f32_16x16x32_bf16 v[8:11], v[176:179], v[244:247], v[8:11]
	v_mfma_f32_16x16x32_bf16 v[0:3], v[184:187], v[244:247], v[0:3]
	s_barrier
	s_add_i32 s47, 0, 0x18000
	v_add_u32_e32 v154, s47, v156
	s_add_i32 s48, 0, 0x1c000
	ds_read_b128 v[138:141], v154
	ds_read_b128 v[160:163], v154 offset:1024
	ds_read_b128 v[164:167], v154 offset:2048
	ds_read_b128 v[168:171], v154 offset:3072
	v_add_u32_e32 v154, s48, v156
	ds_read_b128 v[172:175], v154
	ds_read_b128 v[176:179], v154 offset:1024
	ds_read_b128 v[180:183], v154 offset:2048
	ds_read_b128 v[184:187], v154 offset:3072
	s_add_u32 s26, s26, 0x40000
	s_addc_u32 s27, s27, 0
	s_mov_b32 m0, s36
	v_lshl_add_u64 v[250:251], s[26:27], 0, v[132:133]
	ds_read_b128 v[188:191], v158 offset:32768
	ds_read_b128 v[192:195], v158 offset:33792
	ds_read_b128 v[196:199], v158 offset:34816
	ds_read_b128 v[200:203], v158 offset:35840
	ds_read_b128 v[204:207], v158 offset:36864
	ds_read_b128 v[208:211], v158 offset:37888
	ds_read_b128 v[234:237], v158 offset:38912
	ds_read_b128 v[244:247], v158 offset:39936
	global_load_lds_dwordx4 v[250:251], off
	v_lshl_add_u64 v[250:251], s[26:27], 0, v[130:131]
	s_mov_b32 m0, s37
	s_nop 0
	global_load_lds_dwordx4 v[250:251], off
	s_waitcnt vmcnt(8)
	s_waitcnt lgkmcnt(0)
	s_barrier
	s_waitcnt lgkmcnt(0)
	v_mfma_f32_16x16x32_bf16 v[124:127], v[138:141], v[188:191], v[124:127]
	v_mfma_f32_16x16x32_bf16 v[116:119], v[164:167], v[188:191], v[116:119]
	v_mfma_f32_16x16x32_bf16 v[108:111], v[138:141], v[196:199], v[108:111]
	v_mfma_f32_16x16x32_bf16 v[100:103], v[164:167], v[196:199], v[100:103]
	v_mfma_f32_16x16x32_bf16 v[92:95], v[138:141], v[204:207], v[92:95]
	v_mfma_f32_16x16x32_bf16 v[84:87], v[164:167], v[204:207], v[84:87]
	v_mfma_f32_16x16x32_bf16 v[76:79], v[138:141], v[234:237], v[76:79]
	v_mfma_f32_16x16x32_bf16 v[68:71], v[164:167], v[234:237], v[68:71]
	v_mfma_f32_16x16x32_bf16 v[124:127], v[160:163], v[192:195], v[124:127]
	v_mfma_f32_16x16x32_bf16 v[116:119], v[168:171], v[192:195], v[116:119]
	v_mfma_f32_16x16x32_bf16 v[108:111], v[160:163], v[200:203], v[108:111]
	v_mfma_f32_16x16x32_bf16 v[100:103], v[168:171], v[200:203], v[100:103]
	v_mfma_f32_16x16x32_bf16 v[92:95], v[160:163], v[208:211], v[92:95]
	v_mfma_f32_16x16x32_bf16 v[84:87], v[168:171], v[208:211], v[84:87]
	v_mfma_f32_16x16x32_bf16 v[76:79], v[160:163], v[244:247], v[76:79]
	v_mfma_f32_16x16x32_bf16 v[68:71], v[168:171], v[244:247], v[68:71]
	v_mfma_f32_16x16x32_bf16 v[120:123], v[172:175], v[188:191], v[120:123]
	v_mfma_f32_16x16x32_bf16 v[112:115], v[180:183], v[188:191], v[112:115]
	v_mfma_f32_16x16x32_bf16 v[104:107], v[172:175], v[196:199], v[104:107]
	v_mfma_f32_16x16x32_bf16 v[96:99], v[180:183], v[196:199], v[96:99]
	v_mfma_f32_16x16x32_bf16 v[88:91], v[172:175], v[204:207], v[88:91]
	v_mfma_f32_16x16x32_bf16 v[80:83], v[180:183], v[204:207], v[80:83]
	v_mfma_f32_16x16x32_bf16 v[72:75], v[172:175], v[234:237], v[72:75]
	v_mfma_f32_16x16x32_bf16 v[64:67], v[180:183], v[234:237], v[64:67]
	v_mfma_f32_16x16x32_bf16 v[120:123], v[176:179], v[192:195], v[120:123]
	v_mfma_f32_16x16x32_bf16 v[112:115], v[184:187], v[192:195], v[112:115]
	v_mfma_f32_16x16x32_bf16 v[104:107], v[176:179], v[200:203], v[104:107]
	v_mfma_f32_16x16x32_bf16 v[96:99], v[184:187], v[200:203], v[96:99]
	v_mfma_f32_16x16x32_bf16 v[88:91], v[176:179], v[208:211], v[88:91]
	v_mfma_f32_16x16x32_bf16 v[80:83], v[184:187], v[208:211], v[80:83]
	v_mfma_f32_16x16x32_bf16 v[72:75], v[176:179], v[244:247], v[72:75]
	v_mfma_f32_16x16x32_bf16 v[64:67], v[184:187], v[244:247], v[64:67]
	s_barrier
; #define PG8_STAGE(bufoff, gbase, voff) do { _Pragma("unroll") for (int _i = 0; _i < 2; ++_i) \
;         __builtin_amdgcn_global_load_lds((const unsigned*)((const char*)(gbase) + (voff)[_i]), (PG8_LAS unsigned*)(lds + (bufoff) + ldsw + _i * 8192), 16, 0, 0); } while (0)
; #define PG8_LDA(dst, b, h) do { _Pragma("unroll") for (int m = 0; m < 4; ++m) _Pragma("unroll") for (int k = 0; k < 2; ++k) dst[m][k] = *(const PG8_LAS bf16x8*)(lds + PG8_SA(b, h) + aoff + m * 2048 + k * 1024); } while (0)
; #define PG8_MMA(ai, bj, At, Bt) do { __builtin_amdgcn_s_setprio(1); _Pragma("unroll") for (int m = 0; m < 4; ++m) _Pragma("unroll") for (int n = 0; n < 2; ++n) _Pragma("unroll") for (int k = 0; k < 2; ++k) \
;         acc[ai][bj][m][n] = __builtin_amdgcn_mfma_f32_16x16x32_bf16(Bt[n][k], At[m][k], acc[ai][bj][m][n], 0, 0, 0); __builtin_amdgcn_s_setprio(0); } while (0)
; #define PG8_WAIT_V(n) asm volatile("s_waitcnt vmcnt(" #n ")" ::: "memory")
; #define PG8_WAIT_L(n) asm volatile("s_waitcnt lgkmcnt(" #n ")" ::: "memory")
; #define PG8_BAR __builtin_amdgcn_s_barrier()
; #define PG8_SCHED __builtin_amdgcn_sched_barrier(0)
; template <class Epi, class Sched, bool ALIGN_EPI = false, bool SP2 = false>
; __device__ __forceinline__ void gemm_phase(PG8_LAS unsigned char* lds, const Gemm g, const Sched& S, const Epi& E) {
;     ...
;             PG8_LDA(At, 1, 1); PG8_STAGE(PG8_SB(1, 0), b3, voffB); PG8_STAGE(PG8_SB(1, 1), b3 + hstep, voffB); PG8_STAGE(PG8_SA(1, 0), a3, voffA);
;             PG8_WAIT_V(8); PG8_WAIT_L(0); PG8_BAR; PG8_MMA(1, 0, At, B0); PG8_MMA(1, 1, At, B1); PG8_BAR; PG8_SCHED;
;     ...
;         if constexpr (ALIGN_EPI) { if (wr == 0) PG8_BAR; }
	s_add_i32 s26, s47, s31
	v_lshl_add_u64 v[142:143], v[142:143], 0, s[52:53]
	s_mov_b32 m0, s26
	ds_read_b128 v[188:191], v158 offset:49152
	ds_read_b128 v[192:195], v158 offset:50176
	ds_read_b128 v[196:199], v158 offset:51200
	ds_read_b128 v[200:203], v158 offset:52224
	ds_read_b128 v[204:207], v158 offset:53248
	ds_read_b128 v[208:211], v158 offset:54272
	ds_read_b128 v[234:237], v158 offset:55296
	ds_read_b128 v[244:247], v158 offset:56320
	global_load_lds_dwordx4 v[142:143], off
	s_add_i32 m0, s26, 0x2000
	s_add_u32 s24, s24, 0x40080
	v_lshl_add_u64 v[142:143], v[214:215], 0, s[52:53]
	s_addc_u32 s25, s25, 0
	s_add_i32 s26, s48, s31
	global_load_lds_dwordx4 v[142:143], off
	v_lshl_add_u64 v[142:143], s[24:25], 0, v[144:145]
	s_mov_b32 m0, s26
	s_nop 0
	global_load_lds_dwordx4 v[142:143], off
	v_lshl_add_u64 v[142:143], s[24:25], 0, v[128:129]
	s_add_i32 m0, s26, 0x2000
	s_nop 0
	global_load_lds_dwordx4 v[142:143], off
	v_lshl_add_u64 v[142:143], v[238:239], 0, s[52:53]
	s_mov_b32 m0, s33
	s_nop 0
	global_load_lds_dwordx4 v[142:143], off
	v_lshl_add_u64 v[142:143], v[248:249], 0, s[52:53]
	s_mov_b32 m0, s38
	s_nop 0
	global_load_lds_dwordx4 v[142:143], off
	s_waitcnt vmcnt(8)
	s_waitcnt lgkmcnt(0)
	s_barrier
	s_waitcnt lgkmcnt(0)
	v_mfma_f32_16x16x32_bf16 v[60:63], v[138:141], v[188:191], v[60:63]
	v_mfma_f32_16x16x32_bf16 v[52:55], v[164:167], v[188:191], v[52:55]
	v_mfma_f32_16x16x32_bf16 v[44:47], v[138:141], v[196:199], v[44:47]
	v_mfma_f32_16x16x32_bf16 v[36:39], v[164:167], v[196:199], v[36:39]
	v_mfma_f32_16x16x32_bf16 v[28:31], v[138:141], v[204:207], v[28:31]
	v_mfma_f32_16x16x32_bf16 v[20:23], v[164:167], v[204:207], v[20:23]
	v_mfma_f32_16x16x32_bf16 v[12:15], v[138:141], v[234:237], v[12:15]
	v_mfma_f32_16x16x32_bf16 v[4:7], v[164:167], v[234:237], v[4:7]
	v_mfma_f32_16x16x32_bf16 v[60:63], v[160:163], v[192:195], v[60:63]
	v_mfma_f32_16x16x32_bf16 v[52:55], v[168:171], v[192:195], v[52:55]
	v_mfma_f32_16x16x32_bf16 v[44:47], v[160:163], v[200:203], v[44:47]
	v_mfma_f32_16x16x32_bf16 v[36:39], v[168:171], v[200:203], v[36:39]
	v_mfma_f32_16x16x32_bf16 v[28:31], v[160:163], v[208:211], v[28:31]
	v_mfma_f32_16x16x32_bf16 v[20:23], v[168:171], v[208:211], v[20:23]
	v_mfma_f32_16x16x32_bf16 v[12:15], v[160:163], v[244:247], v[12:15]
	v_mfma_f32_16x16x32_bf16 v[4:7], v[168:171], v[244:247], v[4:7]
	v_mfma_f32_16x16x32_bf16 v[56:59], v[172:175], v[188:191], v[56:59]
	v_mfma_f32_16x16x32_bf16 v[48:51], v[180:183], v[188:191], v[48:51]
	v_mfma_f32_16x16x32_bf16 v[40:43], v[172:175], v[196:199], v[40:43]
	v_mfma_f32_16x16x32_bf16 v[32:35], v[180:183], v[196:199], v[32:35]
	v_mfma_f32_16x16x32_bf16 v[24:27], v[172:175], v[204:207], v[24:27]
	v_mfma_f32_16x16x32_bf16 v[16:19], v[180:183], v[204:207], v[16:19]
	v_mfma_f32_16x16x32_bf16 v[8:11], v[172:175], v[234:237], v[8:11]
	v_mfma_f32_16x16x32_bf16 v[0:3], v[180:183], v[234:237], v[0:3]
	v_mfma_f32_16x16x32_bf16 v[56:59], v[176:179], v[192:195], v[56:59]
	v_mfma_f32_16x16x32_bf16 v[48:51], v[184:187], v[192:195], v[48:51]
	v_mfma_f32_16x16x32_bf16 v[40:43], v[176:179], v[200:203], v[40:43]
	v_mfma_f32_16x16x32_bf16 v[32:35], v[184:187], v[200:203], v[32:35]
	v_mfma_f32_16x16x32_bf16 v[24:27], v[176:179], v[208:211], v[24:27]
	v_mfma_f32_16x16x32_bf16 v[16:19], v[184:187], v[208:211], v[16:19]
	v_mfma_f32_16x16x32_bf16 v[8:11], v[176:179], v[244:247], v[8:11]
	v_mfma_f32_16x16x32_bf16 v[0:3], v[184:187], v[244:247], v[0:3]
	s_barrier
	s_add_i32 s46, s46, 2
	s_add_u32 s44, s44, 0x100
	s_addc_u32 s45, s45, 0
	s_add_u32 s22, s22, 0x100
	s_addc_u32 s23, s23, 0
	s_cmp_gt_u32 s46, 13
	s_cbranch_scc0 .LBB0_1295
	s_and_b64 vcc, exec, s[12:13]
	s_cbranch_vccz .LBB0_1298
	s_barrier

; #define PG8_STAGE(bufoff, gbase, voff) do { _Pragma("unroll") for (int _i = 0; _i < 2; ++_i) \
;         __builtin_amdgcn_global_load_lds((const unsigned*)((const char*)(gbase) + (voff)[_i]), (PG8_LAS unsigned*)(lds + (bufoff) + ldsw + _i * 8192), 16, 0, 0); } while (0)
; #define PG8_LDA(dst, b, h) do { _Pragma("unroll") for (int m = 0; m < 4; ++m) _Pragma("unroll") for (int k = 0; k < 2; ++k) dst[m][k] = *(const PG8_LAS bf16x8*)(lds + PG8_SA(b, h) + aoff + m * 2048 + k * 1024); } while (0)
; #define PG8_LDB(dst, b, h) do { _Pragma("unroll") for (int n = 0; n < 2; ++n) _Pragma("unroll") for (int k = 0; k < 2; ++k) dst[n][k] = *(const PG8_LAS bf16x8*)(lds + PG8_SB(b, h) + boff + n * 2048 + k * 1024); } while (0)
; #define PG8_MMA(ai, bj, At, Bt) do { __builtin_amdgcn_s_setprio(1); _Pragma("unroll") for (int m = 0; m < 4; ++m) _Pragma("unroll") for (int n = 0; n < 2; ++n) _Pragma("unroll") for (int k = 0; k < 2; ++k) \
;         acc[ai][bj][m][n] = __builtin_amdgcn_mfma_f32_16x16x32_bf16(Bt[n][k], At[m][k], acc[ai][bj][m][n], 0, 0, 0); __builtin_amdgcn_s_setprio(0); } while (0)
; #define PG8_WAIT_V(n) asm volatile("s_waitcnt vmcnt(" #n ")" ::: "memory")
; #define PG8_WAIT_L(n) asm volatile("s_waitcnt lgkmcnt(" #n ")" ::: "memory")
; #define PG8_BAR __builtin_amdgcn_s_barrier()
; #define PG8_SCHED __builtin_amdgcn_sched_barrier(0)
; template <class Epi, class Sched, bool ALIGN_EPI = false, bool SP2 = false>
; __device__ __forceinline__ void gemm_phase(PG8_LAS unsigned char* lds, const Gemm g, const Sched& S, const Epi& E) {
;     ...
;             const bool last = (t == nt - 2);
;             const char* a1 = cA + (size_t)(t + 1) * kstep;
;             const char* a2 = last ? nA : cA + (size_t)(t + 2) * kstep; const char* b2 = last ? nB : cB + (size_t)(t + 2) * kstep;
;             const char* a3 = a2 + kstep; const char* b3 = b2 + kstep;
;             if (last && has_next) S.a_ready(nxt);
;             if constexpr (SP2) {
;             PG8_LDB(B0, 0, 0); PG8_LDB(B1, 0, 1); PG8_SCHED; PG8_LDA(At, 0, 0); PG8_STAGE(PG8_SA(1, 1), a1 + hstep, voffA);
;             PG8_WAIT_V(8); PG8_WAIT_L(0); PG8_BAR; PG8_MMA(0, 0, At, B0); PG8_MMA(0, 1, At, B1); PG8_BAR; PG8_SCHED;
;             PG8_LDA(At, 0, 1); PG8_STAGE(PG8_SB(0, 0), b2, voffB); PG8_STAGE(PG8_SB(0, 1), b2 + hstep, voffB); PG8_STAGE(PG8_SA(0, 0), a2, voffA);
.LBB0_1378:
	s_add_i32 s59, s34, 2
	s_add_u32 s12, s30, 0x100
	s_addc_u32 s13, s31, 0
	s_add_i32 s60, 0, 0x10000
	s_cmp_eq_u32 s25, s34
	s_cselect_b32 s37, s23, s13
	s_cselect_b32 s36, s22, s12
	s_cselect_b32 s35, s21, s58
	s_cselect_b32 s34, s20, s57
	s_add_i32 s61, 0, 0x14000
	v_add_u32_e32 v140, s60, v234
	v_add_u32_e32 v178, s61, v234
	s_waitcnt lgkmcnt(0)
	ds_read_b128 v[128:131], v140
	ds_read_b128 v[132:135], v140 offset:1024
	ds_read_b128 v[136:139], v140 offset:2048
	ds_read_b128 v[140:143], v140 offset:3072
	ds_read_b128 v[166:169], v178
	ds_read_b128 v[170:173], v178 offset:1024
	ds_read_b128 v[174:177], v178 offset:2048
	ds_read_b128 v[178:181], v178 offset:3072
	v_lshl_add_u64 v[210:211], s[30:31], 0, v[164:165]
	s_add_i32 m0, s45, 0xc000
	ds_read_b128 v[182:185], v236
	ds_read_b128 v[186:189], v236 offset:1024
	ds_read_b128 v[190:193], v236 offset:2048
	ds_read_b128 v[194:197], v236 offset:3072
	ds_read_b128 v[198:201], v236 offset:4096
	ds_read_b128 v[202:205], v236 offset:5120
	ds_read_b128 v[206:209], v236 offset:6144
	ds_read_b128 v[244:247], v236 offset:7168
	global_load_lds_dwordx4 v[210:211], off
	v_lshl_add_u64 v[210:211], s[30:31], 0, v[162:163]
	s_add_i32 m0, s45, 0xe000
	s_nop 0
	global_load_lds_dwordx4 v[210:211], off
	s_waitcnt vmcnt(8)
	s_waitcnt lgkmcnt(0)
	s_barrier
	s_waitcnt lgkmcnt(0)
	v_mfma_f32_16x16x32_bf16 v[124:127], v[128:131], v[182:185], v[124:127]
	v_mfma_f32_16x16x32_bf16 v[120:123], v[136:139], v[182:185], v[120:123]
	v_mfma_f32_16x16x32_bf16 v[116:119], v[128:131], v[190:193], v[116:119]
	v_mfma_f32_16x16x32_bf16 v[112:115], v[136:139], v[190:193], v[112:115]
	v_mfma_f32_16x16x32_bf16 v[108:111], v[128:131], v[198:201], v[108:111]
	v_mfma_f32_16x16x32_bf16 v[104:107], v[136:139], v[198:201], v[104:107]
	v_mfma_f32_16x16x32_bf16 v[100:103], v[128:131], v[206:209], v[100:103]
	v_mfma_f32_16x16x32_bf16 v[96:99], v[136:139], v[206:209], v[96:99]
	v_mfma_f32_16x16x32_bf16 v[124:127], v[132:135], v[186:189], v[124:127]
	v_mfma_f32_16x16x32_bf16 v[120:123], v[140:143], v[186:189], v[120:123]
	v_mfma_f32_16x16x32_bf16 v[116:119], v[132:135], v[194:197], v[116:119]
	v_mfma_f32_16x16x32_bf16 v[112:115], v[140:143], v[194:197], v[112:115]
	v_mfma_f32_16x16x32_bf16 v[108:111], v[132:135], v[202:205], v[108:111]
	v_mfma_f32_16x16x32_bf16 v[104:107], v[140:143], v[202:205], v[104:107]
	v_mfma_f32_16x16x32_bf16 v[100:103], v[132:135], v[244:247], v[100:103]
	v_mfma_f32_16x16x32_bf16 v[96:99], v[140:143], v[244:247], v[96:99]
	v_mfma_f32_16x16x32_bf16 v[92:95], v[166:169], v[182:185], v[92:95]
	v_mfma_f32_16x16x32_bf16 v[88:91], v[174:177], v[182:185], v[88:91]
	v_mfma_f32_16x16x32_bf16 v[84:87], v[166:169], v[190:193], v[84:87]
	v_mfma_f32_16x16x32_bf16 v[80:83], v[174:177], v[190:193], v[80:83]
	v_mfma_f32_16x16x32_bf16 v[76:79], v[166:169], v[198:201], v[76:79]
	v_mfma_f32_16x16x32_bf16 v[72:75], v[174:177], v[198:201], v[72:75]
	v_mfma_f32_16x16x32_bf16 v[68:71], v[166:169], v[206:209], v[68:71]
	v_mfma_f32_16x16x32_bf16 v[64:67], v[174:177], v[206:209], v[64:67]
	v_mfma_f32_16x16x32_bf16 v[92:95], v[170:173], v[186:189], v[92:95]
	v_mfma_f32_16x16x32_bf16 v[88:91], v[178:181], v[186:189], v[88:91]
	v_mfma_f32_16x16x32_bf16 v[84:87], v[170:173], v[194:197], v[84:87]
	v_mfma_f32_16x16x32_bf16 v[80:83], v[178:181], v[194:197], v[80:83]
	v_mfma_f32_16x16x32_bf16 v[76:79], v[170:173], v[202:205], v[76:79]
	v_mfma_f32_16x16x32_bf16 v[72:75], v[178:181], v[202:205], v[72:75]
	v_mfma_f32_16x16x32_bf16 v[68:71], v[170:173], v[244:247], v[68:71]
	v_mfma_f32_16x16x32_bf16 v[64:67], v[178:181], v[244:247], v[64:67]
	s_barrier
	s_add_i32 s30, s60, s44
	v_lshl_add_u64 v[210:211], s[34:35], 0, v[144:145]
	s_mov_b32 m0, s30
	ds_read_b128 v[182:185], v236 offset:16384
	ds_read_b128 v[186:189], v236 offset:17408
	ds_read_b128 v[190:193], v236 offset:18432
	ds_read_b128 v[194:197], v236 offset:19456
	ds_read_b128 v[198:201], v236 offset:20480
	ds_read_b128 v[202:205], v236 offset:21504
	ds_read_b128 v[206:209], v236 offset:22528
	ds_read_b128 v[244:247], v236 offset:23552
	global_load_lds_dwordx4 v[210:211], off
	s_add_i32 m0, s30, 0x2000
	s_add_u32 s30, s34, 0xb0000
	v_lshl_add_u64 v[214:215], s[34:35], 0, v[158:159]
	s_addc_u32 s31, s35, 0
	s_add_i32 s60, s61, s44
	global_load_lds_dwordx4 v[214:215], off
	v_lshl_add_u64 v[248:249], s[30:31], 0, v[144:145]
	s_mov_b32 m0, s60
	v_lshl_add_u64 v[250:251], s[36:37], 0, v[156:157]
	global_load_lds_dwordx4 v[248:249], off
	v_lshl_add_u64 v[248:249], s[30:31], 0, v[158:159]
	s_add_i32 m0, s60, 0x2000
	s_nop 0
	global_load_lds_dwordx4 v[248:249], off
	v_lshl_add_u64 v[248:249], s[36:37], 0, v[154:155]
	s_mov_b32 m0, s45
	s_nop 0
	global_load_lds_dwordx4 v[248:249], off
	s_mov_b32 m0, s46
	s_nop 0
	global_load_lds_dwordx4 v[250:251], off
	s_waitcnt vmcnt(8)
	s_waitcnt lgkmcnt(0)
	s_barrier
; #define PG8_STAGE(bufoff, gbase, voff) do { _Pragma("unroll") for (int _i = 0; _i < 2; ++_i) \
;         __builtin_amdgcn_global_load_lds((const unsigned*)((const char*)(gbase) + (voff)[_i]), (PG8_LAS unsigned*)(lds + (bufoff) + ldsw + _i * 8192), 16, 0, 0); } while (0)
; #define PG8_LDA(dst, b, h) do { _Pragma("unroll") for (int m = 0; m < 4; ++m) _Pragma("unroll") for (int k = 0; k < 2; ++k) dst[m][k] = *(const PG8_LAS bf16x8*)(lds + PG8_SA(b, h) + aoff + m * 2048 + k * 1024); } while (0)
; #define PG8_LDB(dst, b, h) do { _Pragma("unroll") for (int n = 0; n < 2; ++n) _Pragma("unroll") for (int k = 0; k < 2; ++k) dst[n][k] = *(const PG8_LAS bf16x8*)(lds + PG8_SB(b, h) + boff + n * 2048 + k * 1024); } while (0)
; #define PG8_MMA(ai, bj, At, Bt) do { __builtin_amdgcn_s_setprio(1); _Pragma("unroll") for (int m = 0; m < 4; ++m) _Pragma("unroll") for (int n = 0; n < 2; ++n) _Pragma("unroll") for (int k = 0; k < 2; ++k) \
;         acc[ai][bj][m][n] = __builtin_amdgcn_mfma_f32_16x16x32_bf16(Bt[n][k], At[m][k], acc[ai][bj][m][n], 0, 0, 0); __builtin_amdgcn_s_setprio(0); } while (0)
; #define PG8_WAIT_V(n) asm volatile("s_waitcnt vmcnt(" #n ")" ::: "memory")
; #define PG8_WAIT_L(n) asm volatile("s_waitcnt lgkmcnt(" #n ")" ::: "memory")
; #define PG8_BAR __builtin_amdgcn_s_barrier()
; #define PG8_SCHED __builtin_amdgcn_sched_barrier(0)
; template <class Epi, class Sched, bool ALIGN_EPI = false, bool SP2 = false>
; __device__ __forceinline__ void gemm_phase(PG8_LAS unsigned char* lds, const Gemm g, const Sched& S, const Epi& E) {
;     ...
;             PG8_WAIT_V(8); PG8_WAIT_L(0); PG8_BAR; PG8_MMA(1, 0, At, B0); PG8_MMA(1, 1, At, B1); PG8_BAR; PG8_SCHED;
;             PG8_LDB(B0, 1, 0); PG8_LDB(B1, 1, 1); PG8_SCHED; PG8_LDA(At, 1, 0); PG8_STAGE(PG8_SA(0, 1), a2 + hstep, voffA);
;             PG8_WAIT_V(8); PG8_WAIT_L(0); PG8_BAR; PG8_MMA(0, 0, At, B0); PG8_MMA(0, 1, At, B1); PG8_BAR; PG8_SCHED;
	s_waitcnt lgkmcnt(0)
	v_mfma_f32_16x16x32_bf16 v[60:63], v[128:131], v[182:185], v[60:63]
	v_mfma_f32_16x16x32_bf16 v[56:59], v[136:139], v[182:185], v[56:59]
	v_mfma_f32_16x16x32_bf16 v[52:55], v[128:131], v[190:193], v[52:55]
	v_mfma_f32_16x16x32_bf16 v[48:51], v[136:139], v[190:193], v[48:51]
	v_mfma_f32_16x16x32_bf16 v[44:47], v[128:131], v[198:201], v[44:47]
	v_mfma_f32_16x16x32_bf16 v[40:43], v[136:139], v[198:201], v[40:43]
	v_mfma_f32_16x16x32_bf16 v[36:39], v[128:131], v[206:209], v[36:39]
	v_mfma_f32_16x16x32_bf16 v[32:35], v[136:139], v[206:209], v[32:35]
	v_mfma_f32_16x16x32_bf16 v[60:63], v[132:135], v[186:189], v[60:63]
	v_mfma_f32_16x16x32_bf16 v[56:59], v[140:143], v[186:189], v[56:59]
	v_mfma_f32_16x16x32_bf16 v[52:55], v[132:135], v[194:197], v[52:55]
	v_mfma_f32_16x16x32_bf16 v[48:51], v[140:143], v[194:197], v[48:51]
	v_mfma_f32_16x16x32_bf16 v[44:47], v[132:135], v[202:205], v[44:47]
	v_mfma_f32_16x16x32_bf16 v[40:43], v[140:143], v[202:205], v[40:43]
	v_mfma_f32_16x16x32_bf16 v[36:39], v[132:135], v[244:247], v[36:39]
	v_mfma_f32_16x16x32_bf16 v[32:35], v[140:143], v[244:247], v[32:35]
	v_mfma_f32_16x16x32_bf16 v[28:31], v[166:169], v[182:185], v[28:31]
	v_mfma_f32_16x16x32_bf16 v[24:27], v[174:177], v[182:185], v[24:27]
	v_mfma_f32_16x16x32_bf16 v[20:23], v[166:169], v[190:193], v[20:23]
	v_mfma_f32_16x16x32_bf16 v[16:19], v[174:177], v[190:193], v[16:19]
	v_mfma_f32_16x16x32_bf16 v[12:15], v[166:169], v[198:201], v[12:15]
	v_mfma_f32_16x16x32_bf16 v[8:11], v[174:177], v[198:201], v[8:11]
	v_mfma_f32_16x16x32_bf16 v[4:7], v[166:169], v[206:209], v[4:7]
	v_mfma_f32_16x16x32_bf16 v[0:3], v[174:177], v[206:209], v[0:3]
	v_mfma_f32_16x16x32_bf16 v[28:31], v[170:173], v[186:189], v[28:31]
	v_mfma_f32_16x16x32_bf16 v[24:27], v[178:181], v[186:189], v[24:27]
	v_mfma_f32_16x16x32_bf16 v[20:23], v[170:173], v[194:197], v[20:23]
	v_mfma_f32_16x16x32_bf16 v[16:19], v[178:181], v[194:197], v[16:19]
	v_mfma_f32_16x16x32_bf16 v[12:15], v[170:173], v[202:205], v[12:15]
	v_mfma_f32_16x16x32_bf16 v[8:11], v[178:181], v[202:205], v[8:11]
	v_mfma_f32_16x16x32_bf16 v[4:7], v[170:173], v[244:247], v[4:7]
	v_mfma_f32_16x16x32_bf16 v[0:3], v[178:181], v[244:247], v[0:3]
	s_barrier
	s_add_i32 s60, 0, 0x18000
	s_add_i32 s61, 0, 0x1c000
	v_add_u32_e32 v140, s60, v234
	v_add_u32_e32 v178, s61, v234
	ds_read_b128 v[128:131], v140
	ds_read_b128 v[132:135], v140 offset:1024
	ds_read_b128 v[136:139], v140 offset:2048
	ds_read_b128 v[140:143], v140 offset:3072
	ds_read_b128 v[166:169], v178
	ds_read_b128 v[170:173], v178 offset:1024
	ds_read_b128 v[174:177], v178 offset:2048
	ds_read_b128 v[178:181], v178 offset:3072
	s_add_u32 s30, s36, 0xb0000
	s_addc_u32 s31, s37, 0
	s_mov_b32 m0, s47
	v_lshl_add_u64 v[252:253], s[30:31], 0, v[154:155]
	ds_read_b128 v[182:185], v236 offset:32768
	ds_read_b128 v[186:189], v236 offset:33792
	ds_read_b128 v[190:193], v236 offset:34816
	ds_read_b128 v[194:197], v236 offset:35840
	ds_read_b128 v[198:201], v236 offset:36864
	ds_read_b128 v[202:205], v236 offset:37888
	ds_read_b128 v[206:209], v236 offset:38912
	ds_read_b128 v[244:247], v236 offset:39936
	global_load_lds_dwordx4 v[252:253], off
	v_lshl_add_u64 v[252:253], s[30:31], 0, v[156:157]
	s_mov_b32 m0, s48
	s_nop 0
	global_load_lds_dwordx4 v[252:253], off
	s_waitcnt vmcnt(8)
	s_waitcnt lgkmcnt(0)
	s_barrier
	s_waitcnt lgkmcnt(0)
	v_mfma_f32_16x16x32_bf16 v[124:127], v[128:131], v[182:185], v[124:127]
	v_mfma_f32_16x16x32_bf16 v[120:123], v[136:139], v[182:185], v[120:123]
	v_mfma_f32_16x16x32_bf16 v[116:119], v[128:131], v[190:193], v[116:119]
	v_mfma_f32_16x16x32_bf16 v[112:115], v[136:139], v[190:193], v[112:115]
	v_mfma_f32_16x16x32_bf16 v[108:111], v[128:131], v[198:201], v[108:111]
	v_mfma_f32_16x16x32_bf16 v[104:107], v[136:139], v[198:201], v[104:107]
	v_mfma_f32_16x16x32_bf16 v[100:103], v[128:131], v[206:209], v[100:103]
	v_mfma_f32_16x16x32_bf16 v[96:99], v[136:139], v[206:209], v[96:99]
	v_mfma_f32_16x16x32_bf16 v[124:127], v[132:135], v[186:189], v[124:127]
	v_mfma_f32_16x16x32_bf16 v[120:123], v[140:143], v[186:189], v[120:123]
	v_mfma_f32_16x16x32_bf16 v[116:119], v[132:135], v[194:197], v[116:119]
	v_mfma_f32_16x16x32_bf16 v[112:115], v[140:143], v[194:197], v[112:115]
	v_mfma_f32_16x16x32_bf16 v[108:111], v[132:135], v[202:205], v[108:111]
	v_mfma_f32_16x16x32_bf16 v[104:107], v[140:143], v[202:205], v[104:107]
	v_mfma_f32_16x16x32_bf16 v[100:103], v[132:135], v[244:247], v[100:103]
	v_mfma_f32_16x16x32_bf16 v[96:99], v[140:143], v[244:247], v[96:99]
	v_mfma_f32_16x16x32_bf16 v[92:95], v[166:169], v[182:185], v[92:95]
	v_mfma_f32_16x16x32_bf16 v[88:91], v[174:177], v[182:185], v[88:91]
	v_mfma_f32_16x16x32_bf16 v[84:87], v[166:169], v[190:193], v[84:87]
	v_mfma_f32_16x16x32_bf16 v[80:83], v[174:177], v[190:193], v[80:83]
	v_mfma_f32_16x16x32_bf16 v[76:79], v[166:169], v[198:201], v[76:79]
	v_mfma_f32_16x16x32_bf16 v[72:75], v[174:177], v[198:201], v[72:75]
	v_mfma_f32_16x16x32_bf16 v[68:71], v[166:169], v[206:209], v[68:71]
	v_mfma_f32_16x16x32_bf16 v[64:67], v[174:177], v[206:209], v[64:67]
	v_mfma_f32_16x16x32_bf16 v[92:95], v[170:173], v[186:189], v[92:95]
	v_mfma_f32_16x16x32_bf16 v[88:91], v[178:181], v[186:189], v[88:91]
	v_mfma_f32_16x16x32_bf16 v[84:87], v[170:173], v[194:197], v[84:87]
	v_mfma_f32_16x16x32_bf16 v[80:83], v[178:181], v[194:197], v[80:83]
	v_mfma_f32_16x16x32_bf16 v[76:79], v[170:173], v[202:205], v[76:79]
	v_mfma_f32_16x16x32_bf16 v[72:75], v[178:181], v[202:205], v[72:75]
	v_mfma_f32_16x16x32_bf16 v[68:71], v[170:173], v[244:247], v[68:71]
	v_mfma_f32_16x16x32_bf16 v[64:67], v[178:181], v[244:247], v[64:67]
	s_barrier
; #define PG8_STAGE(bufoff, gbase, voff) do { _Pragma("unroll") for (int _i = 0; _i < 2; ++_i) \
;         __builtin_amdgcn_global_load_lds((const unsigned*)((const char*)(gbase) + (voff)[_i]), (PG8_LAS unsigned*)(lds + (bufoff) + ldsw + _i * 8192), 16, 0, 0); } while (0)
; #define PG8_LDA(dst, b, h) do { _Pragma("unroll") for (int m = 0; m < 4; ++m) _Pragma("unroll") for (int k = 0; k < 2; ++k) dst[m][k] = *(const PG8_LAS bf16x8*)(lds + PG8_SA(b, h) + aoff + m * 2048 + k * 1024); } while (0)
; #define PG8_MMA(ai, bj, At, Bt) do { __builtin_amdgcn_s_setprio(1); _Pragma("unroll") for (int m = 0; m < 4; ++m) _Pragma("unroll") for (int n = 0; n < 2; ++n) _Pragma("unroll") for (int k = 0; k < 2; ++k) \
;         acc[ai][bj][m][n] = __builtin_amdgcn_mfma_f32_16x16x32_bf16(Bt[n][k], At[m][k], acc[ai][bj][m][n], 0, 0, 0); __builtin_amdgcn_s_setprio(0); } while (0)
; #define PG8_WAIT_V(n) asm volatile("s_waitcnt vmcnt(" #n ")" ::: "memory")
; #define PG8_WAIT_L(n) asm volatile("s_waitcnt lgkmcnt(" #n ")" ::: "memory")
; #define PG8_BAR __builtin_amdgcn_s_barrier()
; #define PG8_SCHED __builtin_amdgcn_sched_barrier(0)
; template <class Epi, class Sched, bool ALIGN_EPI = false, bool SP2 = false>
; __device__ __forceinline__ void gemm_phase(PG8_LAS unsigned char* lds, const Gemm g, const Sched& S, const Epi& E) {
;     ...
;             PG8_LDA(At, 1, 1); PG8_STAGE(PG8_SB(1, 0), b3, voffB); PG8_STAGE(PG8_SB(1, 1), b3 + hstep, voffB); PG8_STAGE(PG8_SA(1, 0), a3, voffA);
;             PG8_WAIT_V(8); PG8_WAIT_L(0); PG8_BAR; PG8_MMA(1, 0, At, B0); PG8_MMA(1, 1, At, B1); PG8_BAR; PG8_SCHED;
	s_add_i32 s30, s60, s44
	v_lshl_add_u64 v[210:211], v[210:211], 0, s[62:63]
	s_mov_b32 m0, s30
	ds_read_b128 v[182:185], v236 offset:49152
	ds_read_b128 v[186:189], v236 offset:50176
	ds_read_b128 v[190:193], v236 offset:51200
	ds_read_b128 v[194:197], v236 offset:52224
	ds_read_b128 v[198:201], v236 offset:53248
	ds_read_b128 v[202:205], v236 offset:54272
	ds_read_b128 v[206:209], v236 offset:55296
	ds_read_b128 v[244:247], v236 offset:56320
	global_load_lds_dwordx4 v[210:211], off
	s_add_i32 m0, s30, 0x2000
	s_add_u32 s30, s34, 0xb0080
	v_lshl_add_u64 v[210:211], v[214:215], 0, s[62:63]
	s_addc_u32 s31, s35, 0
	s_add_i32 s34, s61, s44
	global_load_lds_dwordx4 v[210:211], off
	v_lshl_add_u64 v[210:211], s[30:31], 0, v[144:145]
	s_mov_b32 m0, s34
	s_nop 0
	global_load_lds_dwordx4 v[210:211], off
	v_lshl_add_u64 v[210:211], s[30:31], 0, v[158:159]
	s_add_i32 m0, s34, 0x2000
	s_nop 0
	global_load_lds_dwordx4 v[210:211], off
	v_lshl_add_u64 v[210:211], v[248:249], 0, s[62:63]
	s_mov_b32 m0, s51
	s_nop 0
	global_load_lds_dwordx4 v[210:211], off
	v_lshl_add_u64 v[210:211], v[250:251], 0, s[62:63]
	s_mov_b32 m0, s52
	s_nop 0
	global_load_lds_dwordx4 v[210:211], off
	s_waitcnt vmcnt(8)
	s_waitcnt lgkmcnt(0)
	s_barrier
	s_waitcnt lgkmcnt(0)
	v_mfma_f32_16x16x32_bf16 v[60:63], v[128:131], v[182:185], v[60:63]
	v_mfma_f32_16x16x32_bf16 v[56:59], v[136:139], v[182:185], v[56:59]
	v_mfma_f32_16x16x32_bf16 v[52:55], v[128:131], v[190:193], v[52:55]
	v_mfma_f32_16x16x32_bf16 v[48:51], v[136:139], v[190:193], v[48:51]
	v_mfma_f32_16x16x32_bf16 v[44:47], v[128:131], v[198:201], v[44:47]
	v_mfma_f32_16x16x32_bf16 v[40:43], v[136:139], v[198:201], v[40:43]
	v_mfma_f32_16x16x32_bf16 v[36:39], v[128:131], v[206:209], v[36:39]
	v_mfma_f32_16x16x32_bf16 v[32:35], v[136:139], v[206:209], v[32:35]
	v_mfma_f32_16x16x32_bf16 v[60:63], v[132:135], v[186:189], v[60:63]
	v_mfma_f32_16x16x32_bf16 v[56:59], v[140:143], v[186:189], v[56:59]
	v_mfma_f32_16x16x32_bf16 v[52:55], v[132:135], v[194:197], v[52:55]
	v_mfma_f32_16x16x32_bf16 v[48:51], v[140:143], v[194:197], v[48:51]
	v_mfma_f32_16x16x32_bf16 v[44:47], v[132:135], v[202:205], v[44:47]
	v_mfma_f32_16x16x32_bf16 v[40:43], v[140:143], v[202:205], v[40:43]
	v_mfma_f32_16x16x32_bf16 v[36:39], v[132:135], v[244:247], v[36:39]
	v_mfma_f32_16x16x32_bf16 v[32:35], v[140:143], v[244:247], v[32:35]
	v_mfma_f32_16x16x32_bf16 v[28:31], v[166:169], v[182:185], v[28:31]
	v_mfma_f32_16x16x32_bf16 v[24:27], v[174:177], v[182:185], v[24:27]
	v_mfma_f32_16x16x32_bf16 v[20:23], v[166:169], v[190:193], v[20:23]
	v_mfma_f32_16x16x32_bf16 v[16:19], v[174:177], v[190:193], v[16:19]
	v_mfma_f32_16x16x32_bf16 v[12:15], v[166:169], v[198:201], v[12:15]
	v_mfma_f32_16x16x32_bf16 v[8:11], v[174:177], v[198:201], v[8:11]
	v_mfma_f32_16x16x32_bf16 v[4:7], v[166:169], v[206:209], v[4:7]
	v_mfma_f32_16x16x32_bf16 v[0:3], v[174:177], v[206:209], v[0:3]
	v_mfma_f32_16x16x32_bf16 v[28:31], v[170:173], v[186:189], v[28:31]
	v_mfma_f32_16x16x32_bf16 v[24:27], v[178:181], v[186:189], v[24:27]
	v_mfma_f32_16x16x32_bf16 v[20:23], v[170:173], v[194:197], v[20:23]
	v_mfma_f32_16x16x32_bf16 v[16:19], v[178:181], v[194:197], v[16:19]
	v_mfma_f32_16x16x32_bf16 v[12:15], v[170:173], v[202:205], v[12:15]
	v_mfma_f32_16x16x32_bf16 v[8:11], v[178:181], v[202:205], v[8:11]
	v_mfma_f32_16x16x32_bf16 v[4:7], v[170:173], v[244:247], v[4:7]
	v_mfma_f32_16x16x32_bf16 v[0:3], v[178:181], v[244:247], v[0:3]
	s_barrier
	s_add_u32 s57, s57, 0x100
	s_addc_u32 s58, s58, 0
	s_cmp_ge_i32 s59, s27
	s_mov_b64 s[30:31], s[12:13]
	s_mov_b32 s34, s59
	s_cbranch_scc0 .LBB0_1378
	s_and_b64 vcc, exec, s[18:19]
	s_cbranch_vccz .LBB0_1381

; #define PG8_STAGE(bufoff, gbase, voff) do { _Pragma("unroll") for (int _i = 0; _i < 2; ++_i) \
;         __builtin_amdgcn_global_load_lds((const unsigned*)((const char*)(gbase) + (voff)[_i]), (PG8_LAS unsigned*)(lds + (bufoff) + ldsw + _i * 8192), 16, 0, 0); } while (0)
; #define PG8_LDA(dst, b, h) do { _Pragma("unroll") for (int m = 0; m < 4; ++m) _Pragma("unroll") for (int k = 0; k < 2; ++k) dst[m][k] = *(const PG8_LAS bf16x8*)(lds + PG8_SA(b, h) + aoff + m * 2048 + k * 1024); } while (0)
; #define PG8_LDB(dst, b, h) do { _Pragma("unroll") for (int n = 0; n < 2; ++n) _Pragma("unroll") for (int k = 0; k < 2; ++k) dst[n][k] = *(const PG8_LAS bf16x8*)(lds + PG8_SB(b, h) + boff + n * 2048 + k * 1024); } while (0)
; #define PG8_MMA(ai, bj, At, Bt) do { __builtin_amdgcn_s_setprio(1); _Pragma("unroll") for (int m = 0; m < 4; ++m) _Pragma("unroll") for (int n = 0; n < 2; ++n) _Pragma("unroll") for (int k = 0; k < 2; ++k) \
;         acc[ai][bj][m][n] = __builtin_amdgcn_mfma_f32_16x16x32_bf16(Bt[n][k], At[m][k], acc[ai][bj][m][n], 0, 0, 0); __builtin_amdgcn_s_setprio(0); } while (0)
; #define PG8_WAIT_V(n) asm volatile("s_waitcnt vmcnt(" #n ")" ::: "memory")
; #define PG8_WAIT_L(n) asm volatile("s_waitcnt lgkmcnt(" #n ")" ::: "memory")
; #define PG8_BAR __builtin_amdgcn_s_barrier()
; #define PG8_SCHED __builtin_amdgcn_sched_barrier(0)
; template <class Epi, class Sched, bool ALIGN_EPI = false, bool SP2 = false>
; __device__ __forceinline__ void gemm_phase(PG8_LAS unsigned char* lds, const Gemm g, const Sched& S, const Epi& E) {
;     ...
;             const bool last = (t == nt - 2);
;             const char* a1 = cA + (size_t)(t + 1) * kstep;
;             const char* a2 = last ? nA : cA + (size_t)(t + 2) * kstep; const char* b2 = last ? nB : cB + (size_t)(t + 2) * kstep;
;             const char* a3 = a2 + kstep; const char* b3 = b2 + kstep;
;             if (last && has_next) S.a_ready(nxt);
;             if constexpr (SP2) {
;             PG8_LDB(B0, 0, 0); PG8_LDB(B1, 0, 1); PG8_SCHED; PG8_LDA(At, 0, 0); PG8_STAGE(PG8_SA(1, 1), a1 + hstep, voffA);
;             PG8_WAIT_V(8); PG8_WAIT_L(0); PG8_BAR; PG8_MMA(0, 0, At, B0); PG8_MMA(0, 1, At, B1); PG8_BAR; PG8_SCHED;
;             PG8_LDA(At, 0, 1); PG8_STAGE(PG8_SB(0, 0), b2, voffB); PG8_STAGE(PG8_SB(0, 1), b2 + hstep, voffB); PG8_STAGE(PG8_SA(0, 0), a2, voffA);
.LBB0_1454:
	s_add_u32 s18, s16, 0x100
	s_addc_u32 s19, s17, 0
	s_add_i32 s45, 0, 0x10000
	s_cmp_eq_u32 s44, 40
	s_cselect_b32 s23, s9, s19
	s_cselect_b32 s22, s8, s18
	v_add_u32_e32 v142, s45, v157
	s_cselect_b32 s21, s13, s43
	s_cselect_b32 s20, s12, s42
	s_add_i32 s46, 0, 0x14000
	ds_read_b128 v[138:141], v142
	ds_read_b128 v[160:163], v142 offset:1024
	ds_read_b128 v[164:167], v142 offset:2048
	ds_read_b128 v[168:171], v142 offset:3072
	v_add_u32_e32 v142, s46, v157
	ds_read_b128 v[172:175], v142
	ds_read_b128 v[176:179], v142 offset:1024
	ds_read_b128 v[180:183], v142 offset:2048
	ds_read_b128 v[184:187], v142 offset:3072
	v_lshl_add_u64 v[142:143], s[16:17], 0, v[136:137]
	s_add_i32 m0, s24, 0xc000
	ds_read_b128 v[188:191], v159
	ds_read_b128 v[192:195], v159 offset:1024
	ds_read_b128 v[196:199], v159 offset:2048
	ds_read_b128 v[200:203], v159 offset:3072
	ds_read_b128 v[204:207], v159 offset:4096
	ds_read_b128 v[208:211], v159 offset:5120
	ds_read_b128 v[234:237], v159 offset:6144
	ds_read_b128 v[244:247], v159 offset:7168
	global_load_lds_dwordx4 v[142:143], off
	v_lshl_add_u64 v[142:143], s[16:17], 0, v[134:135]
	s_add_i32 m0, s24, 0xe000
	s_nop 0
	global_load_lds_dwordx4 v[142:143], off
	s_waitcnt vmcnt(8)
	s_waitcnt lgkmcnt(0)
	s_barrier
	s_waitcnt lgkmcnt(0)
	v_mfma_f32_16x16x32_bf16 v[124:127], v[138:141], v[188:191], v[124:127]
	v_mfma_f32_16x16x32_bf16 v[120:123], v[164:167], v[188:191], v[120:123]
	v_mfma_f32_16x16x32_bf16 v[108:111], v[138:141], v[196:199], v[108:111]
	v_mfma_f32_16x16x32_bf16 v[104:107], v[164:167], v[196:199], v[104:107]
	v_mfma_f32_16x16x32_bf16 v[92:95], v[138:141], v[204:207], v[92:95]
	v_mfma_f32_16x16x32_bf16 v[88:91], v[164:167], v[204:207], v[88:91]
	v_mfma_f32_16x16x32_bf16 v[76:79], v[138:141], v[234:237], v[76:79]
	v_mfma_f32_16x16x32_bf16 v[72:75], v[164:167], v[234:237], v[72:75]
	v_mfma_f32_16x16x32_bf16 v[124:127], v[160:163], v[192:195], v[124:127]
	v_mfma_f32_16x16x32_bf16 v[120:123], v[168:171], v[192:195], v[120:123]
	v_mfma_f32_16x16x32_bf16 v[108:111], v[160:163], v[200:203], v[108:111]
	v_mfma_f32_16x16x32_bf16 v[104:107], v[168:171], v[200:203], v[104:107]
	v_mfma_f32_16x16x32_bf16 v[92:95], v[160:163], v[208:211], v[92:95]
	v_mfma_f32_16x16x32_bf16 v[88:91], v[168:171], v[208:211], v[88:91]
	v_mfma_f32_16x16x32_bf16 v[76:79], v[160:163], v[244:247], v[76:79]
	v_mfma_f32_16x16x32_bf16 v[72:75], v[168:171], v[244:247], v[72:75]
	v_mfma_f32_16x16x32_bf16 v[116:119], v[172:175], v[188:191], v[116:119]
	v_mfma_f32_16x16x32_bf16 v[112:115], v[180:183], v[188:191], v[112:115]
	v_mfma_f32_16x16x32_bf16 v[100:103], v[172:175], v[196:199], v[100:103]
	v_mfma_f32_16x16x32_bf16 v[96:99], v[180:183], v[196:199], v[96:99]
	v_mfma_f32_16x16x32_bf16 v[84:87], v[172:175], v[204:207], v[84:87]
	v_mfma_f32_16x16x32_bf16 v[80:83], v[180:183], v[204:207], v[80:83]
	v_mfma_f32_16x16x32_bf16 v[68:71], v[172:175], v[234:237], v[68:71]
	v_mfma_f32_16x16x32_bf16 v[64:67], v[180:183], v[234:237], v[64:67]
	v_mfma_f32_16x16x32_bf16 v[116:119], v[176:179], v[192:195], v[116:119]
	v_mfma_f32_16x16x32_bf16 v[112:115], v[184:187], v[192:195], v[112:115]
	v_mfma_f32_16x16x32_bf16 v[100:103], v[176:179], v[200:203], v[100:103]
	v_mfma_f32_16x16x32_bf16 v[96:99], v[184:187], v[200:203], v[96:99]
	v_mfma_f32_16x16x32_bf16 v[84:87], v[176:179], v[208:211], v[84:87]
	v_mfma_f32_16x16x32_bf16 v[80:83], v[184:187], v[208:211], v[80:83]
	v_mfma_f32_16x16x32_bf16 v[68:71], v[176:179], v[244:247], v[68:71]
	v_mfma_f32_16x16x32_bf16 v[64:67], v[184:187], v[244:247], v[64:67]
	s_barrier
	s_add_i32 s16, s45, s0
	v_lshl_add_u64 v[142:143], s[20:21], 0, v[144:145]
	s_mov_b32 m0, s16
	ds_read_b128 v[188:191], v159 offset:16384
	ds_read_b128 v[192:195], v159 offset:17408
	ds_read_b128 v[196:199], v159 offset:18432
	ds_read_b128 v[200:203], v159 offset:19456
	ds_read_b128 v[204:207], v159 offset:20480
	ds_read_b128 v[208:211], v159 offset:21504
	ds_read_b128 v[234:237], v159 offset:22528
	ds_read_b128 v[244:247], v159 offset:23552
	global_load_lds_dwordx4 v[142:143], off
	s_add_i32 m0, s16, 0x2000
	s_add_u32 s16, s20, 0xb0000
	v_lshl_add_u64 v[154:155], s[20:21], 0, v[132:133]
	s_addc_u32 s17, s21, 0
	s_add_i32 s45, s46, s0
	global_load_lds_dwordx4 v[154:155], off
	v_lshl_add_u64 v[214:215], s[16:17], 0, v[144:145]
	s_mov_b32 m0, s45
	v_lshl_add_u64 v[238:239], s[22:23], 0, v[130:131]
	global_load_lds_dwordx4 v[214:215], off
	v_lshl_add_u64 v[214:215], s[16:17], 0, v[132:133]
	s_add_i32 m0, s45, 0x2000
	s_nop 0
	global_load_lds_dwordx4 v[214:215], off
	v_lshl_add_u64 v[214:215], s[22:23], 0, v[128:129]
	s_mov_b32 m0, s24
	s_nop 0
	global_load_lds_dwordx4 v[214:215], off
	s_mov_b32 m0, s25
	s_nop 0
	global_load_lds_dwordx4 v[238:239], off
	s_waitcnt vmcnt(8)
	s_waitcnt lgkmcnt(0)
	s_barrier
; #define PG8_STAGE(bufoff, gbase, voff) do { _Pragma("unroll") for (int _i = 0; _i < 2; ++_i) \
;         __builtin_amdgcn_global_load_lds((const unsigned*)((const char*)(gbase) + (voff)[_i]), (PG8_LAS unsigned*)(lds + (bufoff) + ldsw + _i * 8192), 16, 0, 0); } while (0)
; #define PG8_LDA(dst, b, h) do { _Pragma("unroll") for (int m = 0; m < 4; ++m) _Pragma("unroll") for (int k = 0; k < 2; ++k) dst[m][k] = *(const PG8_LAS bf16x8*)(lds + PG8_SA(b, h) + aoff + m * 2048 + k * 1024); } while (0)
; #define PG8_LDB(dst, b, h) do { _Pragma("unroll") for (int n = 0; n < 2; ++n) _Pragma("unroll") for (int k = 0; k < 2; ++k) dst[n][k] = *(const PG8_LAS bf16x8*)(lds + PG8_SB(b, h) + boff + n * 2048 + k * 1024); } while (0)
; #define PG8_MMA(ai, bj, At, Bt) do { __builtin_amdgcn_s_setprio(1); _Pragma("unroll") for (int m = 0; m < 4; ++m) _Pragma("unroll") for (int n = 0; n < 2; ++n) _Pragma("unroll") for (int k = 0; k < 2; ++k) \
;         acc[ai][bj][m][n] = __builtin_amdgcn_mfma_f32_16x16x32_bf16(Bt[n][k], At[m][k], acc[ai][bj][m][n], 0, 0, 0); __builtin_amdgcn_s_setprio(0); } while (0)
; #define PG8_WAIT_V(n) asm volatile("s_waitcnt vmcnt(" #n ")" ::: "memory")
; #define PG8_WAIT_L(n) asm volatile("s_waitcnt lgkmcnt(" #n ")" ::: "memory")
; #define PG8_BAR __builtin_amdgcn_s_barrier()
; #define PG8_SCHED __builtin_amdgcn_sched_barrier(0)
; template <class Epi, class Sched, bool ALIGN_EPI = false, bool SP2 = false>
; __device__ __forceinline__ void gemm_phase(PG8_LAS unsigned char* lds, const Gemm g, const Sched& S, const Epi& E) {
;     ...
;             PG8_WAIT_V(8); PG8_WAIT_L(0); PG8_BAR; PG8_MMA(1, 0, At, B0); PG8_MMA(1, 1, At, B1); PG8_BAR; PG8_SCHED;
;             PG8_LDB(B0, 1, 0); PG8_LDB(B1, 1, 1); PG8_SCHED; PG8_LDA(At, 1, 0); PG8_STAGE(PG8_SA(0, 1), a2 + hstep, voffA);
;             PG8_WAIT_V(8); PG8_WAIT_L(0); PG8_BAR; PG8_MMA(0, 0, At, B0); PG8_MMA(0, 1, At, B1); PG8_BAR; PG8_SCHED;
	s_waitcnt lgkmcnt(0)
	v_mfma_f32_16x16x32_bf16 v[60:63], v[138:141], v[188:191], v[60:63]
	v_mfma_f32_16x16x32_bf16 v[56:59], v[164:167], v[188:191], v[56:59]
	v_mfma_f32_16x16x32_bf16 v[44:47], v[138:141], v[196:199], v[44:47]
	v_mfma_f32_16x16x32_bf16 v[40:43], v[164:167], v[196:199], v[40:43]
	v_mfma_f32_16x16x32_bf16 v[28:31], v[138:141], v[204:207], v[28:31]
	v_mfma_f32_16x16x32_bf16 v[24:27], v[164:167], v[204:207], v[24:27]
	v_mfma_f32_16x16x32_bf16 v[12:15], v[138:141], v[234:237], v[12:15]
	v_mfma_f32_16x16x32_bf16 v[8:11], v[164:167], v[234:237], v[8:11]
	v_mfma_f32_16x16x32_bf16 v[60:63], v[160:163], v[192:195], v[60:63]
	v_mfma_f32_16x16x32_bf16 v[56:59], v[168:171], v[192:195], v[56:59]
	v_mfma_f32_16x16x32_bf16 v[44:47], v[160:163], v[200:203], v[44:47]
	v_mfma_f32_16x16x32_bf16 v[40:43], v[168:171], v[200:203], v[40:43]
	v_mfma_f32_16x16x32_bf16 v[28:31], v[160:163], v[208:211], v[28:31]
	v_mfma_f32_16x16x32_bf16 v[24:27], v[168:171], v[208:211], v[24:27]
	v_mfma_f32_16x16x32_bf16 v[12:15], v[160:163], v[244:247], v[12:15]
	v_mfma_f32_16x16x32_bf16 v[8:11], v[168:171], v[244:247], v[8:11]
	v_mfma_f32_16x16x32_bf16 v[52:55], v[172:175], v[188:191], v[52:55]
	v_mfma_f32_16x16x32_bf16 v[48:51], v[180:183], v[188:191], v[48:51]
	v_mfma_f32_16x16x32_bf16 v[36:39], v[172:175], v[196:199], v[36:39]
	v_mfma_f32_16x16x32_bf16 v[32:35], v[180:183], v[196:199], v[32:35]
	v_mfma_f32_16x16x32_bf16 v[20:23], v[172:175], v[204:207], v[20:23]
	v_mfma_f32_16x16x32_bf16 v[16:19], v[180:183], v[204:207], v[16:19]
	v_mfma_f32_16x16x32_bf16 v[4:7], v[172:175], v[234:237], v[4:7]
	v_mfma_f32_16x16x32_bf16 v[0:3], v[180:183], v[234:237], v[0:3]
	v_mfma_f32_16x16x32_bf16 v[52:55], v[176:179], v[192:195], v[52:55]
	v_mfma_f32_16x16x32_bf16 v[48:51], v[184:187], v[192:195], v[48:51]
	v_mfma_f32_16x16x32_bf16 v[36:39], v[176:179], v[200:203], v[36:39]
	v_mfma_f32_16x16x32_bf16 v[32:35], v[184:187], v[200:203], v[32:35]
	v_mfma_f32_16x16x32_bf16 v[20:23], v[176:179], v[208:211], v[20:23]
	v_mfma_f32_16x16x32_bf16 v[16:19], v[184:187], v[208:211], v[16:19]
	v_mfma_f32_16x16x32_bf16 v[4:7], v[176:179], v[244:247], v[4:7]
	v_mfma_f32_16x16x32_bf16 v[0:3], v[184:187], v[244:247], v[0:3]
	s_barrier
	s_add_i32 s45, 0, 0x18000
	s_add_i32 s46, 0, 0x1c000
	v_add_u32_e32 v168, s45, v157
	v_add_u32_e32 v184, s46, v157
	ds_read_b128 v[138:141], v168
	ds_read_b128 v[160:163], v168 offset:1024
	ds_read_b128 v[164:167], v168 offset:2048
	ds_read_b128 v[168:171], v168 offset:3072
	ds_read_b128 v[172:175], v184
	ds_read_b128 v[176:179], v184 offset:1024
	ds_read_b128 v[180:183], v184 offset:2048
	ds_read_b128 v[184:187], v184 offset:3072
	s_add_u32 s16, s22, 0xb0000
	s_addc_u32 s17, s23, 0
	s_mov_b32 m0, s26
	v_lshl_add_u64 v[248:249], s[16:17], 0, v[128:129]
	ds_read_b128 v[188:191], v159 offset:32768
	ds_read_b128 v[192:195], v159 offset:33792
	ds_read_b128 v[196:199], v159 offset:34816
	ds_read_b128 v[200:203], v159 offset:35840
	ds_read_b128 v[204:207], v159 offset:36864
	ds_read_b128 v[208:211], v159 offset:37888
	ds_read_b128 v[234:237], v159 offset:38912
	ds_read_b128 v[244:247], v159 offset:39936
	global_load_lds_dwordx4 v[248:249], off
	v_lshl_add_u64 v[248:249], s[16:17], 0, v[130:131]
	s_mov_b32 m0, s27
	s_nop 0
	global_load_lds_dwordx4 v[248:249], off
	s_waitcnt vmcnt(8)
	s_waitcnt lgkmcnt(0)
	s_barrier
	s_waitcnt lgkmcnt(0)
	v_mfma_f32_16x16x32_bf16 v[124:127], v[138:141], v[188:191], v[124:127]
	v_mfma_f32_16x16x32_bf16 v[120:123], v[164:167], v[188:191], v[120:123]
	v_mfma_f32_16x16x32_bf16 v[108:111], v[138:141], v[196:199], v[108:111]
	v_mfma_f32_16x16x32_bf16 v[104:107], v[164:167], v[196:199], v[104:107]
	v_mfma_f32_16x16x32_bf16 v[92:95], v[138:141], v[204:207], v[92:95]
	v_mfma_f32_16x16x32_bf16 v[88:91], v[164:167], v[204:207], v[88:91]
	v_mfma_f32_16x16x32_bf16 v[76:79], v[138:141], v[234:237], v[76:79]
	v_mfma_f32_16x16x32_bf16 v[72:75], v[164:167], v[234:237], v[72:75]
	v_mfma_f32_16x16x32_bf16 v[124:127], v[160:163], v[192:195], v[124:127]
	v_mfma_f32_16x16x32_bf16 v[120:123], v[168:171], v[192:195], v[120:123]
	v_mfma_f32_16x16x32_bf16 v[108:111], v[160:163], v[200:203], v[108:111]
	v_mfma_f32_16x16x32_bf16 v[104:107], v[168:171], v[200:203], v[104:107]
	v_mfma_f32_16x16x32_bf16 v[92:95], v[160:163], v[208:211], v[92:95]
	v_mfma_f32_16x16x32_bf16 v[88:91], v[168:171], v[208:211], v[88:91]
	v_mfma_f32_16x16x32_bf16 v[76:79], v[160:163], v[244:247], v[76:79]
	v_mfma_f32_16x16x32_bf16 v[72:75], v[168:171], v[244:247], v[72:75]
	v_mfma_f32_16x16x32_bf16 v[116:119], v[172:175], v[188:191], v[116:119]
	v_mfma_f32_16x16x32_bf16 v[112:115], v[180:183], v[188:191], v[112:115]
	v_mfma_f32_16x16x32_bf16 v[100:103], v[172:175], v[196:199], v[100:103]
	v_mfma_f32_16x16x32_bf16 v[96:99], v[180:183], v[196:199], v[96:99]
	v_mfma_f32_16x16x32_bf16 v[84:87], v[172:175], v[204:207], v[84:87]
	v_mfma_f32_16x16x32_bf16 v[80:83], v[180:183], v[204:207], v[80:83]
	v_mfma_f32_16x16x32_bf16 v[68:71], v[172:175], v[234:237], v[68:71]
	v_mfma_f32_16x16x32_bf16 v[64:67], v[180:183], v[234:237], v[64:67]
	v_mfma_f32_16x16x32_bf16 v[116:119], v[176:179], v[192:195], v[116:119]
	v_mfma_f32_16x16x32_bf16 v[112:115], v[184:187], v[192:195], v[112:115]
	v_mfma_f32_16x16x32_bf16 v[100:103], v[176:179], v[200:203], v[100:103]
	v_mfma_f32_16x16x32_bf16 v[96:99], v[184:187], v[200:203], v[96:99]
	v_mfma_f32_16x16x32_bf16 v[84:87], v[176:179], v[208:211], v[84:87]
	v_mfma_f32_16x16x32_bf16 v[80:83], v[184:187], v[208:211], v[80:83]
	v_mfma_f32_16x16x32_bf16 v[68:71], v[176:179], v[244:247], v[68:71]
	v_mfma_f32_16x16x32_bf16 v[64:67], v[184:187], v[244:247], v[64:67]
	s_barrier
; #define PG8_STAGE(bufoff, gbase, voff) do { _Pragma("unroll") for (int _i = 0; _i < 2; ++_i) \
;         __builtin_amdgcn_global_load_lds((const unsigned*)((const char*)(gbase) + (voff)[_i]), (PG8_LAS unsigned*)(lds + (bufoff) + ldsw + _i * 8192), 16, 0, 0); } while (0)
; #define PG8_LDA(dst, b, h) do { _Pragma("unroll") for (int m = 0; m < 4; ++m) _Pragma("unroll") for (int k = 0; k < 2; ++k) dst[m][k] = *(const PG8_LAS bf16x8*)(lds + PG8_SA(b, h) + aoff + m * 2048 + k * 1024); } while (0)
; #define PG8_MMA(ai, bj, At, Bt) do { __builtin_amdgcn_s_setprio(1); _Pragma("unroll") for (int m = 0; m < 4; ++m) _Pragma("unroll") for (int n = 0; n < 2; ++n) _Pragma("unroll") for (int k = 0; k < 2; ++k) \
;         acc[ai][bj][m][n] = __builtin_amdgcn_mfma_f32_16x16x32_bf16(Bt[n][k], At[m][k], acc[ai][bj][m][n], 0, 0, 0); __builtin_amdgcn_s_setprio(0); } while (0)
; #define PG8_WAIT_V(n) asm volatile("s_waitcnt vmcnt(" #n ")" ::: "memory")
; #define PG8_WAIT_L(n) asm volatile("s_waitcnt lgkmcnt(" #n ")" ::: "memory")
; #define PG8_BAR __builtin_amdgcn_s_barrier()
; #define PG8_SCHED __builtin_amdgcn_sched_barrier(0)
; template <class Epi, class Sched, bool ALIGN_EPI = false, bool SP2 = false>
; __device__ __forceinline__ void gemm_phase(PG8_LAS unsigned char* lds, const Gemm g, const Sched& S, const Epi& E) {
;     ...
;             PG8_LDA(At, 1, 1); PG8_STAGE(PG8_SB(1, 0), b3, voffB); PG8_STAGE(PG8_SB(1, 1), b3 + hstep, voffB); PG8_STAGE(PG8_SA(1, 0), a3, voffA);
;             PG8_WAIT_V(8); PG8_WAIT_L(0); PG8_BAR; PG8_MMA(1, 0, At, B0); PG8_MMA(1, 1, At, B1); PG8_BAR; PG8_SCHED;
;     ...
;         if constexpr (ALIGN_EPI) { if (wr == 0) PG8_BAR; }
	s_add_i32 s16, s45, s0
	v_lshl_add_u64 v[142:143], v[142:143], 0, s[48:49]
	s_mov_b32 m0, s16
	ds_read_b128 v[188:191], v159 offset:49152
	ds_read_b128 v[192:195], v159 offset:50176
	ds_read_b128 v[196:199], v159 offset:51200
	ds_read_b128 v[200:203], v159 offset:52224
	ds_read_b128 v[204:207], v159 offset:53248
	ds_read_b128 v[208:211], v159 offset:54272
	ds_read_b128 v[234:237], v159 offset:55296
	ds_read_b128 v[244:247], v159 offset:56320
	global_load_lds_dwordx4 v[142:143], off
	s_add_i32 m0, s16, 0x2000
	s_add_u32 s16, s20, 0xb0080
	v_lshl_add_u64 v[142:143], v[154:155], 0, s[48:49]
	s_addc_u32 s17, s21, 0
	s_add_i32 s20, s46, s0
	global_load_lds_dwordx4 v[142:143], off
	v_lshl_add_u64 v[142:143], s[16:17], 0, v[144:145]
	s_mov_b32 m0, s20
	s_nop 0
	global_load_lds_dwordx4 v[142:143], off
	v_lshl_add_u64 v[142:143], s[16:17], 0, v[132:133]
	s_add_i32 m0, s20, 0x2000
	s_nop 0
	global_load_lds_dwordx4 v[142:143], off
	v_lshl_add_u64 v[142:143], v[214:215], 0, s[48:49]
	s_mov_b32 m0, s30
	s_nop 0
	global_load_lds_dwordx4 v[142:143], off
	v_lshl_add_u64 v[142:143], v[238:239], 0, s[48:49]
	s_mov_b32 m0, s31
	s_nop 0
	global_load_lds_dwordx4 v[142:143], off
	s_waitcnt vmcnt(8)
	s_waitcnt lgkmcnt(0)
	s_barrier
	s_waitcnt lgkmcnt(0)
	v_mfma_f32_16x16x32_bf16 v[60:63], v[138:141], v[188:191], v[60:63]
	v_mfma_f32_16x16x32_bf16 v[56:59], v[164:167], v[188:191], v[56:59]
	v_mfma_f32_16x16x32_bf16 v[44:47], v[138:141], v[196:199], v[44:47]
	v_mfma_f32_16x16x32_bf16 v[40:43], v[164:167], v[196:199], v[40:43]
	v_mfma_f32_16x16x32_bf16 v[28:31], v[138:141], v[204:207], v[28:31]
	v_mfma_f32_16x16x32_bf16 v[24:27], v[164:167], v[204:207], v[24:27]
	v_mfma_f32_16x16x32_bf16 v[12:15], v[138:141], v[234:237], v[12:15]
	v_mfma_f32_16x16x32_bf16 v[8:11], v[164:167], v[234:237], v[8:11]
	v_mfma_f32_16x16x32_bf16 v[60:63], v[160:163], v[192:195], v[60:63]
	v_mfma_f32_16x16x32_bf16 v[56:59], v[168:171], v[192:195], v[56:59]
	v_mfma_f32_16x16x32_bf16 v[44:47], v[160:163], v[200:203], v[44:47]
	v_mfma_f32_16x16x32_bf16 v[40:43], v[168:171], v[200:203], v[40:43]
	v_mfma_f32_16x16x32_bf16 v[28:31], v[160:163], v[208:211], v[28:31]
	v_mfma_f32_16x16x32_bf16 v[24:27], v[168:171], v[208:211], v[24:27]
	v_mfma_f32_16x16x32_bf16 v[12:15], v[160:163], v[244:247], v[12:15]
	v_mfma_f32_16x16x32_bf16 v[8:11], v[168:171], v[244:247], v[8:11]
	v_mfma_f32_16x16x32_bf16 v[52:55], v[172:175], v[188:191], v[52:55]
	v_mfma_f32_16x16x32_bf16 v[48:51], v[180:183], v[188:191], v[48:51]
	v_mfma_f32_16x16x32_bf16 v[36:39], v[172:175], v[196:199], v[36:39]
	v_mfma_f32_16x16x32_bf16 v[32:35], v[180:183], v[196:199], v[32:35]
	v_mfma_f32_16x16x32_bf16 v[20:23], v[172:175], v[204:207], v[20:23]
	v_mfma_f32_16x16x32_bf16 v[16:19], v[180:183], v[204:207], v[16:19]
	v_mfma_f32_16x16x32_bf16 v[4:7], v[172:175], v[234:237], v[4:7]
	v_mfma_f32_16x16x32_bf16 v[0:3], v[180:183], v[234:237], v[0:3]
	v_mfma_f32_16x16x32_bf16 v[52:55], v[176:179], v[192:195], v[52:55]
	v_mfma_f32_16x16x32_bf16 v[48:51], v[184:187], v[192:195], v[48:51]
	v_mfma_f32_16x16x32_bf16 v[36:39], v[176:179], v[200:203], v[36:39]
	v_mfma_f32_16x16x32_bf16 v[32:35], v[184:187], v[200:203], v[32:35]
	v_mfma_f32_16x16x32_bf16 v[20:23], v[176:179], v[208:211], v[20:23]
	v_mfma_f32_16x16x32_bf16 v[16:19], v[184:187], v[208:211], v[16:19]
	v_mfma_f32_16x16x32_bf16 v[4:7], v[176:179], v[244:247], v[4:7]
	v_mfma_f32_16x16x32_bf16 v[0:3], v[184:187], v[244:247], v[0:3]
	s_barrier
	s_add_i32 s44, s44, 2
	s_add_u32 s42, s42, 0x100
	s_addc_u32 s43, s43, 0
	s_cmp_gt_u32 s44, 41
	s_mov_b64 s[16:17], s[18:19]
	s_cbranch_scc0 .LBB0_1454
	s_and_b64 vcc, exec, s[10:11]
	s_cbranch_vccz .LBB0_1457
	s_barrier
